# GEMM mainloops: per-segment s_setprio flips removed, one static s_setprio 1 for waves 4-7 around each mainloop
# speedup vs baseline: 1.0040x; 1.0040x over previous
; #define PG8_STAGE(bufoff, gbase, voff) do { _Pragma("unroll") for (int _i = 0; _i < 2; ++_i) \
;         __builtin_amdgcn_global_load_lds((const unsigned*)((const char*)(gbase) + (voff)[_i]), (LAS unsigned*)(lds + (bufoff) + ldsw + _i * 8192), 16, 0, 0); } while (0)
; #define PG8_LDA(dst, b, h) do { _Pragma("unroll") for (int m = 0; m < 4; ++m) _Pragma("unroll") for (int k = 0; k < 2; ++k) dst[m][k] = *(const LAS bf16x8*)(lds + PG8_SA(b, h) + aoff + m * 2048 + k * 1024); } while (0)
; #define PG8_LDB(dst, b, h) do { _Pragma("unroll") for (int n = 0; n < 2; ++n) _Pragma("unroll") for (int k = 0; k < 2; ++k) dst[n][k] = *(const LAS bf16x8*)(lds + PG8_SB(b, h) + boff + n * 2048 + k * 1024); } while (0)
; #define PG8_MMA(ai, bj, At, Bt) do { __builtin_amdgcn_s_setprio(1); _Pragma("unroll") for (int m = 0; m < 4; ++m) _Pragma("unroll") for (int n = 0; n < 2; ++n) _Pragma("unroll") for (int k = 0; k < 2; ++k) \
;         acc[ai][bj][m][n] = __builtin_amdgcn_mfma_f32_16x16x32_bf16(Bt[n][k], At[m][k], acc[ai][bj][m][n], 0, 0, 0); __builtin_amdgcn_s_setprio(0); } while (0)
; #define PG8_BAR __builtin_amdgcn_s_barrier()
; template <class Epi>
; __device__ __forceinline__ void gemm_phase(LAS unsigned char* lds, const Gemm g, const StaticOrder& S, const Epi& E, const int tid) {
;     ...
;         const bool has_next = S.next(ui + 1, nxt);
;         const char* nA = has_next ? (const char*)g.A + (size_t)nxt.pm * tstep : cA; const char* nB = has_next ? (const char*)g.Bt + (size_t)nxt.pn * tstep : cB;
;         for (int t = 0; t < nt; t += 2) {
;             const bool last = (t == nt - 2);
;             const char* a1 = cA + (size_t)(t + 1) * kstep;
;             const char* a2 = last ? nA : cA + (size_t)(t + 2) * kstep; const char* b2 = last ? nB : cB + (size_t)(t + 2) * kstep;
;             const char* a3 = a2 + kstep; const char* b3 = b2 + kstep;
;             PG8_LDB(B0, 0, 0); PG8_SCHED; PG8_LDA(At, 0, 0); PG8_STAGE(PG8_SA(1, 1), a1 + hstep, voffA);
;             PG8_WAIT_L(8); PG8_BAR; PG8_WAIT_L(0); PG8_MMA(0, 0, At, B0); PG8_BAR; PG8_SCHED;
;     ...
; #pragma unroll
;         for (int a = 0; a < 2; ++a)
; #pragma unroll
;             for (int b = 0; b < 2; ++b)
; #pragma unroll
;                 for (int m = 0; m < 4; ++m)
; #pragma unroll
;                     for (int n = 0; n < 2; ++n) acc[a][b][m][n] = (f32x4){0.f, 0.f, 0.f, 0.f};
;         cur = nxt; cA = nA; cB = nB; ++ui;
.LBB0_39:
	s_ashr_i32 s13, s12, 31
	v_cmp_lt_i64_e32 vcc, s[14:15], v[146:147]
	s_lshl_b64 s[14:15], s[12:13], 22
	s_add_u32 s14, s0, s14
	s_addc_u32 s15, s1, s15
	s_and_b64 s[16:17], vcc, exec
	s_cselect_b32 s13, s15, s21
	s_cselect_b32 s44, s14, s20
	s_ashr_i32 s11, s10, 31
	s_lshl_b64 s[16:17], s[10:11], 22
	s_add_u32 s16, s24, s16
	s_addc_u32 s17, s25, s17
	s_and_b64 s[22:23], vcc, exec
	s_cselect_b32 s11, s17, s19
	s_cselect_b32 s45, s16, s18
	s_add_u32 s47, s18, 0x100
	s_addc_u32 s48, s19, 0
	s_add_u32 s18, s20, 0x200080
	v_mov_b32_e32 v2, 0
	s_addc_u32 s19, s21, 0
	s_mov_b32 s49, -2
	v_mov_b32_e32 v3, v2
	v_mov_b32_e32 v4, v2
	v_mov_b32_e32 v5, v2
	v_mov_b32_e32 v6, v2
	v_mov_b32_e32 v7, v2
	v_mov_b32_e32 v8, v2
	v_mov_b32_e32 v9, v2
	v_mov_b32_e32 v18, v2
	v_mov_b32_e32 v19, v2
	v_mov_b32_e32 v20, v2
	v_mov_b32_e32 v21, v2
	v_mov_b32_e32 v22, v2
	v_mov_b32_e32 v23, v2
	v_mov_b32_e32 v24, v2
	v_mov_b32_e32 v25, v2
	v_mov_b32_e32 v34, v2
	v_mov_b32_e32 v35, v2
	v_mov_b32_e32 v36, v2
	v_mov_b32_e32 v37, v2
	v_mov_b32_e32 v38, v2
	v_mov_b32_e32 v39, v2
	v_mov_b32_e32 v40, v2
	v_mov_b32_e32 v41, v2
	v_mov_b32_e32 v58, v2
	v_mov_b32_e32 v59, v2
	v_mov_b32_e32 v60, v2
	v_mov_b32_e32 v61, v2
	v_mov_b32_e32 v62, v2
	v_mov_b32_e32 v63, v2
	v_mov_b32_e32 v64, v2
	v_mov_b32_e32 v65, v2
	v_mov_b32_e32 v10, v2
	v_mov_b32_e32 v11, v2
	v_mov_b32_e32 v12, v2
	v_mov_b32_e32 v13, v2
	v_mov_b32_e32 v14, v2
	v_mov_b32_e32 v15, v2
	v_mov_b32_e32 v16, v2
	v_mov_b32_e32 v17, v2
	v_mov_b32_e32 v26, v2
	v_mov_b32_e32 v27, v2
	v_mov_b32_e32 v28, v2
	v_mov_b32_e32 v29, v2
	v_mov_b32_e32 v30, v2
	v_mov_b32_e32 v31, v2
	v_mov_b32_e32 v32, v2
	v_mov_b32_e32 v33, v2
	v_mov_b32_e32 v42, v2
	v_mov_b32_e32 v43, v2
	v_mov_b32_e32 v44, v2
	v_mov_b32_e32 v45, v2
	v_mov_b32_e32 v46, v2
	v_mov_b32_e32 v47, v2
	v_mov_b32_e32 v48, v2
	v_mov_b32_e32 v49, v2
	v_mov_b32_e32 v74, v2
	v_mov_b32_e32 v75, v2
	v_mov_b32_e32 v76, v2
	v_mov_b32_e32 v77, v2
	v_mov_b32_e32 v78, v2
	v_mov_b32_e32 v79, v2
	v_mov_b32_e32 v80, v2
	v_mov_b32_e32 v81, v2
	v_mov_b32_e32 v82, v2
	v_mov_b32_e32 v83, v2
	v_mov_b32_e32 v84, v2
	v_mov_b32_e32 v85, v2
	v_mov_b32_e32 v86, v2
	v_mov_b32_e32 v87, v2
	v_mov_b32_e32 v88, v2
	v_mov_b32_e32 v89, v2
	v_mov_b32_e32 v98, v2
	v_mov_b32_e32 v99, v2
	v_mov_b32_e32 v100, v2
	v_mov_b32_e32 v101, v2
	v_mov_b32_e32 v102, v2
	v_mov_b32_e32 v103, v2
	v_mov_b32_e32 v104, v2
	v_mov_b32_e32 v105, v2
	v_mov_b32_e32 v114, v2
	v_mov_b32_e32 v115, v2
	v_mov_b32_e32 v116, v2
	v_mov_b32_e32 v117, v2
	v_mov_b32_e32 v118, v2
	v_mov_b32_e32 v119, v2
	v_mov_b32_e32 v120, v2
	v_mov_b32_e32 v121, v2
	v_mov_b32_e32 v130, v2
	v_mov_b32_e32 v131, v2
	v_mov_b32_e32 v132, v2
	v_mov_b32_e32 v133, v2
	v_mov_b32_e32 v134, v2
	v_mov_b32_e32 v135, v2
	v_mov_b32_e32 v136, v2
	v_mov_b32_e32 v137, v2
	v_mov_b32_e32 v90, v2
	v_mov_b32_e32 v91, v2
	v_mov_b32_e32 v92, v2
	v_mov_b32_e32 v93, v2
	v_mov_b32_e32 v94, v2
	v_mov_b32_e32 v95, v2
	v_mov_b32_e32 v96, v2
	v_mov_b32_e32 v97, v2
	v_mov_b32_e32 v106, v2
	v_mov_b32_e32 v107, v2
	v_mov_b32_e32 v108, v2
	v_mov_b32_e32 v109, v2
	v_mov_b32_e32 v110, v2
	v_mov_b32_e32 v111, v2
	v_mov_b32_e32 v112, v2
	v_mov_b32_e32 v113, v2
	v_mov_b32_e32 v122, v2
	v_mov_b32_e32 v123, v2
	v_mov_b32_e32 v124, v2
	v_mov_b32_e32 v125, v2
	v_mov_b32_e32 v126, v2
	v_mov_b32_e32 v127, v2
	v_mov_b32_e32 v128, v2
	v_mov_b32_e32 v129, v2
	s_waitcnt vmcnt(0)
	v_mov_b32_e32 v138, v2
	v_mov_b32_e32 v139, v2
	v_mov_b32_e32 v140, v2
	v_mov_b32_e32 v141, v2
	v_mov_b32_e32 v142, v2
	v_mov_b32_e32 v143, v2
	v_mov_b32_e32 v144, v2
	v_mov_b32_e32 v145, v2
	v_readfirstlane_b32 s32, v158
	s_cmpk_lt_u32 s32, 0x100
	s_cbranch_scc1 .Lgprio0
	s_setprio 1
.Lgprio0:
.LBB0_40:
	s_add_u32 s20, s18, 0xffe00080
	s_addc_u32 s21, s19, -1
	s_add_i32 s50, 0, 0x10000
	v_add_u32_e32 v70, s50, v173
	ds_read_b128 v[50:53], v70
	ds_read_b128 v[54:57], v70 offset:1024
	ds_read_b128 v[66:69], v70 offset:2048
	ds_read_b128 v[70:73], v70 offset:3072
	s_cmpk_eq_i32 s49, 0x7c
	s_cselect_b32 s23, s13, s21
	s_cselect_b32 s22, s44, s20
	s_cselect_b32 s21, s11, s48
	s_cselect_b32 s20, s45, s47
	v_lshl_add_u64 v[170:171], s[18:19], 0, v[168:169]
	s_add_i32 m0, s3, 0xc000
	ds_read_b128 v[176:179], v174
	ds_read_b128 v[180:183], v174 offset:1024
	ds_read_b128 v[184:187], v174 offset:2048
	ds_read_b128 v[188:191], v174 offset:3072
	ds_read_b128 v[192:195], v174 offset:4096
	ds_read_b128 v[196:199], v174 offset:5120
	ds_read_b128 v[210:213], v174 offset:6144
	ds_read_b128 v[214:217], v174 offset:7168
	global_load_lds_dwordx4 v[170:171], off
	v_lshl_add_u64 v[170:171], s[18:19], 0, v[166:167]
	s_add_i32 m0, s3, 0xe000
	s_nop 0
	global_load_lds_dwordx4 v[170:171], off
	s_waitcnt lgkmcnt(8)
	s_barrier
	s_waitcnt lgkmcnt(0)
	v_mfma_f32_16x16x32_bf16 v[142:145], v[50:53], v[176:179], v[142:145]
	v_mfma_f32_16x16x32_bf16 v[138:141], v[66:69], v[176:179], v[138:141]
	v_mfma_f32_16x16x32_bf16 v[126:129], v[50:53], v[184:187], v[126:129]
	v_mfma_f32_16x16x32_bf16 v[122:125], v[66:69], v[184:187], v[122:125]
	v_mfma_f32_16x16x32_bf16 v[110:113], v[50:53], v[192:195], v[110:113]
	v_mfma_f32_16x16x32_bf16 v[106:109], v[66:69], v[192:195], v[106:109]
	v_mfma_f32_16x16x32_bf16 v[94:97], v[50:53], v[210:213], v[94:97]
	v_mfma_f32_16x16x32_bf16 v[90:93], v[66:69], v[210:213], v[90:93]
	v_mfma_f32_16x16x32_bf16 v[142:145], v[54:57], v[180:183], v[142:145]
	v_mfma_f32_16x16x32_bf16 v[138:141], v[70:73], v[180:183], v[138:141]
	v_mfma_f32_16x16x32_bf16 v[126:129], v[54:57], v[188:191], v[126:129]
	v_mfma_f32_16x16x32_bf16 v[122:125], v[70:73], v[188:191], v[122:125]
	v_mfma_f32_16x16x32_bf16 v[110:113], v[54:57], v[196:199], v[110:113]
	v_mfma_f32_16x16x32_bf16 v[106:109], v[70:73], v[196:199], v[106:109]
	v_mfma_f32_16x16x32_bf16 v[94:97], v[54:57], v[214:217], v[94:97]
	v_mfma_f32_16x16x32_bf16 v[90:93], v[70:73], v[214:217], v[90:93]
	s_barrier
; #define PG8_STAGE(bufoff, gbase, voff) do { _Pragma("unroll") for (int _i = 0; _i < 2; ++_i) \
;         __builtin_amdgcn_global_load_lds((const unsigned*)((const char*)(gbase) + (voff)[_i]), (LAS unsigned*)(lds + (bufoff) + ldsw + _i * 8192), 16, 0, 0); } while (0)
; #define PG8_LDA(dst, b, h) do { _Pragma("unroll") for (int m = 0; m < 4; ++m) _Pragma("unroll") for (int k = 0; k < 2; ++k) dst[m][k] = *(const LAS bf16x8*)(lds + PG8_SA(b, h) + aoff + m * 2048 + k * 1024); } while (0)
; #define PG8_LDB(dst, b, h) do { _Pragma("unroll") for (int n = 0; n < 2; ++n) _Pragma("unroll") for (int k = 0; k < 2; ++k) dst[n][k] = *(const LAS bf16x8*)(lds + PG8_SB(b, h) + boff + n * 2048 + k * 1024); } while (0)
; #define PG8_MMA(ai, bj, At, Bt) do { __builtin_amdgcn_s_setprio(1); _Pragma("unroll") for (int m = 0; m < 4; ++m) _Pragma("unroll") for (int n = 0; n < 2; ++n) _Pragma("unroll") for (int k = 0; k < 2; ++k) \
;         acc[ai][bj][m][n] = __builtin_amdgcn_mfma_f32_16x16x32_bf16(Bt[n][k], At[m][k], acc[ai][bj][m][n], 0, 0, 0); __builtin_amdgcn_s_setprio(0); } while (0)
; #define PG8_WAIT_V(n) asm volatile("s_waitcnt vmcnt(" #n ")" ::: "memory")
; #define PG8_WAIT_L(n) asm volatile("s_waitcnt lgkmcnt(" #n ")" ::: "memory")
; #define PG8_BAR __builtin_amdgcn_s_barrier()
; #define PG8_SCHED __builtin_amdgcn_sched_barrier(0)
; template <class Epi>
; __device__ __forceinline__ void gemm_phase(LAS unsigned char* lds, const Gemm g, const StaticOrder& S, const Epi& E, const int tid) {
;     ...
;             PG8_BAR; PG8_WAIT_L(0); PG8_MMA(0, 1, At, B1); PG8_BAR;
;             PG8_LDA(At, 0, 1); PG8_STAGE(PG8_SA(0, 0), a2, voffA);
;             PG8_BAR; PG8_WAIT_L(0); PG8_MMA(1, 0, At, B0); PG8_BAR; PG8_SCHED;
;             PG8_STAGE(PG8_SB(0, 1), b2 + hstep, voffB);
;             PG8_WAIT_V(6); PG8_BAR; PG8_MMA(1, 1, At, B1); PG8_BAR;
;             PG8_LDB(B0, 1, 0); PG8_SCHED; PG8_LDA(At, 1, 0); PG8_STAGE(PG8_SA(0, 1), a2 + hstep, voffA);
;             PG8_WAIT_L(8); PG8_BAR; PG8_WAIT_L(0); PG8_MMA(0, 0, At, B0); PG8_BAR; PG8_SCHED;
	s_add_i32 s54, 0, 0x14000
	v_add_u32_e32 v170, s54, v173
	s_add_i32 s50, s50, s31
	ds_read_b128 v[218:221], v170
	ds_read_b128 v[222:225], v170 offset:1024
	ds_read_b128 v[226:229], v170 offset:2048
	ds_read_b128 v[230:233], v170 offset:3072
	v_lshl_add_u64 v[170:171], s[20:21], 0, v[0:1]
	s_mov_b32 m0, s50
	v_lshl_add_u64 v[200:201], s[20:21], 0, v[164:165]
	global_load_lds_dwordx4 v[170:171], off
	s_add_i32 m0, s50, 0x2000
	s_nop 0
	global_load_lds_dwordx4 v[200:201], off
	s_barrier
	s_waitcnt lgkmcnt(0)
	v_mfma_f32_16x16x32_bf16 v[134:137], v[218:221], v[176:179], v[134:137]
	v_mfma_f32_16x16x32_bf16 v[130:133], v[226:229], v[176:179], v[130:133]
	v_mfma_f32_16x16x32_bf16 v[118:121], v[218:221], v[184:187], v[118:121]
	v_mfma_f32_16x16x32_bf16 v[114:117], v[226:229], v[184:187], v[114:117]
	v_mfma_f32_16x16x32_bf16 v[102:105], v[218:221], v[192:195], v[102:105]
	v_mfma_f32_16x16x32_bf16 v[98:101], v[226:229], v[192:195], v[98:101]
	v_mfma_f32_16x16x32_bf16 v[86:89], v[218:221], v[210:213], v[86:89]
	v_mfma_f32_16x16x32_bf16 v[82:85], v[226:229], v[210:213], v[82:85]
	v_mfma_f32_16x16x32_bf16 v[134:137], v[222:225], v[180:183], v[134:137]
	v_mfma_f32_16x16x32_bf16 v[130:133], v[230:233], v[180:183], v[130:133]
	v_mfma_f32_16x16x32_bf16 v[118:121], v[222:225], v[188:191], v[118:121]
	v_mfma_f32_16x16x32_bf16 v[114:117], v[230:233], v[188:191], v[114:117]
	v_mfma_f32_16x16x32_bf16 v[102:105], v[222:225], v[196:199], v[102:105]
	v_mfma_f32_16x16x32_bf16 v[98:101], v[230:233], v[196:199], v[98:101]
	v_mfma_f32_16x16x32_bf16 v[86:89], v[222:225], v[214:217], v[86:89]
	v_mfma_f32_16x16x32_bf16 v[82:85], v[230:233], v[214:217], v[82:85]
	s_mov_b32 m0, s3
	v_lshl_add_u64 v[234:235], s[22:23], 0, v[160:161]
	s_barrier
	ds_read_b128 v[176:179], v174 offset:16384
	ds_read_b128 v[180:183], v174 offset:17408
	ds_read_b128 v[184:187], v174 offset:18432
	ds_read_b128 v[188:191], v174 offset:19456
	ds_read_b128 v[192:195], v174 offset:20480
	ds_read_b128 v[196:199], v174 offset:21504
	ds_read_b128 v[210:213], v174 offset:22528
	ds_read_b128 v[214:217], v174 offset:23552
	global_load_lds_dwordx4 v[234:235], off
	v_lshl_add_u64 v[236:237], s[22:23], 0, v[162:163]
	s_mov_b32 m0, s34
	s_nop 0
	global_load_lds_dwordx4 v[236:237], off
	s_barrier
	s_waitcnt lgkmcnt(0)
	v_mfma_f32_16x16x32_bf16 v[78:81], v[50:53], v[176:179], v[78:81]
	v_mfma_f32_16x16x32_bf16 v[74:77], v[66:69], v[176:179], v[74:77]
	v_mfma_f32_16x16x32_bf16 v[46:49], v[50:53], v[184:187], v[46:49]
	v_mfma_f32_16x16x32_bf16 v[42:45], v[66:69], v[184:187], v[42:45]
	v_mfma_f32_16x16x32_bf16 v[30:33], v[50:53], v[192:195], v[30:33]
	v_mfma_f32_16x16x32_bf16 v[26:29], v[66:69], v[192:195], v[26:29]
	v_mfma_f32_16x16x32_bf16 v[14:17], v[50:53], v[210:213], v[14:17]
	v_mfma_f32_16x16x32_bf16 v[10:13], v[66:69], v[210:213], v[10:13]
	v_mfma_f32_16x16x32_bf16 v[78:81], v[54:57], v[180:183], v[78:81]
	v_mfma_f32_16x16x32_bf16 v[74:77], v[70:73], v[180:183], v[74:77]
	v_mfma_f32_16x16x32_bf16 v[46:49], v[54:57], v[188:191], v[46:49]
	v_mfma_f32_16x16x32_bf16 v[42:45], v[70:73], v[188:191], v[42:45]
	v_mfma_f32_16x16x32_bf16 v[30:33], v[54:57], v[196:199], v[30:33]
	v_mfma_f32_16x16x32_bf16 v[26:29], v[70:73], v[196:199], v[26:29]
	v_mfma_f32_16x16x32_bf16 v[14:17], v[54:57], v[214:217], v[14:17]
	v_mfma_f32_16x16x32_bf16 v[10:13], v[70:73], v[214:217], v[10:13]
	s_barrier
	s_add_u32 s52, s20, 0x200000
	s_addc_u32 s53, s21, 0
	s_add_i32 s50, s54, s31
	v_lshl_add_u64 v[50:51], s[52:53], 0, v[0:1]
	s_mov_b32 m0, s50
	s_nop 0
	global_load_lds_dwordx4 v[50:51], off
	v_lshl_add_u64 v[50:51], s[52:53], 0, v[164:165]
	s_add_i32 m0, s50, 0x2000
	s_nop 0
	global_load_lds_dwordx4 v[50:51], off
	s_waitcnt vmcnt(6)
	s_barrier
	v_mfma_f32_16x16x32_bf16 v[38:41], v[218:221], v[184:187], v[38:41]
	v_mfma_f32_16x16x32_bf16 v[34:37], v[226:229], v[184:187], v[34:37]
	v_mfma_f32_16x16x32_bf16 v[22:25], v[218:221], v[192:195], v[22:25]
	v_mfma_f32_16x16x32_bf16 v[18:21], v[226:229], v[192:195], v[18:21]
	v_mfma_f32_16x16x32_bf16 v[6:9], v[218:221], v[210:213], v[6:9]
	v_mfma_f32_16x16x32_bf16 v[2:5], v[226:229], v[210:213], v[2:5]
	v_mfma_f32_16x16x32_bf16 v[50:53], v[218:221], v[176:179], v[62:65]
	v_mfma_f32_16x16x32_bf16 v[54:57], v[226:229], v[176:179], v[58:61]
	v_mfma_f32_16x16x32_bf16 v[38:41], v[222:225], v[188:191], v[38:41]
	v_mfma_f32_16x16x32_bf16 v[34:37], v[230:233], v[188:191], v[34:37]
	v_mfma_f32_16x16x32_bf16 v[22:25], v[222:225], v[196:199], v[22:25]
	v_mfma_f32_16x16x32_bf16 v[18:21], v[230:233], v[196:199], v[18:21]
	v_mfma_f32_16x16x32_bf16 v[6:9], v[222:225], v[214:217], v[6:9]
	v_mfma_f32_16x16x32_bf16 v[2:5], v[230:233], v[214:217], v[2:5]
	v_mfma_f32_16x16x32_bf16 v[50:53], v[222:225], v[180:183], v[50:53]
	v_mfma_f32_16x16x32_bf16 v[54:57], v[230:233], v[180:183], v[54:57]
	s_add_i32 s50, 0, 0x18000
	v_add_u32_e32 v70, s50, v173
	s_barrier
	ds_read_b128 v[58:61], v70
	ds_read_b128 v[62:65], v70 offset:1024
	ds_read_b128 v[66:69], v70 offset:2048
	ds_read_b128 v[70:73], v70 offset:3072
	s_add_u32 s22, s22, 0x200000
	s_addc_u32 s23, s23, 0
	s_mov_b32 m0, s35
	v_lshl_add_u64 v[218:219], s[22:23], 0, v[160:161]
	ds_read_b128 v[176:179], v174 offset:32768
	ds_read_b128 v[180:183], v174 offset:33792
	ds_read_b128 v[184:187], v174 offset:34816
	ds_read_b128 v[188:191], v174 offset:35840
	ds_read_b128 v[192:195], v174 offset:36864
	ds_read_b128 v[196:199], v174 offset:37888
	ds_read_b128 v[210:213], v174 offset:38912
	ds_read_b128 v[214:217], v174 offset:39936
	global_load_lds_dwordx4 v[218:219], off
	v_lshl_add_u64 v[218:219], s[22:23], 0, v[162:163]
	s_mov_b32 m0, s36
	s_nop 0
	global_load_lds_dwordx4 v[218:219], off
	s_waitcnt lgkmcnt(8)
	s_barrier
; #define PG8_STAGE(bufoff, gbase, voff) do { _Pragma("unroll") for (int _i = 0; _i < 2; ++_i) \
;         __builtin_amdgcn_global_load_lds((const unsigned*)((const char*)(gbase) + (voff)[_i]), (LAS unsigned*)(lds + (bufoff) + ldsw + _i * 8192), 16, 0, 0); } while (0)
; #define PG8_LDA(dst, b, h) do { _Pragma("unroll") for (int m = 0; m < 4; ++m) _Pragma("unroll") for (int k = 0; k < 2; ++k) dst[m][k] = *(const LAS bf16x8*)(lds + PG8_SA(b, h) + aoff + m * 2048 + k * 1024); } while (0)
; #define PG8_LDB(dst, b, h) do { _Pragma("unroll") for (int n = 0; n < 2; ++n) _Pragma("unroll") for (int k = 0; k < 2; ++k) dst[n][k] = *(const LAS bf16x8*)(lds + PG8_SB(b, h) + boff + n * 2048 + k * 1024); } while (0)
; #define PG8_MMA(ai, bj, At, Bt) do { __builtin_amdgcn_s_setprio(1); _Pragma("unroll") for (int m = 0; m < 4; ++m) _Pragma("unroll") for (int n = 0; n < 2; ++n) _Pragma("unroll") for (int k = 0; k < 2; ++k) \
;         acc[ai][bj][m][n] = __builtin_amdgcn_mfma_f32_16x16x32_bf16(Bt[n][k], At[m][k], acc[ai][bj][m][n], 0, 0, 0); __builtin_amdgcn_s_setprio(0); } while (0)
; #define PG8_WAIT_V(n) asm volatile("s_waitcnt vmcnt(" #n ")" ::: "memory")
; #define PG8_WAIT_L(n) asm volatile("s_waitcnt lgkmcnt(" #n ")" ::: "memory")
; #define PG8_BAR __builtin_amdgcn_s_barrier()
; #define PG8_SCHED __builtin_amdgcn_sched_barrier(0)
; template <class Epi>
; __device__ __forceinline__ void gemm_phase(LAS unsigned char* lds, const Gemm g, const StaticOrder& S, const Epi& E, const int tid) {
;     ...
;             PG8_WAIT_L(8); PG8_BAR; PG8_WAIT_L(0); PG8_MMA(0, 0, At, B0); PG8_BAR; PG8_SCHED;
;             PG8_LDB(B1, 1, 1); PG8_STAGE(PG8_SB(1, 0), b3, voffB);
;             PG8_BAR; PG8_WAIT_L(0); PG8_MMA(0, 1, At, B1); PG8_BAR;
;             PG8_LDA(At, 1, 1); PG8_STAGE(PG8_SA(1, 0), a3, voffA);
;             PG8_BAR; PG8_WAIT_L(0); PG8_MMA(1, 0, At, B0); PG8_BAR; PG8_SCHED;
;             PG8_STAGE(PG8_SB(1, 1), b3 + hstep, voffB);
;             PG8_WAIT_V(6); PG8_BAR; PG8_MMA(1, 1, At, B1); PG8_BAR;
	s_waitcnt lgkmcnt(0)
	v_mfma_f32_16x16x32_bf16 v[142:145], v[58:61], v[176:179], v[142:145]
	v_mfma_f32_16x16x32_bf16 v[138:141], v[66:69], v[176:179], v[138:141]
	v_mfma_f32_16x16x32_bf16 v[126:129], v[58:61], v[184:187], v[126:129]
	v_mfma_f32_16x16x32_bf16 v[122:125], v[66:69], v[184:187], v[122:125]
	v_mfma_f32_16x16x32_bf16 v[110:113], v[58:61], v[192:195], v[110:113]
	v_mfma_f32_16x16x32_bf16 v[106:109], v[66:69], v[192:195], v[106:109]
	v_mfma_f32_16x16x32_bf16 v[94:97], v[58:61], v[210:213], v[94:97]
	v_mfma_f32_16x16x32_bf16 v[90:93], v[66:69], v[210:213], v[90:93]
	v_mfma_f32_16x16x32_bf16 v[142:145], v[62:65], v[180:183], v[142:145]
	v_mfma_f32_16x16x32_bf16 v[138:141], v[70:73], v[180:183], v[138:141]
	v_mfma_f32_16x16x32_bf16 v[126:129], v[62:65], v[188:191], v[126:129]
	v_mfma_f32_16x16x32_bf16 v[122:125], v[70:73], v[188:191], v[122:125]
	v_mfma_f32_16x16x32_bf16 v[110:113], v[62:65], v[196:199], v[110:113]
	v_mfma_f32_16x16x32_bf16 v[106:109], v[70:73], v[196:199], v[106:109]
	v_mfma_f32_16x16x32_bf16 v[94:97], v[62:65], v[214:217], v[94:97]
	v_mfma_f32_16x16x32_bf16 v[90:93], v[70:73], v[214:217], v[90:93]
	s_barrier
	s_add_i32 s22, 0, 0x1c000
	s_add_i32 s23, s50, s31
	v_add_u32_e32 v175, s22, v173
	v_lshl_add_u64 v[170:171], v[170:171], 0, s[56:57]
	s_mov_b32 m0, s23
	ds_read_b128 v[218:221], v175
	ds_read_b128 v[222:225], v175 offset:1024
	ds_read_b128 v[226:229], v175 offset:2048
	ds_read_b128 v[230:233], v175 offset:3072
	global_load_lds_dwordx4 v[170:171], off
	v_lshl_add_u64 v[170:171], v[200:201], 0, s[56:57]
	s_add_i32 m0, s23, 0x2000
	s_nop 0
	global_load_lds_dwordx4 v[170:171], off
	s_barrier
	s_waitcnt lgkmcnt(0)
	v_mfma_f32_16x16x32_bf16 v[134:137], v[218:221], v[176:179], v[134:137]
	v_mfma_f32_16x16x32_bf16 v[130:133], v[226:229], v[176:179], v[130:133]
	v_mfma_f32_16x16x32_bf16 v[118:121], v[218:221], v[184:187], v[118:121]
	v_mfma_f32_16x16x32_bf16 v[114:117], v[226:229], v[184:187], v[114:117]
	v_mfma_f32_16x16x32_bf16 v[102:105], v[218:221], v[192:195], v[102:105]
	v_mfma_f32_16x16x32_bf16 v[98:101], v[226:229], v[192:195], v[98:101]
	v_mfma_f32_16x16x32_bf16 v[86:89], v[218:221], v[210:213], v[86:89]
	v_mfma_f32_16x16x32_bf16 v[82:85], v[226:229], v[210:213], v[82:85]
	v_mfma_f32_16x16x32_bf16 v[134:137], v[222:225], v[180:183], v[134:137]
	v_mfma_f32_16x16x32_bf16 v[130:133], v[230:233], v[180:183], v[130:133]
	v_mfma_f32_16x16x32_bf16 v[118:121], v[222:225], v[188:191], v[118:121]
	v_mfma_f32_16x16x32_bf16 v[114:117], v[230:233], v[188:191], v[114:117]
	v_mfma_f32_16x16x32_bf16 v[102:105], v[222:225], v[196:199], v[102:105]
	v_mfma_f32_16x16x32_bf16 v[98:101], v[230:233], v[196:199], v[98:101]
	v_mfma_f32_16x16x32_bf16 v[86:89], v[222:225], v[214:217], v[86:89]
	v_mfma_f32_16x16x32_bf16 v[82:85], v[230:233], v[214:217], v[82:85]
	s_mov_b32 m0, s39
	v_lshl_add_u64 v[170:171], v[234:235], 0, s[56:57]
	s_barrier
	ds_read_b128 v[176:179], v174 offset:49152
	ds_read_b128 v[180:183], v174 offset:50176
	ds_read_b128 v[184:187], v174 offset:51200
	ds_read_b128 v[188:191], v174 offset:52224
	ds_read_b128 v[192:195], v174 offset:53248
	ds_read_b128 v[196:199], v174 offset:54272
	ds_read_b128 v[210:213], v174 offset:55296
	ds_read_b128 v[214:217], v174 offset:56320
	global_load_lds_dwordx4 v[170:171], off
	v_lshl_add_u64 v[170:171], v[236:237], 0, s[56:57]
	s_mov_b32 m0, s40
	s_nop 0
	global_load_lds_dwordx4 v[170:171], off
	s_barrier
	s_waitcnt lgkmcnt(0)
	v_mfma_f32_16x16x32_bf16 v[78:81], v[58:61], v[176:179], v[78:81]
	v_mfma_f32_16x16x32_bf16 v[74:77], v[66:69], v[176:179], v[74:77]
	v_mfma_f32_16x16x32_bf16 v[46:49], v[58:61], v[184:187], v[46:49]
	v_mfma_f32_16x16x32_bf16 v[42:45], v[66:69], v[184:187], v[42:45]
	v_mfma_f32_16x16x32_bf16 v[30:33], v[58:61], v[192:195], v[30:33]
	v_mfma_f32_16x16x32_bf16 v[26:29], v[66:69], v[192:195], v[26:29]
	v_mfma_f32_16x16x32_bf16 v[14:17], v[58:61], v[210:213], v[14:17]
	v_mfma_f32_16x16x32_bf16 v[10:13], v[66:69], v[210:213], v[10:13]
	v_mfma_f32_16x16x32_bf16 v[78:81], v[62:65], v[180:183], v[78:81]
	v_mfma_f32_16x16x32_bf16 v[74:77], v[70:73], v[180:183], v[74:77]
	v_mfma_f32_16x16x32_bf16 v[46:49], v[62:65], v[188:191], v[46:49]
	v_mfma_f32_16x16x32_bf16 v[42:45], v[70:73], v[188:191], v[42:45]
	v_mfma_f32_16x16x32_bf16 v[30:33], v[62:65], v[196:199], v[30:33]
	v_mfma_f32_16x16x32_bf16 v[26:29], v[70:73], v[196:199], v[26:29]
	v_mfma_f32_16x16x32_bf16 v[14:17], v[62:65], v[214:217], v[14:17]
	v_mfma_f32_16x16x32_bf16 v[10:13], v[70:73], v[214:217], v[10:13]
	s_barrier
	s_add_u32 s20, s20, 0x200080
	s_addc_u32 s21, s21, 0
	s_add_i32 s22, s22, s31
	v_lshl_add_u64 v[58:59], s[20:21], 0, v[0:1]
	s_mov_b32 m0, s22
	s_nop 0
	global_load_lds_dwordx4 v[58:59], off
	v_lshl_add_u64 v[58:59], s[20:21], 0, v[164:165]
	s_add_i32 m0, s22, 0x2000
	s_nop 0
	global_load_lds_dwordx4 v[58:59], off
	s_waitcnt vmcnt(6)
	s_barrier
	v_mfma_f32_16x16x32_bf16 v[50:53], v[218:221], v[176:179], v[50:53]
	v_mfma_f32_16x16x32_bf16 v[62:65], v[222:225], v[180:183], v[50:53]
	v_mfma_f32_16x16x32_bf16 v[50:53], v[226:229], v[176:179], v[54:57]
	v_mfma_f32_16x16x32_bf16 v[38:41], v[218:221], v[184:187], v[38:41]
	v_mfma_f32_16x16x32_bf16 v[34:37], v[226:229], v[184:187], v[34:37]
	v_mfma_f32_16x16x32_bf16 v[22:25], v[218:221], v[192:195], v[22:25]
	v_mfma_f32_16x16x32_bf16 v[18:21], v[226:229], v[192:195], v[18:21]
	v_mfma_f32_16x16x32_bf16 v[6:9], v[218:221], v[210:213], v[6:9]
	v_mfma_f32_16x16x32_bf16 v[2:5], v[226:229], v[210:213], v[2:5]
	v_mfma_f32_16x16x32_bf16 v[58:61], v[230:233], v[180:183], v[50:53]
	v_mfma_f32_16x16x32_bf16 v[38:41], v[222:225], v[188:191], v[38:41]
	v_mfma_f32_16x16x32_bf16 v[34:37], v[230:233], v[188:191], v[34:37]
	v_mfma_f32_16x16x32_bf16 v[22:25], v[222:225], v[196:199], v[22:25]
	v_mfma_f32_16x16x32_bf16 v[18:21], v[230:233], v[196:199], v[18:21]
	v_mfma_f32_16x16x32_bf16 v[6:9], v[222:225], v[214:217], v[6:9]
	v_mfma_f32_16x16x32_bf16 v[2:5], v[230:233], v[214:217], v[2:5]
	s_add_i32 s49, s49, 2
	s_add_u32 s47, s47, 0x100
	s_addc_u32 s48, s48, 0
	s_add_u32 s18, s18, 0x100
	s_addc_u32 s19, s19, 0
	s_cmpk_gt_u32 s49, 0x7d
	s_barrier
; __device__ __forceinline__ unsigned pk2(float lo, float hi) { f32x2 v = {lo, hi}; return __builtin_bit_cast(unsigned, __builtin_convertvector(v, bf16x2_t)); }
; __device__ __forceinline__ float bf_lo(unsigned w) { return __uint_as_float(w << 16); }
; __device__ __forceinline__ float bf_hi(unsigned w) { return __uint_as_float(w & 0xffff0000u); }
;     __device__ __forceinline__ void operator()(const f32x4 (&acc)[2][2][4][2], const Unit& u, int wr, int wc, int fr, int fq) const {
;         asm volatile("" : "+v"(fr), "+v"(fq));
;         const int row0 = u.pm * BM + wr * 64 + fr, col0 = u.pn * BM + wc * 32 + 8 * fq;
;         const float* gp = gate + (size_t)(u.pm >> 5) * 12288 + col0;
;         f32x4 gv[2][2];
; #pragma unroll
;         for (int bj = 0; bj < 2; ++bj)
; #pragma unroll
;             for (int n = 0; n < 2; ++n) gv[bj][n] = *(const f32x4*)(gp + bj * HALF + 4 * n);
; #pragma unroll
;         for (int ai = 0; ai < 2; ++ai)
; #pragma unroll
;             for (int m = 0; m < 4; ++m) {
;                 const size_t ro = (size_t)(row0 + ai * HALF + m * 16) * DM + col0;
; #pragma unroll
;                 for (int bj = 0; bj < 2; ++bj) {
;                     f32x4 r0, r1;
;                     if (RB) { const u32x4 rw = *(const u32x4*)((const bf16_t*)resid + ro + bj * HALF);
;                         r0 = (f32x4){bf_lo(rw.x), bf_hi(rw.x), bf_lo(rw.y), bf_hi(rw.y)}; r1 = (f32x4){bf_lo(rw.z), bf_hi(rw.z), bf_lo(rw.w), bf_hi(rw.w)}; }
;                     else { r0 = *(const f32x4*)((const float*)resid + ro + bj * HALF); r1 = *(const f32x4*)((const float*)resid + ro + bj * HALF + 4); }
;                     const f32x4 v0 = r0 + gv[bj][0] * acc[ai][bj][m][0], v1 = r1 + gv[bj][1] * acc[ai][bj][m][1];
;                     if (OB) { u32x4 w; w.x = pk2(v0[0], v0[1]); w.y = pk2(v0[2], v0[3]); w.z = pk2(v1[0], v1[1]); w.w = pk2(v1[2], v1[3]); *(u32x4*)((bf16_t*)out + ro + bj * HALF) = w; }
;                     else { *(f32x4*)((float*)out + ro + bj * HALF) = v0; *(f32x4*)((float*)out + ro + bj * HALF + 4) = v1; }
	s_cbranch_scc0 .LBB0_40
	s_setprio 0
	s_lshl_b32 s11, s2, 8
	s_lshl_b32 s13, s43, 8
	v_mov_b32_e32 v50, v172
	v_mov_b32_e32 v175, v159
	s_add_i32 s11, s11, s37
	s_or_b32 s13, s13, s38
	s_ashr_i32 s2, s2, 5
	s_mov_b32 s43, s10
	v_lshl_add_u32 v170, v50, 3, s13
	s_mul_hi_i32 s13, s2, 0xc000
	s_mul_i32 s2, s2, 0xc000
	v_add_u32_e32 v176, s11, v175
	s_add_u32 s18, s27, s2
	v_ashrrev_i32_e32 v177, 31, v176
	s_addc_u32 s19, s28, s13
	v_ashrrev_i32_e32 v171, 31, v170
	v_lshlrev_b64 v[176:177], 11, v[176:177]
	v_lshl_add_u64 v[54:55], v[170:171], 2, s[18:19]
	v_lshl_add_u64 v[170:171], v[176:177], 0, v[170:171]
	v_lshl_add_u64 v[180:181], v[170:171], 1, s[8:9]
	global_load_dwordx4 v[66:69], v[54:55], off offset:16
	global_load_dwordx4 v[70:73], v[54:55], off
	global_load_dwordx4 v[50:53], v[54:55], off offset:528
	s_nop 0
	global_load_dwordx4 v[54:57], v[54:55], off offset:512
	v_lshlrev_b32_e32 v175, 1, v170
	v_lshlrev_b32_e32 v200, 2, v170
	s_mov_b64 s[92:93], s[8:9]
	s_mov_b64 s[94:95], s[6:7]
	global_load_dwordx4 v[184:187], v175, s[92:93]
	global_load_dwordx4 v[188:191], v175, s[92:93] offset:256
	s_add_u32 s92, s92, 0x10000
	s_addc_u32 s93, s93, 0
	global_load_dwordx4 v[192:195], v175, s[92:93]
	global_load_dwordx4 v[196:199], v175, s[92:93] offset:256
	s_add_u32 s92, s92, 0x10000
	s_addc_u32 s93, s93, 0
	global_load_dwordx4 v[210:213], v175, s[92:93]
	global_load_dwordx4 v[214:217], v175, s[92:93] offset:256
	s_add_u32 s92, s92, 0x10000
	s_addc_u32 s93, s93, 0
	global_load_dwordx4 v[218:221], v175, s[92:93]
	global_load_dwordx4 v[222:225], v175, s[92:93] offset:256
	s_add_u32 s92, s92, 0x50000
	s_addc_u32 s93, s93, 0
	global_load_dwordx4 v[226:229], v175, s[92:93]
	global_load_dwordx4 v[230:233], v175, s[92:93] offset:256
	s_add_u32 s92, s92, 0x10000
	s_addc_u32 s93, s93, 0
	global_load_dwordx4 v[234:237], v175, s[92:93]
	s_waitcnt vmcnt(10)
	v_lshlrev_b32_e32 v176, 16, v184
	v_and_b32_e32 v177, 0xffff0000, v184
	v_lshlrev_b32_e32 v178, 16, v185
	v_and_b32_e32 v179, 0xffff0000, v185
	v_lshlrev_b32_e32 v180, 16, v186
	v_and_b32_e32 v181, 0xffff0000, v186
	v_lshlrev_b32_e32 v182, 16, v187
	v_and_b32_e32 v183, 0xffff0000, v187
	v_pk_fma_f32 v[142:143], v[142:143], v[70:71], v[176:177]
	v_pk_fma_f32 v[144:145], v[144:145], v[72:73], v[178:179]
	v_pk_fma_f32 v[138:139], v[138:139], v[66:67], v[180:181]
	v_pk_fma_f32 v[140:141], v[140:141], v[68:69], v[182:183]
	global_load_dwordx4 v[184:187], v175, s[92:93] offset:256
	global_store_dwordx4 v200, v[142:145], s[94:95]
	global_store_dwordx4 v200, v[138:141], s[94:95] offset:16
	s_waitcnt vmcnt(12)
	v_lshlrev_b32_e32 v176, 16, v188
	v_and_b32_e32 v177, 0xffff0000, v188
	v_lshlrev_b32_e32 v178, 16, v189
	v_and_b32_e32 v179, 0xffff0000, v189
	v_lshlrev_b32_e32 v180, 16, v190
	v_and_b32_e32 v181, 0xffff0000, v190
	v_lshlrev_b32_e32 v182, 16, v191
	v_and_b32_e32 v183, 0xffff0000, v191
	v_pk_fma_f32 v[134:135], v[134:135], v[54:55], v[176:177]
	v_pk_fma_f32 v[136:137], v[136:137], v[56:57], v[178:179]
	v_pk_fma_f32 v[130:131], v[130:131], v[50:51], v[180:181]
	v_pk_fma_f32 v[132:133], v[132:133], v[52:53], v[182:183]
	s_add_u32 s92, s92, 0x10000
	s_addc_u32 s93, s93, 0
	global_load_dwordx4 v[188:191], v175, s[92:93]
	global_store_dwordx4 v200, v[134:137], s[94:95] offset:512
	global_store_dwordx4 v200, v[130:133], s[94:95] offset:528
	s_waitcnt vmcnt(14)
	v_lshlrev_b32_e32 v176, 16, v192
	v_and_b32_e32 v177, 0xffff0000, v192
	v_lshlrev_b32_e32 v178, 16, v193
	v_and_b32_e32 v179, 0xffff0000, v193
	v_lshlrev_b32_e32 v180, 16, v194
	v_and_b32_e32 v181, 0xffff0000, v194
	v_lshlrev_b32_e32 v182, 16, v195
	v_and_b32_e32 v183, 0xffff0000, v195
	v_pk_fma_f32 v[126:127], v[126:127], v[70:71], v[176:177]
	v_pk_fma_f32 v[128:129], v[128:129], v[72:73], v[178:179]
	v_pk_fma_f32 v[122:123], v[122:123], v[66:67], v[180:181]
	v_pk_fma_f32 v[124:125], v[124:125], v[68:69], v[182:183]
	global_load_dwordx4 v[192:195], v175, s[92:93] offset:256
	s_add_u32 s94, s94, 0x20000
	s_addc_u32 s95, s95, 0
	global_store_dwordx4 v200, v[126:129], s[94:95]
	global_store_dwordx4 v200, v[122:125], s[94:95] offset:16
	s_waitcnt vmcnt(16)
	v_lshlrev_b32_e32 v176, 16, v196
	v_and_b32_e32 v177, 0xffff0000, v196
	v_lshlrev_b32_e32 v178, 16, v197
	v_and_b32_e32 v179, 0xffff0000, v197
	v_lshlrev_b32_e32 v180, 16, v198
	v_and_b32_e32 v181, 0xffff0000, v198
	v_lshlrev_b32_e32 v182, 16, v199
	v_and_b32_e32 v183, 0xffff0000, v199
	v_pk_fma_f32 v[118:119], v[118:119], v[54:55], v[176:177]
	v_pk_fma_f32 v[120:121], v[120:121], v[56:57], v[178:179]
	v_pk_fma_f32 v[114:115], v[114:115], v[50:51], v[180:181]
	v_pk_fma_f32 v[116:117], v[116:117], v[52:53], v[182:183]
	s_add_u32 s92, s92, 0x10000
	s_addc_u32 s93, s93, 0
	global_load_dwordx4 v[196:199], v175, s[92:93]
	global_store_dwordx4 v200, v[118:121], s[94:95] offset:512
	global_store_dwordx4 v200, v[114:117], s[94:95] offset:528
	s_waitcnt vmcnt(18)
	v_lshlrev_b32_e32 v176, 16, v210
	v_and_b32_e32 v177, 0xffff0000, v210
	v_lshlrev_b32_e32 v178, 16, v211
	v_and_b32_e32 v179, 0xffff0000, v211
	v_lshlrev_b32_e32 v180, 16, v212
	v_and_b32_e32 v181, 0xffff0000, v212
	v_lshlrev_b32_e32 v182, 16, v213
	v_and_b32_e32 v183, 0xffff0000, v213
	v_pk_fma_f32 v[110:111], v[110:111], v[70:71], v[176:177]
	v_pk_fma_f32 v[112:113], v[112:113], v[72:73], v[178:179]
	v_pk_fma_f32 v[106:107], v[106:107], v[66:67], v[180:181]
	v_pk_fma_f32 v[108:109], v[108:109], v[68:69], v[182:183]
	global_load_dwordx4 v[210:213], v175, s[92:93] offset:256
	s_add_u32 s94, s94, 0x20000
	s_addc_u32 s95, s95, 0
	global_store_dwordx4 v200, v[110:113], s[94:95]
	global_store_dwordx4 v200, v[106:109], s[94:95] offset:16
	s_waitcnt vmcnt(20)
; __device__ __forceinline__ unsigned pk2(float lo, float hi) { f32x2 v = {lo, hi}; return __builtin_bit_cast(unsigned, __builtin_convertvector(v, bf16x2_t)); }
; __device__ __forceinline__ float bf_lo(unsigned w) { return __uint_as_float(w << 16); }
; __device__ __forceinline__ float bf_hi(unsigned w) { return __uint_as_float(w & 0xffff0000u); }
;     __device__ __forceinline__ void operator()(const f32x4 (&acc)[2][2][4][2], const Unit& u, int wr, int wc, int fr, int fq) const {
;     ...
;             for (int m = 0; m < 4; ++m) {
;                 const size_t ro = (size_t)(row0 + ai * HALF + m * 16) * DM + col0;
; #pragma unroll
;                 for (int bj = 0; bj < 2; ++bj) {
;                     f32x4 r0, r1;
;                     if (RB) { const u32x4 rw = *(const u32x4*)((const bf16_t*)resid + ro + bj * HALF);
;                         r0 = (f32x4){bf_lo(rw.x), bf_hi(rw.x), bf_lo(rw.y), bf_hi(rw.y)}; r1 = (f32x4){bf_lo(rw.z), bf_hi(rw.z), bf_lo(rw.w), bf_hi(rw.w)}; }
;                     else { r0 = *(const f32x4*)((const float*)resid + ro + bj * HALF); r1 = *(const f32x4*)((const float*)resid + ro + bj * HALF + 4); }
;                     const f32x4 v0 = r0 + gv[bj][0] * acc[ai][bj][m][0], v1 = r1 + gv[bj][1] * acc[ai][bj][m][1];
;                     if (OB) { u32x4 w; w.x = pk2(v0[0], v0[1]); w.y = pk2(v0[2], v0[3]); w.z = pk2(v1[0], v1[1]); w.w = pk2(v1[2], v1[3]); *(u32x4*)((bf16_t*)out + ro + bj * HALF) = w; }
;                     else { *(f32x4*)((float*)out + ro + bj * HALF) = v0; *(f32x4*)((float*)out + ro + bj * HALF + 4) = v1; }
	v_lshlrev_b32_e32 v176, 16, v214
	v_and_b32_e32 v177, 0xffff0000, v214
	v_lshlrev_b32_e32 v178, 16, v215
	v_and_b32_e32 v179, 0xffff0000, v215
	v_lshlrev_b32_e32 v180, 16, v216
	v_and_b32_e32 v181, 0xffff0000, v216
	v_lshlrev_b32_e32 v182, 16, v217
	v_and_b32_e32 v183, 0xffff0000, v217
	v_pk_fma_f32 v[102:103], v[102:103], v[54:55], v[176:177]
	v_pk_fma_f32 v[104:105], v[104:105], v[56:57], v[178:179]
	v_pk_fma_f32 v[98:99], v[98:99], v[50:51], v[180:181]
	v_pk_fma_f32 v[100:101], v[100:101], v[52:53], v[182:183]
	global_store_dwordx4 v200, v[102:105], s[94:95] offset:512
	global_store_dwordx4 v200, v[98:101], s[94:95] offset:528
	s_waitcnt vmcnt(21)
	v_lshlrev_b32_e32 v176, 16, v218
	v_and_b32_e32 v177, 0xffff0000, v218
	v_lshlrev_b32_e32 v178, 16, v219
	v_and_b32_e32 v179, 0xffff0000, v219
	v_lshlrev_b32_e32 v180, 16, v220
	v_and_b32_e32 v181, 0xffff0000, v220
	v_lshlrev_b32_e32 v182, 16, v221
	v_and_b32_e32 v183, 0xffff0000, v221
	v_pk_fma_f32 v[94:95], v[94:95], v[70:71], v[176:177]
	v_pk_fma_f32 v[96:97], v[96:97], v[72:73], v[178:179]
	v_pk_fma_f32 v[90:91], v[90:91], v[66:67], v[180:181]
	v_pk_fma_f32 v[92:93], v[92:93], v[68:69], v[182:183]
	s_add_u32 s94, s94, 0x20000
	s_addc_u32 s95, s95, 0
	global_store_dwordx4 v200, v[94:97], s[94:95]
	global_store_dwordx4 v200, v[90:93], s[94:95] offset:16
	s_waitcnt vmcnt(22)
	v_lshlrev_b32_e32 v176, 16, v222
	v_and_b32_e32 v177, 0xffff0000, v222
	v_lshlrev_b32_e32 v178, 16, v223
	v_and_b32_e32 v179, 0xffff0000, v223
	v_lshlrev_b32_e32 v180, 16, v224
	v_and_b32_e32 v181, 0xffff0000, v224
	v_lshlrev_b32_e32 v182, 16, v225
	v_and_b32_e32 v183, 0xffff0000, v225
	v_pk_fma_f32 v[86:87], v[86:87], v[54:55], v[176:177]
	v_pk_fma_f32 v[88:89], v[88:89], v[56:57], v[178:179]
	v_pk_fma_f32 v[82:83], v[82:83], v[50:51], v[180:181]
	v_pk_fma_f32 v[84:85], v[84:85], v[52:53], v[182:183]
	global_store_dwordx4 v200, v[86:89], s[94:95] offset:512
	global_store_dwordx4 v200, v[82:85], s[94:95] offset:528
	s_waitcnt vmcnt(23)
	v_lshlrev_b32_e32 v176, 16, v226
	v_and_b32_e32 v177, 0xffff0000, v226
	v_lshlrev_b32_e32 v178, 16, v227
	v_and_b32_e32 v179, 0xffff0000, v227
	v_lshlrev_b32_e32 v180, 16, v228
	v_and_b32_e32 v181, 0xffff0000, v228
	v_lshlrev_b32_e32 v182, 16, v229
	v_and_b32_e32 v183, 0xffff0000, v229
	v_pk_fma_f32 v[78:79], v[78:79], v[70:71], v[176:177]
	v_pk_fma_f32 v[80:81], v[80:81], v[72:73], v[178:179]
	v_pk_fma_f32 v[74:75], v[74:75], v[66:67], v[180:181]
	v_pk_fma_f32 v[76:77], v[76:77], v[68:69], v[182:183]
	s_add_u32 s94, s94, 0xa0000
	s_addc_u32 s95, s95, 0
	global_store_dwordx4 v200, v[78:81], s[94:95]
	global_store_dwordx4 v200, v[74:77], s[94:95] offset:16
	s_waitcnt vmcnt(24)
	v_lshlrev_b32_e32 v176, 16, v230
	v_and_b32_e32 v177, 0xffff0000, v230
	v_lshlrev_b32_e32 v178, 16, v231
	v_and_b32_e32 v179, 0xffff0000, v231
	v_lshlrev_b32_e32 v180, 16, v232
	v_and_b32_e32 v181, 0xffff0000, v232
	v_lshlrev_b32_e32 v182, 16, v233
	v_and_b32_e32 v183, 0xffff0000, v233
	v_pk_fma_f32 v[62:63], v[62:63], v[54:55], v[176:177]
	v_pk_fma_f32 v[64:65], v[64:65], v[56:57], v[178:179]
	v_pk_fma_f32 v[58:59], v[58:59], v[50:51], v[180:181]
	v_pk_fma_f32 v[60:61], v[60:61], v[52:53], v[182:183]
	global_store_dwordx4 v200, v[62:65], s[94:95] offset:512
	global_store_dwordx4 v200, v[58:61], s[94:95] offset:528
	s_waitcnt vmcnt(25)
	v_lshlrev_b32_e32 v176, 16, v234
	v_and_b32_e32 v177, 0xffff0000, v234
	v_lshlrev_b32_e32 v178, 16, v235
	v_and_b32_e32 v179, 0xffff0000, v235
	v_lshlrev_b32_e32 v180, 16, v236
	v_and_b32_e32 v181, 0xffff0000, v236
	v_lshlrev_b32_e32 v182, 16, v237
	v_and_b32_e32 v183, 0xffff0000, v237
	v_pk_fma_f32 v[46:47], v[46:47], v[70:71], v[176:177]
	v_pk_fma_f32 v[48:49], v[48:49], v[72:73], v[178:179]
	v_pk_fma_f32 v[42:43], v[42:43], v[66:67], v[180:181]
	v_pk_fma_f32 v[44:45], v[44:45], v[68:69], v[182:183]
	s_add_u32 s94, s94, 0x20000
	s_addc_u32 s95, s95, 0
	global_store_dwordx4 v200, v[46:49], s[94:95]
	global_store_dwordx4 v200, v[42:45], s[94:95] offset:16
	s_waitcnt vmcnt(26)
; __device__ __forceinline__ unsigned pk2(float lo, float hi) { f32x2 v = {lo, hi}; return __builtin_bit_cast(unsigned, __builtin_convertvector(v, bf16x2_t)); }
; __device__ __forceinline__ float bf_lo(unsigned w) { return __uint_as_float(w << 16); }
; __device__ __forceinline__ float bf_hi(unsigned w) { return __uint_as_float(w & 0xffff0000u); }
; #define PG8_WAIT_V(n) asm volatile("s_waitcnt vmcnt(" #n ")" ::: "memory")
; #define PG8_BAR __builtin_amdgcn_s_barrier()
;     __device__ __forceinline__ void operator()(const f32x4 (&acc)[2][2][4][2], const Unit& u, int wr, int wc, int fr, int fq) const {
;     ...
;             for (int m = 0; m < 4; ++m) {
;                 const size_t ro = (size_t)(row0 + ai * HALF + m * 16) * DM + col0;
; #pragma unroll
;                 for (int bj = 0; bj < 2; ++bj) {
;                     f32x4 r0, r1;
;                     if (RB) { const u32x4 rw = *(const u32x4*)((const bf16_t*)resid + ro + bj * HALF);
;                         r0 = (f32x4){bf_lo(rw.x), bf_hi(rw.x), bf_lo(rw.y), bf_hi(rw.y)}; r1 = (f32x4){bf_lo(rw.z), bf_hi(rw.z), bf_lo(rw.w), bf_hi(rw.w)}; }
;                     else { r0 = *(const f32x4*)((const float*)resid + ro + bj * HALF); r1 = *(const f32x4*)((const float*)resid + ro + bj * HALF + 4); }
;                     const f32x4 v0 = r0 + gv[bj][0] * acc[ai][bj][m][0], v1 = r1 + gv[bj][1] * acc[ai][bj][m][1];
;                     if (OB) { u32x4 w; w.x = pk2(v0[0], v0[1]); w.y = pk2(v0[2], v0[3]); w.z = pk2(v1[0], v1[1]); w.w = pk2(v1[2], v1[3]); *(u32x4*)((bf16_t*)out + ro + bj * HALF) = w; }
;                     else { *(f32x4*)((float*)out + ro + bj * HALF) = v0; *(f32x4*)((float*)out + ro + bj * HALF + 4) = v1; }
; template <class Epi>
; __device__ __forceinline__ void gemm_phase(LAS unsigned char* lds, const Gemm g, const StaticOrder& S, const Epi& E, const int tid) {
;     ...
;         E(acc, cur, wr, wc, fr, fq);
;         if (!has_next) break;
; #pragma unroll
;         for (int a = 0; a < 2; ++a)
; #pragma unroll
;             for (int b = 0; b < 2; ++b)
; #pragma unroll
;                 for (int m = 0; m < 4; ++m)
; #pragma unroll
;                     for (int n = 0; n < 2; ++n) acc[a][b][m][n] = (f32x4){0.f, 0.f, 0.f, 0.f};
;         cur = nxt; cA = nA; cB = nB; ++ui;
;     }
;     PG8_WAIT_V(0);
;     if (wr == 0) PG8_BAR;
;     PG8_BAR;
	v_lshlrev_b32_e32 v176, 16, v184
	v_and_b32_e32 v177, 0xffff0000, v184
	v_lshlrev_b32_e32 v178, 16, v185
	v_and_b32_e32 v179, 0xffff0000, v185
	v_lshlrev_b32_e32 v180, 16, v186
	v_and_b32_e32 v181, 0xffff0000, v186
	v_lshlrev_b32_e32 v182, 16, v187
	v_and_b32_e32 v183, 0xffff0000, v187
	v_pk_fma_f32 v[38:39], v[38:39], v[54:55], v[176:177]
	v_pk_fma_f32 v[40:41], v[40:41], v[56:57], v[178:179]
	v_pk_fma_f32 v[34:35], v[34:35], v[50:51], v[180:181]
	v_pk_fma_f32 v[36:37], v[36:37], v[52:53], v[182:183]
	global_store_dwordx4 v200, v[38:41], s[94:95] offset:512
	global_store_dwordx4 v200, v[34:37], s[94:95] offset:528
	s_waitcnt vmcnt(25)
	v_lshlrev_b32_e32 v176, 16, v188
	v_and_b32_e32 v177, 0xffff0000, v188
	v_lshlrev_b32_e32 v178, 16, v189
	v_and_b32_e32 v179, 0xffff0000, v189
	v_lshlrev_b32_e32 v180, 16, v190
	v_and_b32_e32 v181, 0xffff0000, v190
	v_lshlrev_b32_e32 v182, 16, v191
	v_and_b32_e32 v183, 0xffff0000, v191
	v_pk_fma_f32 v[30:31], v[30:31], v[70:71], v[176:177]
	v_pk_fma_f32 v[32:33], v[32:33], v[72:73], v[178:179]
	v_pk_fma_f32 v[26:27], v[26:27], v[66:67], v[180:181]
	v_pk_fma_f32 v[28:29], v[28:29], v[68:69], v[182:183]
	s_add_u32 s94, s94, 0x20000
	s_addc_u32 s95, s95, 0
	global_store_dwordx4 v200, v[30:33], s[94:95]
	global_store_dwordx4 v200, v[26:29], s[94:95] offset:16
	s_waitcnt vmcnt(24)
	v_lshlrev_b32_e32 v176, 16, v192
	v_and_b32_e32 v177, 0xffff0000, v192
	v_lshlrev_b32_e32 v178, 16, v193
	v_and_b32_e32 v179, 0xffff0000, v193
	v_lshlrev_b32_e32 v180, 16, v194
	v_and_b32_e32 v181, 0xffff0000, v194
	v_lshlrev_b32_e32 v182, 16, v195
	v_and_b32_e32 v183, 0xffff0000, v195
	v_pk_fma_f32 v[22:23], v[22:23], v[54:55], v[176:177]
	v_pk_fma_f32 v[24:25], v[24:25], v[56:57], v[178:179]
	v_pk_fma_f32 v[18:19], v[18:19], v[50:51], v[180:181]
	v_pk_fma_f32 v[20:21], v[20:21], v[52:53], v[182:183]
	global_store_dwordx4 v200, v[22:25], s[94:95] offset:512
	global_store_dwordx4 v200, v[18:21], s[94:95] offset:528
	s_waitcnt vmcnt(23)
	v_lshlrev_b32_e32 v176, 16, v196
	v_and_b32_e32 v177, 0xffff0000, v196
	v_lshlrev_b32_e32 v178, 16, v197
	v_and_b32_e32 v179, 0xffff0000, v197
	v_lshlrev_b32_e32 v180, 16, v198
	v_and_b32_e32 v181, 0xffff0000, v198
	v_lshlrev_b32_e32 v182, 16, v199
	v_and_b32_e32 v183, 0xffff0000, v199
	v_pk_fma_f32 v[14:15], v[14:15], v[70:71], v[176:177]
	v_pk_fma_f32 v[16:17], v[16:17], v[72:73], v[178:179]
	v_pk_fma_f32 v[10:11], v[10:11], v[66:67], v[180:181]
	v_pk_fma_f32 v[12:13], v[12:13], v[68:69], v[182:183]
	s_add_u32 s94, s94, 0x20000
	s_addc_u32 s95, s95, 0
	global_store_dwordx4 v200, v[14:17], s[94:95]
	global_store_dwordx4 v200, v[10:13], s[94:95] offset:16
	s_waitcnt vmcnt(22)
	v_lshlrev_b32_e32 v176, 16, v210
	v_and_b32_e32 v177, 0xffff0000, v210
	v_lshlrev_b32_e32 v178, 16, v211
	v_and_b32_e32 v179, 0xffff0000, v211
	v_lshlrev_b32_e32 v180, 16, v212
	v_and_b32_e32 v181, 0xffff0000, v212
	v_lshlrev_b32_e32 v182, 16, v213
	v_and_b32_e32 v183, 0xffff0000, v213
	v_pk_fma_f32 v[6:7], v[6:7], v[54:55], v[176:177]
	v_pk_fma_f32 v[8:9], v[8:9], v[56:57], v[178:179]
	v_pk_fma_f32 v[2:3], v[2:3], v[50:51], v[180:181]
	v_pk_fma_f32 v[4:5], v[4:5], v[52:53], v[182:183]
	global_store_dwordx4 v200, v[6:9], s[94:95] offset:512
	global_store_dwordx4 v200, v[2:5], s[94:95] offset:528
	s_mov_b32 s2, s12
	s_mov_b64 s[20:21], s[14:15]
	s_mov_b64 s[18:19], s[16:17]
	s_and_b64 vcc, exec, s[4:5]
	s_nop 1
	s_cbranch_vccz .LBB0_33
	s_waitcnt vmcnt(0)
	s_cmpk_gt_u32 s29, 0xff
	s_cbranch_scc1 .LBB0_44
	s_barrier

; #define PG8_STAGE(bufoff, gbase, voff) do { _Pragma("unroll") for (int _i = 0; _i < 2; ++_i) \
;         __builtin_amdgcn_global_load_lds((const unsigned*)((const char*)(gbase) + (voff)[_i]), (LAS unsigned*)(lds + (bufoff) + ldsw + _i * 8192), 16, 0, 0); } while (0)
; #define PG8_LDA(dst, b, h) do { _Pragma("unroll") for (int m = 0; m < 4; ++m) _Pragma("unroll") for (int k = 0; k < 2; ++k) dst[m][k] = *(const LAS bf16x8*)(lds + PG8_SA(b, h) + aoff + m * 2048 + k * 1024); } while (0)
; #define PG8_LDB(dst, b, h) do { _Pragma("unroll") for (int n = 0; n < 2; ++n) _Pragma("unroll") for (int k = 0; k < 2; ++k) dst[n][k] = *(const LAS bf16x8*)(lds + PG8_SB(b, h) + boff + n * 2048 + k * 1024); } while (0)
; #define PG8_MMA(ai, bj, At, Bt) do { __builtin_amdgcn_s_setprio(1); _Pragma("unroll") for (int m = 0; m < 4; ++m) _Pragma("unroll") for (int n = 0; n < 2; ++n) _Pragma("unroll") for (int k = 0; k < 2; ++k) \
;         acc[ai][bj][m][n] = __builtin_amdgcn_mfma_f32_16x16x32_bf16(Bt[n][k], At[m][k], acc[ai][bj][m][n], 0, 0, 0); __builtin_amdgcn_s_setprio(0); } while (0)
; #define PG8_BAR __builtin_amdgcn_s_barrier()
; template <class Epi>
; __device__ __forceinline__ void gemm_phase(LAS unsigned char* lds, const Gemm g, const StaticOrder& S, const Epi& E, const int tid) {
;     ...
;         const bool has_next = S.next(ui + 1, nxt);
;         const char* nA = has_next ? (const char*)g.A + (size_t)nxt.pm * tstep : cA; const char* nB = has_next ? (const char*)g.Bt + (size_t)nxt.pn * tstep : cB;
;         for (int t = 0; t < nt; t += 2) {
;             const bool last = (t == nt - 2);
;             const char* a1 = cA + (size_t)(t + 1) * kstep;
;             const char* a2 = last ? nA : cA + (size_t)(t + 2) * kstep; const char* b2 = last ? nB : cB + (size_t)(t + 2) * kstep;
;             const char* a3 = a2 + kstep; const char* b3 = b2 + kstep;
;             PG8_LDB(B0, 0, 0); PG8_SCHED; PG8_LDA(At, 0, 0); PG8_STAGE(PG8_SA(1, 1), a1 + hstep, voffA);
;             PG8_WAIT_L(8); PG8_BAR; PG8_WAIT_L(0); PG8_MMA(0, 0, At, B0); PG8_BAR; PG8_SCHED;
;     ...
; #pragma unroll
;         for (int a = 0; a < 2; ++a)
; #pragma unroll
;             for (int b = 0; b < 2; ++b)
; #pragma unroll
;                 for (int m = 0; m < 4; ++m)
; #pragma unroll
;                     for (int n = 0; n < 2; ++n) acc[a][b][m][n] = (f32x4){0.f, 0.f, 0.f, 0.f};
;         cur = nxt; cA = nA; cB = nB; ++ui;
.LBB0_61:
	s_ashr_i32 s13, s12, 31
	v_cmp_lt_i64_e32 vcc, s[14:15], v[146:147]
	s_lshl_b64 s[14:15], s[12:13], 22
	s_add_u32 s14, s0, s14
	s_addc_u32 s15, s1, s15
	s_and_b64 s[16:17], vcc, exec
	s_cselect_b32 s13, s15, s21
	s_cselect_b32 s44, s14, s20
	s_ashr_i32 s11, s10, 31
	s_lshl_b64 s[16:17], s[10:11], 22
	s_add_u32 s16, s24, s16
	s_addc_u32 s17, s25, s17
	s_and_b64 s[22:23], vcc, exec
	s_cselect_b32 s11, s17, s19
	s_cselect_b32 s45, s16, s18
	s_add_u32 s47, s18, 0x100
	s_addc_u32 s48, s19, 0
	s_add_u32 s18, s20, 0x200080
	v_mov_b32_e32 v2, 0
	s_addc_u32 s19, s21, 0
	s_mov_b32 s49, -2
	v_mov_b32_e32 v3, v2
	v_mov_b32_e32 v4, v2
	v_mov_b32_e32 v5, v2
	v_mov_b32_e32 v6, v2
	v_mov_b32_e32 v7, v2
	v_mov_b32_e32 v8, v2
	v_mov_b32_e32 v9, v2
	v_mov_b32_e32 v18, v2
	v_mov_b32_e32 v19, v2
	v_mov_b32_e32 v20, v2
	v_mov_b32_e32 v21, v2
	v_mov_b32_e32 v22, v2
	v_mov_b32_e32 v23, v2
	v_mov_b32_e32 v24, v2
	v_mov_b32_e32 v25, v2
	v_mov_b32_e32 v34, v2
	v_mov_b32_e32 v35, v2
	v_mov_b32_e32 v36, v2
	v_mov_b32_e32 v37, v2
	v_mov_b32_e32 v38, v2
	v_mov_b32_e32 v39, v2
	v_mov_b32_e32 v40, v2
	v_mov_b32_e32 v41, v2
	v_mov_b32_e32 v66, v2
	v_mov_b32_e32 v67, v2
	v_mov_b32_e32 v68, v2
	v_mov_b32_e32 v69, v2
	v_mov_b32_e32 v70, v2
	v_mov_b32_e32 v71, v2
	v_mov_b32_e32 v72, v2
	v_mov_b32_e32 v73, v2
	v_mov_b32_e32 v10, v2
	v_mov_b32_e32 v11, v2
	v_mov_b32_e32 v12, v2
	v_mov_b32_e32 v13, v2
	v_mov_b32_e32 v14, v2
	v_mov_b32_e32 v15, v2
	v_mov_b32_e32 v16, v2
	v_mov_b32_e32 v17, v2
	v_mov_b32_e32 v26, v2
	v_mov_b32_e32 v27, v2
	v_mov_b32_e32 v28, v2
	v_mov_b32_e32 v29, v2
	v_mov_b32_e32 v30, v2
	v_mov_b32_e32 v31, v2
	v_mov_b32_e32 v32, v2
	v_mov_b32_e32 v33, v2
	v_mov_b32_e32 v50, v2
	v_mov_b32_e32 v51, v2
	v_mov_b32_e32 v52, v2
	v_mov_b32_e32 v53, v2
	v_mov_b32_e32 v54, v2
	v_mov_b32_e32 v55, v2
	v_mov_b32_e32 v56, v2
	v_mov_b32_e32 v57, v2
	v_mov_b32_e32 v74, v2
	v_mov_b32_e32 v75, v2
	v_mov_b32_e32 v76, v2
	v_mov_b32_e32 v77, v2
	v_mov_b32_e32 v78, v2
	v_mov_b32_e32 v79, v2
	v_mov_b32_e32 v80, v2
	v_mov_b32_e32 v81, v2
	v_mov_b32_e32 v82, v2
	v_mov_b32_e32 v83, v2
	v_mov_b32_e32 v84, v2
	v_mov_b32_e32 v85, v2
	v_mov_b32_e32 v86, v2
	v_mov_b32_e32 v87, v2
	v_mov_b32_e32 v88, v2
	v_mov_b32_e32 v89, v2
	v_mov_b32_e32 v98, v2
	v_mov_b32_e32 v99, v2
	v_mov_b32_e32 v100, v2
	v_mov_b32_e32 v101, v2
	v_mov_b32_e32 v102, v2
	v_mov_b32_e32 v103, v2
	v_mov_b32_e32 v104, v2
	v_mov_b32_e32 v105, v2
	v_mov_b32_e32 v114, v2
	v_mov_b32_e32 v115, v2
	v_mov_b32_e32 v116, v2
	v_mov_b32_e32 v117, v2
	v_mov_b32_e32 v118, v2
	v_mov_b32_e32 v119, v2
	v_mov_b32_e32 v120, v2
	v_mov_b32_e32 v121, v2
	v_mov_b32_e32 v130, v2
	v_mov_b32_e32 v131, v2
	v_mov_b32_e32 v132, v2
	v_mov_b32_e32 v133, v2
	v_mov_b32_e32 v134, v2
	v_mov_b32_e32 v135, v2
	v_mov_b32_e32 v136, v2
	v_mov_b32_e32 v137, v2
	v_mov_b32_e32 v90, v2
	v_mov_b32_e32 v91, v2
	v_mov_b32_e32 v92, v2
	v_mov_b32_e32 v93, v2
	v_mov_b32_e32 v94, v2
	v_mov_b32_e32 v95, v2
	v_mov_b32_e32 v96, v2
	v_mov_b32_e32 v97, v2
	v_mov_b32_e32 v106, v2
	v_mov_b32_e32 v107, v2
	v_mov_b32_e32 v108, v2
	v_mov_b32_e32 v109, v2
	v_mov_b32_e32 v110, v2
	v_mov_b32_e32 v111, v2
	v_mov_b32_e32 v112, v2
	v_mov_b32_e32 v113, v2
	v_mov_b32_e32 v122, v2
	v_mov_b32_e32 v123, v2
	v_mov_b32_e32 v124, v2
	v_mov_b32_e32 v125, v2
	v_mov_b32_e32 v126, v2
	v_mov_b32_e32 v127, v2
	v_mov_b32_e32 v128, v2
	v_mov_b32_e32 v129, v2
	s_waitcnt vmcnt(0)
	v_mov_b32_e32 v138, v2
	v_mov_b32_e32 v139, v2
	v_mov_b32_e32 v140, v2
	v_mov_b32_e32 v141, v2
	v_mov_b32_e32 v142, v2
	v_mov_b32_e32 v143, v2
	v_mov_b32_e32 v144, v2
	v_mov_b32_e32 v145, v2
	v_readfirstlane_b32 s32, v158
	s_cmpk_lt_u32 s32, 0x100
	s_cbranch_scc1 .Lgprio1
	s_setprio 1
.Lgprio1:
.LBB0_62:
	s_add_u32 s20, s18, 0xffe00080
	s_addc_u32 s21, s19, -1
	s_add_i32 s50, 0, 0x10000
	v_add_u32_e32 v62, s50, v173
	ds_read_b128 v[42:45], v62
	ds_read_b128 v[46:49], v62 offset:1024
	ds_read_b128 v[58:61], v62 offset:2048
	ds_read_b128 v[62:65], v62 offset:3072
	s_cmpk_eq_i32 s49, 0x7c
	s_cselect_b32 s23, s13, s21
	s_cselect_b32 s22, s44, s20
	s_cselect_b32 s21, s11, s48
	s_cselect_b32 s20, s45, s47
	v_lshl_add_u64 v[170:171], s[18:19], 0, v[168:169]
	s_add_i32 m0, s3, 0xc000
	ds_read_b128 v[176:179], v174
	ds_read_b128 v[180:183], v174 offset:1024
	ds_read_b128 v[184:187], v174 offset:2048
	ds_read_b128 v[188:191], v174 offset:3072
	ds_read_b128 v[192:195], v174 offset:4096
	ds_read_b128 v[196:199], v174 offset:5120
	ds_read_b128 v[210:213], v174 offset:6144
	ds_read_b128 v[214:217], v174 offset:7168
	global_load_lds_dwordx4 v[170:171], off
	v_lshl_add_u64 v[170:171], s[18:19], 0, v[166:167]
	s_add_i32 m0, s3, 0xe000
	s_nop 0
	global_load_lds_dwordx4 v[170:171], off
	s_waitcnt lgkmcnt(8)
	s_barrier
	s_waitcnt lgkmcnt(0)
	v_mfma_f32_16x16x32_bf16 v[142:145], v[42:45], v[176:179], v[142:145]
	v_mfma_f32_16x16x32_bf16 v[138:141], v[58:61], v[176:179], v[138:141]
	v_mfma_f32_16x16x32_bf16 v[126:129], v[42:45], v[184:187], v[126:129]
	v_mfma_f32_16x16x32_bf16 v[122:125], v[58:61], v[184:187], v[122:125]
	v_mfma_f32_16x16x32_bf16 v[110:113], v[42:45], v[192:195], v[110:113]
	v_mfma_f32_16x16x32_bf16 v[106:109], v[58:61], v[192:195], v[106:109]
	v_mfma_f32_16x16x32_bf16 v[94:97], v[42:45], v[210:213], v[94:97]
	v_mfma_f32_16x16x32_bf16 v[90:93], v[58:61], v[210:213], v[90:93]
	v_mfma_f32_16x16x32_bf16 v[142:145], v[46:49], v[180:183], v[142:145]
	v_mfma_f32_16x16x32_bf16 v[138:141], v[62:65], v[180:183], v[138:141]
	v_mfma_f32_16x16x32_bf16 v[126:129], v[46:49], v[188:191], v[126:129]
	v_mfma_f32_16x16x32_bf16 v[122:125], v[62:65], v[188:191], v[122:125]
	v_mfma_f32_16x16x32_bf16 v[110:113], v[46:49], v[196:199], v[110:113]
	v_mfma_f32_16x16x32_bf16 v[106:109], v[62:65], v[196:199], v[106:109]
	v_mfma_f32_16x16x32_bf16 v[94:97], v[46:49], v[214:217], v[94:97]
	v_mfma_f32_16x16x32_bf16 v[90:93], v[62:65], v[214:217], v[90:93]
	s_barrier
; #define PG8_STAGE(bufoff, gbase, voff) do { _Pragma("unroll") for (int _i = 0; _i < 2; ++_i) \
;         __builtin_amdgcn_global_load_lds((const unsigned*)((const char*)(gbase) + (voff)[_i]), (LAS unsigned*)(lds + (bufoff) + ldsw + _i * 8192), 16, 0, 0); } while (0)
; #define PG8_LDA(dst, b, h) do { _Pragma("unroll") for (int m = 0; m < 4; ++m) _Pragma("unroll") for (int k = 0; k < 2; ++k) dst[m][k] = *(const LAS bf16x8*)(lds + PG8_SA(b, h) + aoff + m * 2048 + k * 1024); } while (0)
; #define PG8_LDB(dst, b, h) do { _Pragma("unroll") for (int n = 0; n < 2; ++n) _Pragma("unroll") for (int k = 0; k < 2; ++k) dst[n][k] = *(const LAS bf16x8*)(lds + PG8_SB(b, h) + boff + n * 2048 + k * 1024); } while (0)
; #define PG8_MMA(ai, bj, At, Bt) do { __builtin_amdgcn_s_setprio(1); _Pragma("unroll") for (int m = 0; m < 4; ++m) _Pragma("unroll") for (int n = 0; n < 2; ++n) _Pragma("unroll") for (int k = 0; k < 2; ++k) \
;         acc[ai][bj][m][n] = __builtin_amdgcn_mfma_f32_16x16x32_bf16(Bt[n][k], At[m][k], acc[ai][bj][m][n], 0, 0, 0); __builtin_amdgcn_s_setprio(0); } while (0)
; #define PG8_WAIT_V(n) asm volatile("s_waitcnt vmcnt(" #n ")" ::: "memory")
; #define PG8_WAIT_L(n) asm volatile("s_waitcnt lgkmcnt(" #n ")" ::: "memory")
; #define PG8_BAR __builtin_amdgcn_s_barrier()
; #define PG8_SCHED __builtin_amdgcn_sched_barrier(0)
; template <class Epi>
; __device__ __forceinline__ void gemm_phase(LAS unsigned char* lds, const Gemm g, const StaticOrder& S, const Epi& E, const int tid) {
;     ...
;             PG8_BAR; PG8_WAIT_L(0); PG8_MMA(0, 1, At, B1); PG8_BAR;
;             PG8_LDA(At, 0, 1); PG8_STAGE(PG8_SA(0, 0), a2, voffA);
;             PG8_BAR; PG8_WAIT_L(0); PG8_MMA(1, 0, At, B0); PG8_BAR; PG8_SCHED;
;             PG8_STAGE(PG8_SB(0, 1), b2 + hstep, voffB);
;             PG8_WAIT_V(6); PG8_BAR; PG8_MMA(1, 1, At, B1); PG8_BAR;
;             PG8_LDB(B0, 1, 0); PG8_SCHED; PG8_LDA(At, 1, 0); PG8_STAGE(PG8_SA(0, 1), a2 + hstep, voffA);
;             PG8_WAIT_L(8); PG8_BAR; PG8_WAIT_L(0); PG8_MMA(0, 0, At, B0); PG8_BAR; PG8_SCHED;
	s_add_i32 s54, 0, 0x14000
	v_add_u32_e32 v170, s54, v173
	s_add_i32 s50, s50, s31
	ds_read_b128 v[218:221], v170
	ds_read_b128 v[222:225], v170 offset:1024
	ds_read_b128 v[226:229], v170 offset:2048
	ds_read_b128 v[230:233], v170 offset:3072
	v_lshl_add_u64 v[170:171], s[20:21], 0, v[0:1]
	s_mov_b32 m0, s50
	v_lshl_add_u64 v[200:201], s[20:21], 0, v[164:165]
	global_load_lds_dwordx4 v[170:171], off
	s_add_i32 m0, s50, 0x2000
	s_nop 0
	global_load_lds_dwordx4 v[200:201], off
	s_barrier
	s_waitcnt lgkmcnt(0)
	v_mfma_f32_16x16x32_bf16 v[134:137], v[218:221], v[176:179], v[134:137]
	v_mfma_f32_16x16x32_bf16 v[130:133], v[226:229], v[176:179], v[130:133]
	v_mfma_f32_16x16x32_bf16 v[118:121], v[218:221], v[184:187], v[118:121]
	v_mfma_f32_16x16x32_bf16 v[114:117], v[226:229], v[184:187], v[114:117]
	v_mfma_f32_16x16x32_bf16 v[102:105], v[218:221], v[192:195], v[102:105]
	v_mfma_f32_16x16x32_bf16 v[98:101], v[226:229], v[192:195], v[98:101]
	v_mfma_f32_16x16x32_bf16 v[86:89], v[218:221], v[210:213], v[86:89]
	v_mfma_f32_16x16x32_bf16 v[82:85], v[226:229], v[210:213], v[82:85]
	v_mfma_f32_16x16x32_bf16 v[134:137], v[222:225], v[180:183], v[134:137]
	v_mfma_f32_16x16x32_bf16 v[130:133], v[230:233], v[180:183], v[130:133]
	v_mfma_f32_16x16x32_bf16 v[118:121], v[222:225], v[188:191], v[118:121]
	v_mfma_f32_16x16x32_bf16 v[114:117], v[230:233], v[188:191], v[114:117]
	v_mfma_f32_16x16x32_bf16 v[102:105], v[222:225], v[196:199], v[102:105]
	v_mfma_f32_16x16x32_bf16 v[98:101], v[230:233], v[196:199], v[98:101]
	v_mfma_f32_16x16x32_bf16 v[86:89], v[222:225], v[214:217], v[86:89]
	v_mfma_f32_16x16x32_bf16 v[82:85], v[230:233], v[214:217], v[82:85]
	s_mov_b32 m0, s3
	v_lshl_add_u64 v[234:235], s[22:23], 0, v[160:161]
	s_barrier
	ds_read_b128 v[176:179], v174 offset:16384
	ds_read_b128 v[180:183], v174 offset:17408
	ds_read_b128 v[184:187], v174 offset:18432
	ds_read_b128 v[188:191], v174 offset:19456
	ds_read_b128 v[192:195], v174 offset:20480
	ds_read_b128 v[196:199], v174 offset:21504
	ds_read_b128 v[210:213], v174 offset:22528
	ds_read_b128 v[214:217], v174 offset:23552
	global_load_lds_dwordx4 v[234:235], off
	v_lshl_add_u64 v[236:237], s[22:23], 0, v[162:163]
	s_mov_b32 m0, s34
	s_nop 0
	global_load_lds_dwordx4 v[236:237], off
	s_barrier
	s_waitcnt lgkmcnt(0)
	v_mfma_f32_16x16x32_bf16 v[78:81], v[42:45], v[176:179], v[78:81]
	v_mfma_f32_16x16x32_bf16 v[74:77], v[58:61], v[176:179], v[74:77]
	v_mfma_f32_16x16x32_bf16 v[54:57], v[42:45], v[184:187], v[54:57]
	v_mfma_f32_16x16x32_bf16 v[50:53], v[58:61], v[184:187], v[50:53]
	v_mfma_f32_16x16x32_bf16 v[30:33], v[42:45], v[192:195], v[30:33]
	v_mfma_f32_16x16x32_bf16 v[26:29], v[58:61], v[192:195], v[26:29]
	v_mfma_f32_16x16x32_bf16 v[14:17], v[42:45], v[210:213], v[14:17]
	v_mfma_f32_16x16x32_bf16 v[10:13], v[58:61], v[210:213], v[10:13]
	v_mfma_f32_16x16x32_bf16 v[78:81], v[46:49], v[180:183], v[78:81]
	v_mfma_f32_16x16x32_bf16 v[74:77], v[62:65], v[180:183], v[74:77]
	v_mfma_f32_16x16x32_bf16 v[54:57], v[46:49], v[188:191], v[54:57]
	v_mfma_f32_16x16x32_bf16 v[50:53], v[62:65], v[188:191], v[50:53]
	v_mfma_f32_16x16x32_bf16 v[30:33], v[46:49], v[196:199], v[30:33]
	v_mfma_f32_16x16x32_bf16 v[26:29], v[62:65], v[196:199], v[26:29]
	v_mfma_f32_16x16x32_bf16 v[14:17], v[46:49], v[214:217], v[14:17]
	v_mfma_f32_16x16x32_bf16 v[10:13], v[62:65], v[214:217], v[10:13]
	s_barrier
	s_add_u32 s52, s20, 0x200000
	s_addc_u32 s53, s21, 0
	s_add_i32 s50, s54, s31
	v_lshl_add_u64 v[42:43], s[52:53], 0, v[0:1]
	s_mov_b32 m0, s50
	s_nop 0
	global_load_lds_dwordx4 v[42:43], off
	v_lshl_add_u64 v[42:43], s[52:53], 0, v[164:165]
	s_add_i32 m0, s50, 0x2000
	s_nop 0
	global_load_lds_dwordx4 v[42:43], off
	s_waitcnt vmcnt(6)
	s_barrier
	v_mfma_f32_16x16x32_bf16 v[38:41], v[218:221], v[184:187], v[38:41]
	v_mfma_f32_16x16x32_bf16 v[34:37], v[226:229], v[184:187], v[34:37]
	v_mfma_f32_16x16x32_bf16 v[22:25], v[218:221], v[192:195], v[22:25]
	v_mfma_f32_16x16x32_bf16 v[18:21], v[226:229], v[192:195], v[18:21]
	v_mfma_f32_16x16x32_bf16 v[6:9], v[218:221], v[210:213], v[6:9]
	v_mfma_f32_16x16x32_bf16 v[2:5], v[226:229], v[210:213], v[2:5]
	v_mfma_f32_16x16x32_bf16 v[42:45], v[218:221], v[176:179], v[70:73]
	v_mfma_f32_16x16x32_bf16 v[46:49], v[226:229], v[176:179], v[66:69]
	v_mfma_f32_16x16x32_bf16 v[38:41], v[222:225], v[188:191], v[38:41]
	v_mfma_f32_16x16x32_bf16 v[34:37], v[230:233], v[188:191], v[34:37]
	v_mfma_f32_16x16x32_bf16 v[22:25], v[222:225], v[196:199], v[22:25]
	v_mfma_f32_16x16x32_bf16 v[18:21], v[230:233], v[196:199], v[18:21]
	v_mfma_f32_16x16x32_bf16 v[6:9], v[222:225], v[214:217], v[6:9]
	v_mfma_f32_16x16x32_bf16 v[2:5], v[230:233], v[214:217], v[2:5]
	v_mfma_f32_16x16x32_bf16 v[42:45], v[222:225], v[180:183], v[42:45]
	v_mfma_f32_16x16x32_bf16 v[46:49], v[230:233], v[180:183], v[46:49]
	s_add_i32 s50, 0, 0x18000
	v_add_u32_e32 v70, s50, v173
	s_barrier
	ds_read_b128 v[58:61], v70
	ds_read_b128 v[62:65], v70 offset:1024
	ds_read_b128 v[66:69], v70 offset:2048
	ds_read_b128 v[70:73], v70 offset:3072
	s_add_u32 s22, s22, 0x200000
	s_addc_u32 s23, s23, 0
	s_mov_b32 m0, s35
	v_lshl_add_u64 v[218:219], s[22:23], 0, v[160:161]
	ds_read_b128 v[176:179], v174 offset:32768
	ds_read_b128 v[180:183], v174 offset:33792
	ds_read_b128 v[184:187], v174 offset:34816
	ds_read_b128 v[188:191], v174 offset:35840
	ds_read_b128 v[192:195], v174 offset:36864
	ds_read_b128 v[196:199], v174 offset:37888
	ds_read_b128 v[210:213], v174 offset:38912
	ds_read_b128 v[214:217], v174 offset:39936
	global_load_lds_dwordx4 v[218:219], off
	v_lshl_add_u64 v[218:219], s[22:23], 0, v[162:163]
	s_mov_b32 m0, s36
	s_nop 0
	global_load_lds_dwordx4 v[218:219], off
	s_waitcnt lgkmcnt(8)
	s_barrier
; #define PG8_STAGE(bufoff, gbase, voff) do { _Pragma("unroll") for (int _i = 0; _i < 2; ++_i) \
;         __builtin_amdgcn_global_load_lds((const unsigned*)((const char*)(gbase) + (voff)[_i]), (LAS unsigned*)(lds + (bufoff) + ldsw + _i * 8192), 16, 0, 0); } while (0)
; #define PG8_LDA(dst, b, h) do { _Pragma("unroll") for (int m = 0; m < 4; ++m) _Pragma("unroll") for (int k = 0; k < 2; ++k) dst[m][k] = *(const LAS bf16x8*)(lds + PG8_SA(b, h) + aoff + m * 2048 + k * 1024); } while (0)
; #define PG8_LDB(dst, b, h) do { _Pragma("unroll") for (int n = 0; n < 2; ++n) _Pragma("unroll") for (int k = 0; k < 2; ++k) dst[n][k] = *(const LAS bf16x8*)(lds + PG8_SB(b, h) + boff + n * 2048 + k * 1024); } while (0)
; #define PG8_MMA(ai, bj, At, Bt) do { __builtin_amdgcn_s_setprio(1); _Pragma("unroll") for (int m = 0; m < 4; ++m) _Pragma("unroll") for (int n = 0; n < 2; ++n) _Pragma("unroll") for (int k = 0; k < 2; ++k) \
;         acc[ai][bj][m][n] = __builtin_amdgcn_mfma_f32_16x16x32_bf16(Bt[n][k], At[m][k], acc[ai][bj][m][n], 0, 0, 0); __builtin_amdgcn_s_setprio(0); } while (0)
; #define PG8_WAIT_V(n) asm volatile("s_waitcnt vmcnt(" #n ")" ::: "memory")
; #define PG8_WAIT_L(n) asm volatile("s_waitcnt lgkmcnt(" #n ")" ::: "memory")
; #define PG8_BAR __builtin_amdgcn_s_barrier()
; #define PG8_SCHED __builtin_amdgcn_sched_barrier(0)
; template <class Epi>
; __device__ __forceinline__ void gemm_phase(LAS unsigned char* lds, const Gemm g, const StaticOrder& S, const Epi& E, const int tid) {
;     ...
;             PG8_WAIT_L(8); PG8_BAR; PG8_WAIT_L(0); PG8_MMA(0, 0, At, B0); PG8_BAR; PG8_SCHED;
;             PG8_LDB(B1, 1, 1); PG8_STAGE(PG8_SB(1, 0), b3, voffB);
;             PG8_BAR; PG8_WAIT_L(0); PG8_MMA(0, 1, At, B1); PG8_BAR;
;             PG8_LDA(At, 1, 1); PG8_STAGE(PG8_SA(1, 0), a3, voffA);
;             PG8_BAR; PG8_WAIT_L(0); PG8_MMA(1, 0, At, B0); PG8_BAR; PG8_SCHED;
;             PG8_STAGE(PG8_SB(1, 1), b3 + hstep, voffB);
;             PG8_WAIT_V(6); PG8_BAR; PG8_MMA(1, 1, At, B1); PG8_BAR;
	s_waitcnt lgkmcnt(0)
	v_mfma_f32_16x16x32_bf16 v[142:145], v[58:61], v[176:179], v[142:145]
	v_mfma_f32_16x16x32_bf16 v[138:141], v[66:69], v[176:179], v[138:141]
	v_mfma_f32_16x16x32_bf16 v[126:129], v[58:61], v[184:187], v[126:129]
	v_mfma_f32_16x16x32_bf16 v[122:125], v[66:69], v[184:187], v[122:125]
	v_mfma_f32_16x16x32_bf16 v[110:113], v[58:61], v[192:195], v[110:113]
	v_mfma_f32_16x16x32_bf16 v[106:109], v[66:69], v[192:195], v[106:109]
	v_mfma_f32_16x16x32_bf16 v[94:97], v[58:61], v[210:213], v[94:97]
	v_mfma_f32_16x16x32_bf16 v[90:93], v[66:69], v[210:213], v[90:93]
	v_mfma_f32_16x16x32_bf16 v[142:145], v[62:65], v[180:183], v[142:145]
	v_mfma_f32_16x16x32_bf16 v[138:141], v[70:73], v[180:183], v[138:141]
	v_mfma_f32_16x16x32_bf16 v[126:129], v[62:65], v[188:191], v[126:129]
	v_mfma_f32_16x16x32_bf16 v[122:125], v[70:73], v[188:191], v[122:125]
	v_mfma_f32_16x16x32_bf16 v[110:113], v[62:65], v[196:199], v[110:113]
	v_mfma_f32_16x16x32_bf16 v[106:109], v[70:73], v[196:199], v[106:109]
	v_mfma_f32_16x16x32_bf16 v[94:97], v[62:65], v[214:217], v[94:97]
	v_mfma_f32_16x16x32_bf16 v[90:93], v[70:73], v[214:217], v[90:93]
	s_barrier
	s_add_i32 s22, 0, 0x1c000
	s_add_i32 s23, s50, s31
	v_add_u32_e32 v175, s22, v173
	v_lshl_add_u64 v[170:171], v[170:171], 0, s[56:57]
	s_mov_b32 m0, s23
	ds_read_b128 v[218:221], v175
	ds_read_b128 v[222:225], v175 offset:1024
	ds_read_b128 v[226:229], v175 offset:2048
	ds_read_b128 v[230:233], v175 offset:3072
	global_load_lds_dwordx4 v[170:171], off
	v_lshl_add_u64 v[170:171], v[200:201], 0, s[56:57]
	s_add_i32 m0, s23, 0x2000
	s_nop 0
	global_load_lds_dwordx4 v[170:171], off
	s_barrier
	s_waitcnt lgkmcnt(0)
	v_mfma_f32_16x16x32_bf16 v[134:137], v[218:221], v[176:179], v[134:137]
	v_mfma_f32_16x16x32_bf16 v[130:133], v[226:229], v[176:179], v[130:133]
	v_mfma_f32_16x16x32_bf16 v[118:121], v[218:221], v[184:187], v[118:121]
	v_mfma_f32_16x16x32_bf16 v[114:117], v[226:229], v[184:187], v[114:117]
	v_mfma_f32_16x16x32_bf16 v[102:105], v[218:221], v[192:195], v[102:105]
	v_mfma_f32_16x16x32_bf16 v[98:101], v[226:229], v[192:195], v[98:101]
	v_mfma_f32_16x16x32_bf16 v[86:89], v[218:221], v[210:213], v[86:89]
	v_mfma_f32_16x16x32_bf16 v[82:85], v[226:229], v[210:213], v[82:85]
	v_mfma_f32_16x16x32_bf16 v[134:137], v[222:225], v[180:183], v[134:137]
	v_mfma_f32_16x16x32_bf16 v[130:133], v[230:233], v[180:183], v[130:133]
	v_mfma_f32_16x16x32_bf16 v[118:121], v[222:225], v[188:191], v[118:121]
	v_mfma_f32_16x16x32_bf16 v[114:117], v[230:233], v[188:191], v[114:117]
	v_mfma_f32_16x16x32_bf16 v[102:105], v[222:225], v[196:199], v[102:105]
	v_mfma_f32_16x16x32_bf16 v[98:101], v[230:233], v[196:199], v[98:101]
	v_mfma_f32_16x16x32_bf16 v[86:89], v[222:225], v[214:217], v[86:89]
	v_mfma_f32_16x16x32_bf16 v[82:85], v[230:233], v[214:217], v[82:85]
	s_mov_b32 m0, s39
	v_lshl_add_u64 v[170:171], v[234:235], 0, s[56:57]
	s_barrier
	ds_read_b128 v[176:179], v174 offset:49152
	ds_read_b128 v[180:183], v174 offset:50176
	ds_read_b128 v[184:187], v174 offset:51200
	ds_read_b128 v[188:191], v174 offset:52224
	ds_read_b128 v[192:195], v174 offset:53248
	ds_read_b128 v[196:199], v174 offset:54272
	ds_read_b128 v[210:213], v174 offset:55296
	ds_read_b128 v[214:217], v174 offset:56320
	global_load_lds_dwordx4 v[170:171], off
	v_lshl_add_u64 v[170:171], v[236:237], 0, s[56:57]
	s_mov_b32 m0, s40
	s_nop 0
	global_load_lds_dwordx4 v[170:171], off
	s_barrier
	s_waitcnt lgkmcnt(0)
	v_mfma_f32_16x16x32_bf16 v[78:81], v[58:61], v[176:179], v[78:81]
	v_mfma_f32_16x16x32_bf16 v[74:77], v[66:69], v[176:179], v[74:77]
	v_mfma_f32_16x16x32_bf16 v[54:57], v[58:61], v[184:187], v[54:57]
	v_mfma_f32_16x16x32_bf16 v[50:53], v[66:69], v[184:187], v[50:53]
	v_mfma_f32_16x16x32_bf16 v[30:33], v[58:61], v[192:195], v[30:33]
	v_mfma_f32_16x16x32_bf16 v[26:29], v[66:69], v[192:195], v[26:29]
	v_mfma_f32_16x16x32_bf16 v[14:17], v[58:61], v[210:213], v[14:17]
	v_mfma_f32_16x16x32_bf16 v[10:13], v[66:69], v[210:213], v[10:13]
	v_mfma_f32_16x16x32_bf16 v[78:81], v[62:65], v[180:183], v[78:81]
	v_mfma_f32_16x16x32_bf16 v[74:77], v[70:73], v[180:183], v[74:77]
	v_mfma_f32_16x16x32_bf16 v[54:57], v[62:65], v[188:191], v[54:57]
	v_mfma_f32_16x16x32_bf16 v[50:53], v[70:73], v[188:191], v[50:53]
	v_mfma_f32_16x16x32_bf16 v[30:33], v[62:65], v[196:199], v[30:33]
	v_mfma_f32_16x16x32_bf16 v[26:29], v[70:73], v[196:199], v[26:29]
	v_mfma_f32_16x16x32_bf16 v[14:17], v[62:65], v[214:217], v[14:17]
	v_mfma_f32_16x16x32_bf16 v[10:13], v[70:73], v[214:217], v[10:13]
	s_barrier
	s_add_u32 s20, s20, 0x200080
	s_addc_u32 s21, s21, 0
	s_add_i32 s22, s22, s31
	v_lshl_add_u64 v[58:59], s[20:21], 0, v[0:1]
	s_mov_b32 m0, s22
	s_nop 0
	global_load_lds_dwordx4 v[58:59], off
	v_lshl_add_u64 v[58:59], s[20:21], 0, v[164:165]
	s_add_i32 m0, s22, 0x2000
	s_nop 0
	global_load_lds_dwordx4 v[58:59], off
	s_waitcnt vmcnt(6)
	s_barrier
	v_mfma_f32_16x16x32_bf16 v[42:45], v[218:221], v[176:179], v[42:45]
	v_mfma_f32_16x16x32_bf16 v[70:73], v[222:225], v[180:183], v[42:45]
	v_mfma_f32_16x16x32_bf16 v[42:45], v[226:229], v[176:179], v[46:49]
	v_mfma_f32_16x16x32_bf16 v[38:41], v[218:221], v[184:187], v[38:41]
	v_mfma_f32_16x16x32_bf16 v[34:37], v[226:229], v[184:187], v[34:37]
	v_mfma_f32_16x16x32_bf16 v[22:25], v[218:221], v[192:195], v[22:25]
	v_mfma_f32_16x16x32_bf16 v[18:21], v[226:229], v[192:195], v[18:21]
	v_mfma_f32_16x16x32_bf16 v[6:9], v[218:221], v[210:213], v[6:9]
	v_mfma_f32_16x16x32_bf16 v[2:5], v[226:229], v[210:213], v[2:5]
	v_mfma_f32_16x16x32_bf16 v[66:69], v[230:233], v[180:183], v[42:45]
	v_mfma_f32_16x16x32_bf16 v[38:41], v[222:225], v[188:191], v[38:41]
	v_mfma_f32_16x16x32_bf16 v[34:37], v[230:233], v[188:191], v[34:37]
	v_mfma_f32_16x16x32_bf16 v[22:25], v[222:225], v[196:199], v[22:25]
	v_mfma_f32_16x16x32_bf16 v[18:21], v[230:233], v[196:199], v[18:21]
	v_mfma_f32_16x16x32_bf16 v[6:9], v[222:225], v[214:217], v[6:9]
	v_mfma_f32_16x16x32_bf16 v[2:5], v[230:233], v[214:217], v[2:5]
	s_add_i32 s49, s49, 2
	s_add_u32 s47, s47, 0x100
	s_addc_u32 s48, s48, 0
	s_add_u32 s18, s18, 0x100
	s_addc_u32 s19, s19, 0
	s_cmpk_gt_u32 s49, 0x7d
	s_barrier
; __device__ __forceinline__ unsigned pk2(float lo, float hi) { f32x2 v = {lo, hi}; return __builtin_bit_cast(unsigned, __builtin_convertvector(v, bf16x2_t)); }
; __device__ __forceinline__ float bf_lo(unsigned w) { return __uint_as_float(w << 16); }
; __device__ __forceinline__ float bf_hi(unsigned w) { return __uint_as_float(w & 0xffff0000u); }
;     __device__ __forceinline__ void operator()(const f32x4 (&acc)[2][2][4][2], const Unit& u, int wr, int wc, int fr, int fq) const {
;         asm volatile("" : "+v"(fr), "+v"(fq));
;         const int row0 = u.pm * BM + wr * 64 + fr, col0 = u.pn * BM + wc * 32 + 8 * fq;
;         const float* gp = gate + (size_t)(u.pm >> 5) * 12288 + col0;
;         f32x4 gv[2][2];
; #pragma unroll
;         for (int bj = 0; bj < 2; ++bj)
; #pragma unroll
;             for (int n = 0; n < 2; ++n) gv[bj][n] = *(const f32x4*)(gp + bj * HALF + 4 * n);
; #pragma unroll
;         for (int ai = 0; ai < 2; ++ai)
; #pragma unroll
;             for (int m = 0; m < 4; ++m) {
;                 const size_t ro = (size_t)(row0 + ai * HALF + m * 16) * DM + col0;
; #pragma unroll
;                 for (int bj = 0; bj < 2; ++bj) {
;                     f32x4 r0, r1;
;                     if (RB) { const u32x4 rw = *(const u32x4*)((const bf16_t*)resid + ro + bj * HALF);
;                         r0 = (f32x4){bf_lo(rw.x), bf_hi(rw.x), bf_lo(rw.y), bf_hi(rw.y)}; r1 = (f32x4){bf_lo(rw.z), bf_hi(rw.z), bf_lo(rw.w), bf_hi(rw.w)}; }
;                     else { r0 = *(const f32x4*)((const float*)resid + ro + bj * HALF); r1 = *(const f32x4*)((const float*)resid + ro + bj * HALF + 4); }
;                     const f32x4 v0 = r0 + gv[bj][0] * acc[ai][bj][m][0], v1 = r1 + gv[bj][1] * acc[ai][bj][m][1];
;                     if (OB) { u32x4 w; w.x = pk2(v0[0], v0[1]); w.y = pk2(v0[2], v0[3]); w.z = pk2(v1[0], v1[1]); w.w = pk2(v1[2], v1[3]); *(u32x4*)((bf16_t*)out + ro + bj * HALF) = w; }
;                     else { *(f32x4*)((float*)out + ro + bj * HALF) = v0; *(f32x4*)((float*)out + ro + bj * HALF + 4) = v1; }
	s_cbranch_scc0 .LBB0_62
	s_setprio 0
	s_lshl_b32 s11, s2, 8
	s_lshl_b32 s13, s43, 8
	v_mov_b32_e32 v175, v172
	v_mov_b32_e32 v42, v159
	s_add_i32 s11, s11, s37
	s_or_b32 s13, s13, s38
	s_ashr_i32 s2, s2, 5
	s_mov_b32 s43, s10
	v_lshl_add_u32 v170, v42, 3, s13
	s_mul_hi_i32 s13, s2, 0xc000
	s_mul_i32 s2, s2, 0xc000
	v_add_u32_e32 v176, s11, v175
	s_add_u32 s18, s27, s2
	v_ashrrev_i32_e32 v177, 31, v176
	s_addc_u32 s19, s28, s13
	v_ashrrev_i32_e32 v171, 31, v170
	v_lshlrev_b64 v[176:177], 11, v[176:177]
	v_lshl_add_u64 v[46:47], v[170:171], 2, s[18:19]
	v_lshl_add_u64 v[170:171], v[176:177], 0, v[170:171]
	v_lshlrev_b64 v[170:171], 1, v[170:171]
	v_lshl_add_u64 v[180:181], s[8:9], 0, v[170:171]
	global_load_dwordx4 v[58:61], v[46:47], off offset:16
	global_load_dwordx4 v[62:65], v[46:47], off
	global_load_dwordx4 v[42:45], v[46:47], off offset:528
	s_nop 0
	global_load_dwordx4 v[46:49], v[46:47], off offset:512
	s_mov_b64 s[92:93], s[8:9]
	s_mov_b64 s[94:95], s[6:7]
	global_load_dwordx4 v[184:187], v170, s[92:93]
	global_load_dwordx4 v[188:191], v170, s[92:93] offset:256
	s_add_u32 s92, s92, 0x10000
	s_addc_u32 s93, s93, 0
	global_load_dwordx4 v[192:195], v170, s[92:93]
	global_load_dwordx4 v[196:199], v170, s[92:93] offset:256
	s_add_u32 s92, s92, 0x10000
	s_addc_u32 s93, s93, 0
	global_load_dwordx4 v[210:213], v170, s[92:93]
	global_load_dwordx4 v[214:217], v170, s[92:93] offset:256
	s_add_u32 s92, s92, 0x10000
	s_addc_u32 s93, s93, 0
	global_load_dwordx4 v[218:221], v170, s[92:93]
	global_load_dwordx4 v[222:225], v170, s[92:93] offset:256
	s_add_u32 s92, s92, 0x50000
	s_addc_u32 s93, s93, 0
	global_load_dwordx4 v[226:229], v170, s[92:93]
	global_load_dwordx4 v[230:233], v170, s[92:93] offset:256
	s_add_u32 s92, s92, 0x10000
	s_addc_u32 s93, s93, 0
	global_load_dwordx4 v[234:237], v170, s[92:93]
	s_waitcnt vmcnt(10)
	v_lshlrev_b32_e32 v176, 16, v184
	v_and_b32_e32 v177, 0xffff0000, v184
	v_lshlrev_b32_e32 v178, 16, v185
	v_and_b32_e32 v179, 0xffff0000, v185
	v_lshlrev_b32_e32 v180, 16, v186
	v_and_b32_e32 v181, 0xffff0000, v186
	v_lshlrev_b32_e32 v182, 16, v187
	v_and_b32_e32 v183, 0xffff0000, v187
	v_pk_fma_f32 v[142:143], v[142:143], v[62:63], v[176:177]
	v_pk_fma_f32 v[144:145], v[144:145], v[64:65], v[178:179]
	v_pk_fma_f32 v[138:139], v[138:139], v[58:59], v[180:181]
	v_pk_fma_f32 v[140:141], v[140:141], v[60:61], v[182:183]
	global_load_dwordx4 v[184:187], v170, s[92:93] offset:256
	v_cvt_pk_bf16_f32 v142, v142, v143
	v_cvt_pk_bf16_f32 v143, v144, v145
	v_cvt_pk_bf16_f32 v144, v138, v139
	v_cvt_pk_bf16_f32 v145, v140, v141
	global_store_dwordx4 v170, v[142:145], s[94:95]
	s_waitcnt vmcnt(11)
	v_lshlrev_b32_e32 v176, 16, v188
	v_and_b32_e32 v177, 0xffff0000, v188
	v_lshlrev_b32_e32 v178, 16, v189
	v_and_b32_e32 v179, 0xffff0000, v189
	v_lshlrev_b32_e32 v180, 16, v190
	v_and_b32_e32 v181, 0xffff0000, v190
	v_lshlrev_b32_e32 v182, 16, v191
	v_and_b32_e32 v183, 0xffff0000, v191
	v_pk_fma_f32 v[134:135], v[134:135], v[46:47], v[176:177]
	v_pk_fma_f32 v[136:137], v[136:137], v[48:49], v[178:179]
	v_pk_fma_f32 v[130:131], v[130:131], v[42:43], v[180:181]
	v_pk_fma_f32 v[132:133], v[132:133], v[44:45], v[182:183]
	s_add_u32 s92, s92, 0x10000
	s_addc_u32 s93, s93, 0
	global_load_dwordx4 v[188:191], v170, s[92:93]
	v_cvt_pk_bf16_f32 v134, v134, v135
	v_cvt_pk_bf16_f32 v135, v136, v137
	v_cvt_pk_bf16_f32 v136, v130, v131
	v_cvt_pk_bf16_f32 v137, v132, v133
	global_store_dwordx4 v170, v[134:137], s[94:95] offset:256
	s_waitcnt vmcnt(12)
	v_lshlrev_b32_e32 v176, 16, v192
	v_and_b32_e32 v177, 0xffff0000, v192
	v_lshlrev_b32_e32 v178, 16, v193
	v_and_b32_e32 v179, 0xffff0000, v193
	v_lshlrev_b32_e32 v180, 16, v194
	v_and_b32_e32 v181, 0xffff0000, v194
	v_lshlrev_b32_e32 v182, 16, v195
	v_and_b32_e32 v183, 0xffff0000, v195
	v_pk_fma_f32 v[126:127], v[126:127], v[62:63], v[176:177]
	v_pk_fma_f32 v[128:129], v[128:129], v[64:65], v[178:179]
	v_pk_fma_f32 v[122:123], v[122:123], v[58:59], v[180:181]
	v_pk_fma_f32 v[124:125], v[124:125], v[60:61], v[182:183]
	global_load_dwordx4 v[192:195], v170, s[92:93] offset:256
	s_add_u32 s94, s94, 0x10000
	s_addc_u32 s95, s95, 0
	v_cvt_pk_bf16_f32 v126, v126, v127
	v_cvt_pk_bf16_f32 v127, v128, v129
	v_cvt_pk_bf16_f32 v128, v122, v123
	v_cvt_pk_bf16_f32 v129, v124, v125
	global_store_dwordx4 v170, v[126:129], s[94:95]
	s_waitcnt vmcnt(13)
	v_lshlrev_b32_e32 v176, 16, v196
	v_and_b32_e32 v177, 0xffff0000, v196
	v_lshlrev_b32_e32 v178, 16, v197
	v_and_b32_e32 v179, 0xffff0000, v197
	v_lshlrev_b32_e32 v180, 16, v198
	v_and_b32_e32 v181, 0xffff0000, v198
	v_lshlrev_b32_e32 v182, 16, v199
	v_and_b32_e32 v183, 0xffff0000, v199
	v_pk_fma_f32 v[118:119], v[118:119], v[46:47], v[176:177]
	v_pk_fma_f32 v[120:121], v[120:121], v[48:49], v[178:179]
	v_pk_fma_f32 v[114:115], v[114:115], v[42:43], v[180:181]
	v_pk_fma_f32 v[116:117], v[116:117], v[44:45], v[182:183]
	s_add_u32 s92, s92, 0x10000
	s_addc_u32 s93, s93, 0
	global_load_dwordx4 v[196:199], v170, s[92:93]
	v_cvt_pk_bf16_f32 v118, v118, v119
	v_cvt_pk_bf16_f32 v119, v120, v121
	v_cvt_pk_bf16_f32 v120, v114, v115
	v_cvt_pk_bf16_f32 v121, v116, v117
	global_store_dwordx4 v170, v[118:121], s[94:95] offset:256
	s_waitcnt vmcnt(14)
	v_lshlrev_b32_e32 v176, 16, v210
	v_and_b32_e32 v177, 0xffff0000, v210
	v_lshlrev_b32_e32 v178, 16, v211
	v_and_b32_e32 v179, 0xffff0000, v211
	v_lshlrev_b32_e32 v180, 16, v212
	v_and_b32_e32 v181, 0xffff0000, v212
	v_lshlrev_b32_e32 v182, 16, v213
	v_and_b32_e32 v183, 0xffff0000, v213
	v_pk_fma_f32 v[110:111], v[110:111], v[62:63], v[176:177]
	v_pk_fma_f32 v[112:113], v[112:113], v[64:65], v[178:179]
	v_pk_fma_f32 v[106:107], v[106:107], v[58:59], v[180:181]
	v_pk_fma_f32 v[108:109], v[108:109], v[60:61], v[182:183]
	global_load_dwordx4 v[210:213], v170, s[92:93] offset:256
	s_add_u32 s94, s94, 0x10000
	s_addc_u32 s95, s95, 0
	v_cvt_pk_bf16_f32 v110, v110, v111
	v_cvt_pk_bf16_f32 v111, v112, v113
	v_cvt_pk_bf16_f32 v112, v106, v107
	v_cvt_pk_bf16_f32 v113, v108, v109
	global_store_dwordx4 v170, v[110:113], s[94:95]
	s_waitcnt vmcnt(15)
; __device__ __forceinline__ unsigned pk2(float lo, float hi) { f32x2 v = {lo, hi}; return __builtin_bit_cast(unsigned, __builtin_convertvector(v, bf16x2_t)); }
; __device__ __forceinline__ float bf_lo(unsigned w) { return __uint_as_float(w << 16); }
; __device__ __forceinline__ float bf_hi(unsigned w) { return __uint_as_float(w & 0xffff0000u); }
;     __device__ __forceinline__ void operator()(const f32x4 (&acc)[2][2][4][2], const Unit& u, int wr, int wc, int fr, int fq) const {
;     ...
;             for (int m = 0; m < 4; ++m) {
;                 const size_t ro = (size_t)(row0 + ai * HALF + m * 16) * DM + col0;
; #pragma unroll
;                 for (int bj = 0; bj < 2; ++bj) {
;                     f32x4 r0, r1;
;                     if (RB) { const u32x4 rw = *(const u32x4*)((const bf16_t*)resid + ro + bj * HALF);
;                         r0 = (f32x4){bf_lo(rw.x), bf_hi(rw.x), bf_lo(rw.y), bf_hi(rw.y)}; r1 = (f32x4){bf_lo(rw.z), bf_hi(rw.z), bf_lo(rw.w), bf_hi(rw.w)}; }
;                     else { r0 = *(const f32x4*)((const float*)resid + ro + bj * HALF); r1 = *(const f32x4*)((const float*)resid + ro + bj * HALF + 4); }
;                     const f32x4 v0 = r0 + gv[bj][0] * acc[ai][bj][m][0], v1 = r1 + gv[bj][1] * acc[ai][bj][m][1];
;                     if (OB) { u32x4 w; w.x = pk2(v0[0], v0[1]); w.y = pk2(v0[2], v0[3]); w.z = pk2(v1[0], v1[1]); w.w = pk2(v1[2], v1[3]); *(u32x4*)((bf16_t*)out + ro + bj * HALF) = w; }
;                     else { *(f32x4*)((float*)out + ro + bj * HALF) = v0; *(f32x4*)((float*)out + ro + bj * HALF + 4) = v1; }
;                 }
	v_lshlrev_b32_e32 v176, 16, v214
	v_and_b32_e32 v177, 0xffff0000, v214
	v_lshlrev_b32_e32 v178, 16, v215
	v_and_b32_e32 v179, 0xffff0000, v215
	v_lshlrev_b32_e32 v180, 16, v216
	v_and_b32_e32 v181, 0xffff0000, v216
	v_lshlrev_b32_e32 v182, 16, v217
	v_and_b32_e32 v183, 0xffff0000, v217
	v_pk_fma_f32 v[102:103], v[102:103], v[46:47], v[176:177]
	v_pk_fma_f32 v[104:105], v[104:105], v[48:49], v[178:179]
	v_pk_fma_f32 v[98:99], v[98:99], v[42:43], v[180:181]
	v_pk_fma_f32 v[100:101], v[100:101], v[44:45], v[182:183]
	v_cvt_pk_bf16_f32 v102, v102, v103
	v_cvt_pk_bf16_f32 v103, v104, v105
	v_cvt_pk_bf16_f32 v104, v98, v99
	v_cvt_pk_bf16_f32 v105, v100, v101
	global_store_dwordx4 v170, v[102:105], s[94:95] offset:256
	s_waitcnt vmcnt(15)
	v_lshlrev_b32_e32 v176, 16, v218
	v_and_b32_e32 v177, 0xffff0000, v218
	v_lshlrev_b32_e32 v178, 16, v219
	v_and_b32_e32 v179, 0xffff0000, v219
	v_lshlrev_b32_e32 v180, 16, v220
	v_and_b32_e32 v181, 0xffff0000, v220
	v_lshlrev_b32_e32 v182, 16, v221
	v_and_b32_e32 v183, 0xffff0000, v221
	v_pk_fma_f32 v[94:95], v[94:95], v[62:63], v[176:177]
	v_pk_fma_f32 v[96:97], v[96:97], v[64:65], v[178:179]
	v_pk_fma_f32 v[90:91], v[90:91], v[58:59], v[180:181]
	v_pk_fma_f32 v[92:93], v[92:93], v[60:61], v[182:183]
	s_add_u32 s94, s94, 0x10000
	s_addc_u32 s95, s95, 0
	v_cvt_pk_bf16_f32 v94, v94, v95
	v_cvt_pk_bf16_f32 v95, v96, v97
	v_cvt_pk_bf16_f32 v96, v90, v91
	v_cvt_pk_bf16_f32 v97, v92, v93
	global_store_dwordx4 v170, v[94:97], s[94:95]
	s_waitcnt vmcnt(15)
	v_lshlrev_b32_e32 v176, 16, v222
	v_and_b32_e32 v177, 0xffff0000, v222
	v_lshlrev_b32_e32 v178, 16, v223
	v_and_b32_e32 v179, 0xffff0000, v223
	v_lshlrev_b32_e32 v180, 16, v224
	v_and_b32_e32 v181, 0xffff0000, v224
	v_lshlrev_b32_e32 v182, 16, v225
	v_and_b32_e32 v183, 0xffff0000, v225
	v_pk_fma_f32 v[86:87], v[86:87], v[46:47], v[176:177]
	v_pk_fma_f32 v[88:89], v[88:89], v[48:49], v[178:179]
	v_pk_fma_f32 v[82:83], v[82:83], v[42:43], v[180:181]
	v_pk_fma_f32 v[84:85], v[84:85], v[44:45], v[182:183]
	v_cvt_pk_bf16_f32 v86, v86, v87
	v_cvt_pk_bf16_f32 v87, v88, v89
	v_cvt_pk_bf16_f32 v88, v82, v83
	v_cvt_pk_bf16_f32 v89, v84, v85
	global_store_dwordx4 v170, v[86:89], s[94:95] offset:256
	s_waitcnt vmcnt(15)
	v_lshlrev_b32_e32 v176, 16, v226
	v_and_b32_e32 v177, 0xffff0000, v226
	v_lshlrev_b32_e32 v178, 16, v227
	v_and_b32_e32 v179, 0xffff0000, v227
	v_lshlrev_b32_e32 v180, 16, v228
	v_and_b32_e32 v181, 0xffff0000, v228
	v_lshlrev_b32_e32 v182, 16, v229
	v_and_b32_e32 v183, 0xffff0000, v229
	v_pk_fma_f32 v[78:79], v[78:79], v[62:63], v[176:177]
	v_pk_fma_f32 v[80:81], v[80:81], v[64:65], v[178:179]
	v_pk_fma_f32 v[74:75], v[74:75], v[58:59], v[180:181]
	v_pk_fma_f32 v[76:77], v[76:77], v[60:61], v[182:183]
	s_add_u32 s94, s94, 0x50000
	s_addc_u32 s95, s95, 0
	v_cvt_pk_bf16_f32 v78, v78, v79
	v_cvt_pk_bf16_f32 v79, v80, v81
	v_cvt_pk_bf16_f32 v80, v74, v75
	v_cvt_pk_bf16_f32 v81, v76, v77
	global_store_dwordx4 v170, v[78:81], s[94:95]
	s_waitcnt vmcnt(15)
	v_lshlrev_b32_e32 v176, 16, v230
	v_and_b32_e32 v177, 0xffff0000, v230
	v_lshlrev_b32_e32 v178, 16, v231
	v_and_b32_e32 v179, 0xffff0000, v231
	v_lshlrev_b32_e32 v180, 16, v232
	v_and_b32_e32 v181, 0xffff0000, v232
	v_lshlrev_b32_e32 v182, 16, v233
	v_and_b32_e32 v183, 0xffff0000, v233
	v_pk_fma_f32 v[70:71], v[70:71], v[46:47], v[176:177]
	v_pk_fma_f32 v[72:73], v[72:73], v[48:49], v[178:179]
	v_pk_fma_f32 v[66:67], v[66:67], v[42:43], v[180:181]
	v_pk_fma_f32 v[68:69], v[68:69], v[44:45], v[182:183]
	v_cvt_pk_bf16_f32 v70, v70, v71
	v_cvt_pk_bf16_f32 v71, v72, v73
	v_cvt_pk_bf16_f32 v72, v66, v67
	v_cvt_pk_bf16_f32 v73, v68, v69
	global_store_dwordx4 v170, v[70:73], s[94:95] offset:256
	s_waitcnt vmcnt(15)
	v_lshlrev_b32_e32 v176, 16, v234
	v_and_b32_e32 v177, 0xffff0000, v234
	v_lshlrev_b32_e32 v178, 16, v235
	v_and_b32_e32 v179, 0xffff0000, v235
	v_lshlrev_b32_e32 v180, 16, v236
	v_and_b32_e32 v181, 0xffff0000, v236
	v_lshlrev_b32_e32 v182, 16, v237
	v_and_b32_e32 v183, 0xffff0000, v237
	v_pk_fma_f32 v[54:55], v[54:55], v[62:63], v[176:177]
	v_pk_fma_f32 v[56:57], v[56:57], v[64:65], v[178:179]
	v_pk_fma_f32 v[50:51], v[50:51], v[58:59], v[180:181]
	v_pk_fma_f32 v[52:53], v[52:53], v[60:61], v[182:183]
	s_add_u32 s94, s94, 0x10000
	s_addc_u32 s95, s95, 0
	v_cvt_pk_bf16_f32 v54, v54, v55
	v_cvt_pk_bf16_f32 v55, v56, v57
	v_cvt_pk_bf16_f32 v56, v50, v51
	v_cvt_pk_bf16_f32 v57, v52, v53
	global_store_dwordx4 v170, v[54:57], s[94:95]
	s_waitcnt vmcnt(15)
; __device__ __forceinline__ unsigned pk2(float lo, float hi) { f32x2 v = {lo, hi}; return __builtin_bit_cast(unsigned, __builtin_convertvector(v, bf16x2_t)); }
; __device__ __forceinline__ float bf_lo(unsigned w) { return __uint_as_float(w << 16); }
; __device__ __forceinline__ float bf_hi(unsigned w) { return __uint_as_float(w & 0xffff0000u); }
; #define PG8_WAIT_V(n) asm volatile("s_waitcnt vmcnt(" #n ")" ::: "memory")
; #define PG8_BAR __builtin_amdgcn_s_barrier()
;     __device__ __forceinline__ void operator()(const f32x4 (&acc)[2][2][4][2], const Unit& u, int wr, int wc, int fr, int fq) const {
;     ...
;                     if (RB) { const u32x4 rw = *(const u32x4*)((const bf16_t*)resid + ro + bj * HALF);
;                         r0 = (f32x4){bf_lo(rw.x), bf_hi(rw.x), bf_lo(rw.y), bf_hi(rw.y)}; r1 = (f32x4){bf_lo(rw.z), bf_hi(rw.z), bf_lo(rw.w), bf_hi(rw.w)}; }
;                     else { r0 = *(const f32x4*)((const float*)resid + ro + bj * HALF); r1 = *(const f32x4*)((const float*)resid + ro + bj * HALF + 4); }
;                     const f32x4 v0 = r0 + gv[bj][0] * acc[ai][bj][m][0], v1 = r1 + gv[bj][1] * acc[ai][bj][m][1];
;                     if (OB) { u32x4 w; w.x = pk2(v0[0], v0[1]); w.y = pk2(v0[2], v0[3]); w.z = pk2(v1[0], v1[1]); w.w = pk2(v1[2], v1[3]); *(u32x4*)((bf16_t*)out + ro + bj * HALF) = w; }
;                     else { *(f32x4*)((float*)out + ro + bj * HALF) = v0; *(f32x4*)((float*)out + ro + bj * HALF + 4) = v1; }
;                 }
; template <class Epi>
; __device__ __forceinline__ void gemm_phase(LAS unsigned char* lds, const Gemm g, const StaticOrder& S, const Epi& E, const int tid) {
;     ...
;         E(acc, cur, wr, wc, fr, fq);
;         if (!has_next) break;
; #pragma unroll
;         for (int a = 0; a < 2; ++a)
; #pragma unroll
;             for (int b = 0; b < 2; ++b)
; #pragma unroll
;                 for (int m = 0; m < 4; ++m)
; #pragma unroll
;                     for (int n = 0; n < 2; ++n) acc[a][b][m][n] = (f32x4){0.f, 0.f, 0.f, 0.f};
;         cur = nxt; cA = nA; cB = nB; ++ui;
;     }
;     PG8_WAIT_V(0);
;     if (wr == 0) PG8_BAR;
	v_lshlrev_b32_e32 v176, 16, v184
	v_and_b32_e32 v177, 0xffff0000, v184
	v_lshlrev_b32_e32 v178, 16, v185
	v_and_b32_e32 v179, 0xffff0000, v185
	v_lshlrev_b32_e32 v180, 16, v186
	v_and_b32_e32 v181, 0xffff0000, v186
	v_lshlrev_b32_e32 v182, 16, v187
	v_and_b32_e32 v183, 0xffff0000, v187
	v_pk_fma_f32 v[38:39], v[38:39], v[46:47], v[176:177]
	v_pk_fma_f32 v[40:41], v[40:41], v[48:49], v[178:179]
	v_pk_fma_f32 v[34:35], v[34:35], v[42:43], v[180:181]
	v_pk_fma_f32 v[36:37], v[36:37], v[44:45], v[182:183]
	v_cvt_pk_bf16_f32 v38, v38, v39
	v_cvt_pk_bf16_f32 v39, v40, v41
	v_cvt_pk_bf16_f32 v40, v34, v35
	v_cvt_pk_bf16_f32 v41, v36, v37
	global_store_dwordx4 v170, v[38:41], s[94:95] offset:256
	s_waitcnt vmcnt(14)
	v_lshlrev_b32_e32 v176, 16, v188
	v_and_b32_e32 v177, 0xffff0000, v188
	v_lshlrev_b32_e32 v178, 16, v189
	v_and_b32_e32 v179, 0xffff0000, v189
	v_lshlrev_b32_e32 v180, 16, v190
	v_and_b32_e32 v181, 0xffff0000, v190
	v_lshlrev_b32_e32 v182, 16, v191
	v_and_b32_e32 v183, 0xffff0000, v191
	v_pk_fma_f32 v[30:31], v[30:31], v[62:63], v[176:177]
	v_pk_fma_f32 v[32:33], v[32:33], v[64:65], v[178:179]
	v_pk_fma_f32 v[26:27], v[26:27], v[58:59], v[180:181]
	v_pk_fma_f32 v[28:29], v[28:29], v[60:61], v[182:183]
	s_add_u32 s94, s94, 0x10000
	s_addc_u32 s95, s95, 0
	v_cvt_pk_bf16_f32 v30, v30, v31
	v_cvt_pk_bf16_f32 v31, v32, v33
	v_cvt_pk_bf16_f32 v32, v26, v27
	v_cvt_pk_bf16_f32 v33, v28, v29
	global_store_dwordx4 v170, v[30:33], s[94:95]
	s_waitcnt vmcnt(13)
	v_lshlrev_b32_e32 v176, 16, v192
	v_and_b32_e32 v177, 0xffff0000, v192
	v_lshlrev_b32_e32 v178, 16, v193
	v_and_b32_e32 v179, 0xffff0000, v193
	v_lshlrev_b32_e32 v180, 16, v194
	v_and_b32_e32 v181, 0xffff0000, v194
	v_lshlrev_b32_e32 v182, 16, v195
	v_and_b32_e32 v183, 0xffff0000, v195
	v_pk_fma_f32 v[22:23], v[22:23], v[46:47], v[176:177]
	v_pk_fma_f32 v[24:25], v[24:25], v[48:49], v[178:179]
	v_pk_fma_f32 v[18:19], v[18:19], v[42:43], v[180:181]
	v_pk_fma_f32 v[20:21], v[20:21], v[44:45], v[182:183]
	v_cvt_pk_bf16_f32 v22, v22, v23
	v_cvt_pk_bf16_f32 v23, v24, v25
	v_cvt_pk_bf16_f32 v24, v18, v19
	v_cvt_pk_bf16_f32 v25, v20, v21
	global_store_dwordx4 v170, v[22:25], s[94:95] offset:256
	s_waitcnt vmcnt(12)
	v_lshlrev_b32_e32 v176, 16, v196
	v_and_b32_e32 v177, 0xffff0000, v196
	v_lshlrev_b32_e32 v178, 16, v197
	v_and_b32_e32 v179, 0xffff0000, v197
	v_lshlrev_b32_e32 v180, 16, v198
	v_and_b32_e32 v181, 0xffff0000, v198
	v_lshlrev_b32_e32 v182, 16, v199
	v_and_b32_e32 v183, 0xffff0000, v199
	v_pk_fma_f32 v[14:15], v[14:15], v[62:63], v[176:177]
	v_pk_fma_f32 v[16:17], v[16:17], v[64:65], v[178:179]
	v_pk_fma_f32 v[10:11], v[10:11], v[58:59], v[180:181]
	v_pk_fma_f32 v[12:13], v[12:13], v[60:61], v[182:183]
	s_add_u32 s94, s94, 0x10000
	s_addc_u32 s95, s95, 0
	v_cvt_pk_bf16_f32 v14, v14, v15
	v_cvt_pk_bf16_f32 v15, v16, v17
	v_cvt_pk_bf16_f32 v16, v10, v11
	v_cvt_pk_bf16_f32 v17, v12, v13
	global_store_dwordx4 v170, v[14:17], s[94:95]
	s_waitcnt vmcnt(11)
	v_lshlrev_b32_e32 v176, 16, v210
	v_and_b32_e32 v177, 0xffff0000, v210
	v_lshlrev_b32_e32 v178, 16, v211
	v_and_b32_e32 v179, 0xffff0000, v211
	v_lshlrev_b32_e32 v180, 16, v212
	v_and_b32_e32 v181, 0xffff0000, v212
	v_lshlrev_b32_e32 v182, 16, v213
	v_and_b32_e32 v183, 0xffff0000, v213
	v_pk_fma_f32 v[6:7], v[6:7], v[46:47], v[176:177]
	v_pk_fma_f32 v[8:9], v[8:9], v[48:49], v[178:179]
	v_pk_fma_f32 v[2:3], v[2:3], v[42:43], v[180:181]
	v_pk_fma_f32 v[4:5], v[4:5], v[44:45], v[182:183]
	v_cvt_pk_bf16_f32 v6, v6, v7
	v_cvt_pk_bf16_f32 v7, v8, v9
	v_cvt_pk_bf16_f32 v8, v2, v3
	v_cvt_pk_bf16_f32 v9, v4, v5
	global_store_dwordx4 v170, v[6:9], s[94:95] offset:256
	s_mov_b32 s2, s12
	s_mov_b64 s[20:21], s[14:15]
	s_mov_b64 s[18:19], s[16:17]
	s_and_b64 vcc, exec, s[4:5]
	s_nop 1
	s_cbranch_vccz .LBB0_55
	s_waitcnt vmcnt(0)
	s_cmpk_gt_u32 s29, 0xff
	s_cbranch_scc1 .LBB0_66
	s_barrier

; #define PG8_STAGE(bufoff, gbase, voff) do { _Pragma("unroll") for (int _i = 0; _i < 2; ++_i) \
;         __builtin_amdgcn_global_load_lds((const unsigned*)((const char*)(gbase) + (voff)[_i]), (LAS unsigned*)(lds + (bufoff) + ldsw + _i * 8192), 16, 0, 0); } while (0)
; #define PG8_LDA(dst, b, h) do { _Pragma("unroll") for (int m = 0; m < 4; ++m) _Pragma("unroll") for (int k = 0; k < 2; ++k) dst[m][k] = *(const LAS bf16x8*)(lds + PG8_SA(b, h) + aoff + m * 2048 + k * 1024); } while (0)
; #define PG8_LDB(dst, b, h) do { _Pragma("unroll") for (int n = 0; n < 2; ++n) _Pragma("unroll") for (int k = 0; k < 2; ++k) dst[n][k] = *(const LAS bf16x8*)(lds + PG8_SB(b, h) + boff + n * 2048 + k * 1024); } while (0)
; #define PG8_MMA(ai, bj, At, Bt) do { __builtin_amdgcn_s_setprio(1); _Pragma("unroll") for (int m = 0; m < 4; ++m) _Pragma("unroll") for (int n = 0; n < 2; ++n) _Pragma("unroll") for (int k = 0; k < 2; ++k) \
;         acc[ai][bj][m][n] = __builtin_amdgcn_mfma_f32_16x16x32_bf16(Bt[n][k], At[m][k], acc[ai][bj][m][n], 0, 0, 0); __builtin_amdgcn_s_setprio(0); } while (0)
; #define PG8_BAR __builtin_amdgcn_s_barrier()
; template <class Epi>
; __device__ __forceinline__ void gemm_phase(LAS unsigned char* lds, const Gemm g, const StaticOrder& S, const Epi& E, const int tid) {
;     ...
;         const bool has_next = S.next(ui + 1, nxt);
;         const char* nA = has_next ? (const char*)g.A + (size_t)nxt.pm * tstep : cA; const char* nB = has_next ? (const char*)g.Bt + (size_t)nxt.pn * tstep : cB;
;         for (int t = 0; t < nt; t += 2) {
;             const bool last = (t == nt - 2);
;             const char* a1 = cA + (size_t)(t + 1) * kstep;
;             const char* a2 = last ? nA : cA + (size_t)(t + 2) * kstep; const char* b2 = last ? nB : cB + (size_t)(t + 2) * kstep;
;             const char* a3 = a2 + kstep; const char* b3 = b2 + kstep;
;             PG8_LDB(B0, 0, 0); PG8_SCHED; PG8_LDA(At, 0, 0); PG8_STAGE(PG8_SA(1, 1), a1 + hstep, voffA);
;             PG8_WAIT_L(8); PG8_BAR; PG8_WAIT_L(0); PG8_MMA(0, 0, At, B0); PG8_BAR; PG8_SCHED;
;     ...
; #pragma unroll
;         for (int a = 0; a < 2; ++a)
; #pragma unroll
;             for (int b = 0; b < 2; ++b)
; #pragma unroll
;                 for (int m = 0; m < 4; ++m)
; #pragma unroll
;                     for (int n = 0; n < 2; ++n) acc[a][b][m][n] = (f32x4){0.f, 0.f, 0.f, 0.f};
;         cur = nxt; cA = nA; cB = nB; ++ui;
.LBB0_83:
	s_ashr_i32 s9, s8, 31
	v_cmp_lt_i64_e32 vcc, s[10:11], v[152:153]
	s_lshl_b64 s[10:11], s[8:9], 20
	s_add_u32 s10, s22, s10
	s_addc_u32 s11, s23, s11
	s_and_b64 s[12:13], vcc, exec
	s_cselect_b32 s9, s11, s19
	s_cselect_b32 s40, s10, s18
	s_ashr_i32 s7, s6, 31
	s_lshl_b64 s[12:13], s[6:7], 20
	s_add_u32 s12, s24, s12
	s_addc_u32 s13, s25, s13
	s_and_b64 s[20:21], vcc, exec
	s_cselect_b32 s7, s13, s17
	s_cselect_b32 s41, s12, s16
	s_add_u32 s42, s16, 0x100
	s_addc_u32 s43, s17, 0
	s_add_u32 s16, s18, 0x80080
	v_mov_b32_e32 v2, 0
	s_addc_u32 s17, s19, 0
	s_mov_b32 s44, -2
	v_mov_b32_e32 v3, v2
	v_mov_b32_e32 v4, v2
	v_mov_b32_e32 v5, v2
	v_mov_b32_e32 v6, v2
	v_mov_b32_e32 v7, v2
	v_mov_b32_e32 v8, v2
	v_mov_b32_e32 v9, v2
	v_mov_b32_e32 v18, v2
	v_mov_b32_e32 v19, v2
	v_mov_b32_e32 v20, v2
	v_mov_b32_e32 v21, v2
	v_mov_b32_e32 v22, v2
	v_mov_b32_e32 v23, v2
	v_mov_b32_e32 v24, v2
	v_mov_b32_e32 v25, v2
	v_mov_b32_e32 v34, v2
	v_mov_b32_e32 v35, v2
	v_mov_b32_e32 v36, v2
	v_mov_b32_e32 v37, v2
	v_mov_b32_e32 v38, v2
	v_mov_b32_e32 v39, v2
	v_mov_b32_e32 v40, v2
	v_mov_b32_e32 v41, v2
	v_mov_b32_e32 v50, v2
	v_mov_b32_e32 v51, v2
	v_mov_b32_e32 v52, v2
	v_mov_b32_e32 v53, v2
	v_mov_b32_e32 v54, v2
	v_mov_b32_e32 v55, v2
	v_mov_b32_e32 v56, v2
	v_mov_b32_e32 v57, v2
	v_mov_b32_e32 v10, v2
	v_mov_b32_e32 v11, v2
	v_mov_b32_e32 v12, v2
	v_mov_b32_e32 v13, v2
	v_mov_b32_e32 v14, v2
	v_mov_b32_e32 v15, v2
	v_mov_b32_e32 v16, v2
	v_mov_b32_e32 v17, v2
	v_mov_b32_e32 v26, v2
	v_mov_b32_e32 v27, v2
	v_mov_b32_e32 v28, v2
	v_mov_b32_e32 v29, v2
	v_mov_b32_e32 v30, v2
	v_mov_b32_e32 v31, v2
	v_mov_b32_e32 v32, v2
	v_mov_b32_e32 v33, v2
	v_mov_b32_e32 v42, v2
	v_mov_b32_e32 v43, v2
	v_mov_b32_e32 v44, v2
	v_mov_b32_e32 v45, v2
	v_mov_b32_e32 v46, v2
	v_mov_b32_e32 v47, v2
	v_mov_b32_e32 v48, v2
	v_mov_b32_e32 v49, v2
	v_mov_b32_e32 v58, v2
	v_mov_b32_e32 v59, v2
	v_mov_b32_e32 v60, v2
	v_mov_b32_e32 v61, v2
	v_mov_b32_e32 v62, v2
	v_mov_b32_e32 v63, v2
	v_mov_b32_e32 v64, v2
	v_mov_b32_e32 v65, v2
	v_mov_b32_e32 v66, v2
	v_mov_b32_e32 v67, v2
	v_mov_b32_e32 v68, v2
	v_mov_b32_e32 v69, v2
	v_mov_b32_e32 v70, v2
	v_mov_b32_e32 v71, v2
	v_mov_b32_e32 v72, v2
	v_mov_b32_e32 v73, v2
	v_mov_b32_e32 v82, v2
	v_mov_b32_e32 v83, v2
	v_mov_b32_e32 v84, v2
	v_mov_b32_e32 v85, v2
	v_mov_b32_e32 v86, v2
	v_mov_b32_e32 v87, v2
	v_mov_b32_e32 v88, v2
	v_mov_b32_e32 v89, v2
	v_mov_b32_e32 v98, v2
	v_mov_b32_e32 v99, v2
	v_mov_b32_e32 v100, v2
	v_mov_b32_e32 v101, v2
	v_mov_b32_e32 v102, v2
	v_mov_b32_e32 v103, v2
	v_mov_b32_e32 v104, v2
	v_mov_b32_e32 v105, v2
	v_mov_b32_e32 v114, v2
	v_mov_b32_e32 v115, v2
	v_mov_b32_e32 v116, v2
	v_mov_b32_e32 v117, v2
	v_mov_b32_e32 v118, v2
	v_mov_b32_e32 v119, v2
	v_mov_b32_e32 v120, v2
	v_mov_b32_e32 v121, v2
	v_mov_b32_e32 v74, v2
	v_mov_b32_e32 v75, v2
	v_mov_b32_e32 v76, v2
	v_mov_b32_e32 v77, v2
	v_mov_b32_e32 v78, v2
	v_mov_b32_e32 v79, v2
	v_mov_b32_e32 v80, v2
	v_mov_b32_e32 v81, v2
	v_mov_b32_e32 v90, v2
	v_mov_b32_e32 v91, v2
	v_mov_b32_e32 v92, v2
	v_mov_b32_e32 v93, v2
	v_mov_b32_e32 v94, v2
	v_mov_b32_e32 v95, v2
	v_mov_b32_e32 v96, v2
	v_mov_b32_e32 v97, v2
	v_mov_b32_e32 v106, v2
	v_mov_b32_e32 v107, v2
	v_mov_b32_e32 v108, v2
	v_mov_b32_e32 v109, v2
	v_mov_b32_e32 v110, v2
	v_mov_b32_e32 v111, v2
	v_mov_b32_e32 v112, v2
	v_mov_b32_e32 v113, v2
	v_mov_b32_e32 v122, v2
	v_mov_b32_e32 v123, v2
	v_mov_b32_e32 v124, v2
	v_mov_b32_e32 v125, v2
	v_mov_b32_e32 v126, v2
	v_mov_b32_e32 v127, v2
	v_mov_b32_e32 v128, v2
	v_mov_b32_e32 v129, v2
	v_readfirstlane_b32 s32, v158
	s_cmpk_lt_u32 s32, 0x100
	s_cbranch_scc1 .Lgprio2
	s_setprio 1
.Lgprio2:
.LBB0_84:
	s_add_u32 s18, s16, 0xfff80080
	s_addc_u32 s19, s17, -1
	s_add_i32 s45, 0, 0x10000
	v_add_u32_e32 v140, s45, v144
	ds_read_b128 v[160:163], v140
	ds_read_b128 v[164:167], v140 offset:1024
	ds_read_b128 v[168:171], v140 offset:2048
	ds_read_b128 v[172:175], v140 offset:3072
	s_cmp_eq_u32 s44, 28
	s_cselect_b32 s21, s9, s19
	s_cselect_b32 s20, s40, s18
	s_cselect_b32 s19, s7, s43
	s_cselect_b32 s18, s41, s42
	v_lshl_add_u64 v[140:141], s[16:17], 0, v[138:139]
	s_add_i32 m0, s15, 0xc000
	ds_read_b128 v[176:179], v145
	ds_read_b128 v[180:183], v145 offset:1024
	ds_read_b128 v[184:187], v145 offset:2048
	ds_read_b128 v[188:191], v145 offset:3072
	ds_read_b128 v[192:195], v145 offset:4096
	ds_read_b128 v[196:199], v145 offset:5120
	ds_read_b128 v[210:213], v145 offset:6144
	ds_read_b128 v[214:217], v145 offset:7168
	global_load_lds_dwordx4 v[140:141], off
	v_lshl_add_u64 v[140:141], s[16:17], 0, v[136:137]
	s_add_i32 m0, s15, 0xe000
	s_nop 0
	global_load_lds_dwordx4 v[140:141], off
	s_waitcnt lgkmcnt(8)
	s_barrier
	s_waitcnt lgkmcnt(0)
	v_mfma_f32_16x16x32_bf16 v[126:129], v[160:163], v[176:179], v[126:129]
	v_mfma_f32_16x16x32_bf16 v[122:125], v[168:171], v[176:179], v[122:125]
	v_mfma_f32_16x16x32_bf16 v[110:113], v[160:163], v[184:187], v[110:113]
	v_mfma_f32_16x16x32_bf16 v[106:109], v[168:171], v[184:187], v[106:109]
	v_mfma_f32_16x16x32_bf16 v[94:97], v[160:163], v[192:195], v[94:97]
	v_mfma_f32_16x16x32_bf16 v[90:93], v[168:171], v[192:195], v[90:93]
	v_mfma_f32_16x16x32_bf16 v[78:81], v[160:163], v[210:213], v[78:81]
	v_mfma_f32_16x16x32_bf16 v[74:77], v[168:171], v[210:213], v[74:77]
	v_mfma_f32_16x16x32_bf16 v[126:129], v[164:167], v[180:183], v[126:129]
	v_mfma_f32_16x16x32_bf16 v[122:125], v[172:175], v[180:183], v[122:125]
	v_mfma_f32_16x16x32_bf16 v[110:113], v[164:167], v[188:191], v[110:113]
	v_mfma_f32_16x16x32_bf16 v[106:109], v[172:175], v[188:191], v[106:109]
	v_mfma_f32_16x16x32_bf16 v[94:97], v[164:167], v[196:199], v[94:97]
	v_mfma_f32_16x16x32_bf16 v[90:93], v[172:175], v[196:199], v[90:93]
	v_mfma_f32_16x16x32_bf16 v[78:81], v[164:167], v[214:217], v[78:81]
	v_mfma_f32_16x16x32_bf16 v[74:77], v[172:175], v[214:217], v[74:77]
	s_barrier
; #define PG8_STAGE(bufoff, gbase, voff) do { _Pragma("unroll") for (int _i = 0; _i < 2; ++_i) \
;         __builtin_amdgcn_global_load_lds((const unsigned*)((const char*)(gbase) + (voff)[_i]), (LAS unsigned*)(lds + (bufoff) + ldsw + _i * 8192), 16, 0, 0); } while (0)
; #define PG8_LDA(dst, b, h) do { _Pragma("unroll") for (int m = 0; m < 4; ++m) _Pragma("unroll") for (int k = 0; k < 2; ++k) dst[m][k] = *(const LAS bf16x8*)(lds + PG8_SA(b, h) + aoff + m * 2048 + k * 1024); } while (0)
; #define PG8_LDB(dst, b, h) do { _Pragma("unroll") for (int n = 0; n < 2; ++n) _Pragma("unroll") for (int k = 0; k < 2; ++k) dst[n][k] = *(const LAS bf16x8*)(lds + PG8_SB(b, h) + boff + n * 2048 + k * 1024); } while (0)
; #define PG8_MMA(ai, bj, At, Bt) do { __builtin_amdgcn_s_setprio(1); _Pragma("unroll") for (int m = 0; m < 4; ++m) _Pragma("unroll") for (int n = 0; n < 2; ++n) _Pragma("unroll") for (int k = 0; k < 2; ++k) \
;         acc[ai][bj][m][n] = __builtin_amdgcn_mfma_f32_16x16x32_bf16(Bt[n][k], At[m][k], acc[ai][bj][m][n], 0, 0, 0); __builtin_amdgcn_s_setprio(0); } while (0)
; #define PG8_WAIT_V(n) asm volatile("s_waitcnt vmcnt(" #n ")" ::: "memory")
; #define PG8_WAIT_L(n) asm volatile("s_waitcnt lgkmcnt(" #n ")" ::: "memory")
; #define PG8_BAR __builtin_amdgcn_s_barrier()
; #define PG8_SCHED __builtin_amdgcn_sched_barrier(0)
; template <class Epi>
; __device__ __forceinline__ void gemm_phase(LAS unsigned char* lds, const Gemm g, const StaticOrder& S, const Epi& E, const int tid) {
;     ...
;             PG8_LDB(B1, 0, 1); PG8_STAGE(PG8_SB(0, 0), b2, voffB);
;             PG8_BAR; PG8_WAIT_L(0); PG8_MMA(0, 1, At, B1); PG8_BAR;
;             PG8_LDA(At, 0, 1); PG8_STAGE(PG8_SA(0, 0), a2, voffA);
;             PG8_BAR; PG8_WAIT_L(0); PG8_MMA(1, 0, At, B0); PG8_BAR; PG8_SCHED;
;             PG8_STAGE(PG8_SB(0, 1), b2 + hstep, voffB);
;             PG8_WAIT_V(6); PG8_BAR; PG8_MMA(1, 1, At, B1); PG8_BAR;
;             PG8_LDB(B0, 1, 0); PG8_SCHED; PG8_LDA(At, 1, 0); PG8_STAGE(PG8_SA(0, 1), a2 + hstep, voffA);
;             PG8_WAIT_L(8); PG8_BAR; PG8_WAIT_L(0); PG8_MMA(0, 0, At, B0); PG8_BAR; PG8_SCHED;
	s_add_i32 s47, 0, 0x14000
	v_add_u32_e32 v140, s47, v144
	s_add_i32 s45, s45, s26
	ds_read_b128 v[218:221], v140
	ds_read_b128 v[222:225], v140 offset:1024
	ds_read_b128 v[226:229], v140 offset:2048
	ds_read_b128 v[230:233], v140 offset:3072
	v_lshl_add_u64 v[140:141], s[18:19], 0, v[0:1]
	s_mov_b32 m0, s45
	v_lshl_add_u64 v[200:201], s[18:19], 0, v[134:135]
	global_load_lds_dwordx4 v[140:141], off
	s_add_i32 m0, s45, 0x2000
	s_nop 0
	global_load_lds_dwordx4 v[200:201], off
	s_barrier
	s_waitcnt lgkmcnt(0)
	v_mfma_f32_16x16x32_bf16 v[118:121], v[218:221], v[176:179], v[118:121]
	v_mfma_f32_16x16x32_bf16 v[114:117], v[226:229], v[176:179], v[114:117]
	v_mfma_f32_16x16x32_bf16 v[102:105], v[218:221], v[184:187], v[102:105]
	v_mfma_f32_16x16x32_bf16 v[98:101], v[226:229], v[184:187], v[98:101]
	v_mfma_f32_16x16x32_bf16 v[86:89], v[218:221], v[192:195], v[86:89]
	v_mfma_f32_16x16x32_bf16 v[82:85], v[226:229], v[192:195], v[82:85]
	v_mfma_f32_16x16x32_bf16 v[70:73], v[218:221], v[210:213], v[70:73]
	v_mfma_f32_16x16x32_bf16 v[66:69], v[226:229], v[210:213], v[66:69]
	v_mfma_f32_16x16x32_bf16 v[118:121], v[222:225], v[180:183], v[118:121]
	v_mfma_f32_16x16x32_bf16 v[114:117], v[230:233], v[180:183], v[114:117]
	v_mfma_f32_16x16x32_bf16 v[102:105], v[222:225], v[188:191], v[102:105]
	v_mfma_f32_16x16x32_bf16 v[98:101], v[230:233], v[188:191], v[98:101]
	v_mfma_f32_16x16x32_bf16 v[86:89], v[222:225], v[196:199], v[86:89]
	v_mfma_f32_16x16x32_bf16 v[82:85], v[230:233], v[196:199], v[82:85]
	v_mfma_f32_16x16x32_bf16 v[70:73], v[222:225], v[214:217], v[70:73]
	v_mfma_f32_16x16x32_bf16 v[66:69], v[230:233], v[214:217], v[66:69]
	s_mov_b32 m0, s15
	v_lshl_add_u64 v[234:235], s[20:21], 0, v[130:131]
	s_barrier
	ds_read_b128 v[176:179], v145 offset:16384
	ds_read_b128 v[180:183], v145 offset:17408
	ds_read_b128 v[184:187], v145 offset:18432
	ds_read_b128 v[188:191], v145 offset:19456
	ds_read_b128 v[192:195], v145 offset:20480
	ds_read_b128 v[196:199], v145 offset:21504
	ds_read_b128 v[210:213], v145 offset:22528
	ds_read_b128 v[214:217], v145 offset:23552
	global_load_lds_dwordx4 v[234:235], off
	v_lshl_add_u64 v[236:237], s[20:21], 0, v[132:133]
	s_mov_b32 m0, s27
	s_nop 0
	global_load_lds_dwordx4 v[236:237], off
	s_barrier
	s_waitcnt lgkmcnt(0)
	v_mfma_f32_16x16x32_bf16 v[62:65], v[160:163], v[176:179], v[62:65]
	v_mfma_f32_16x16x32_bf16 v[58:61], v[168:171], v[176:179], v[58:61]
	v_mfma_f32_16x16x32_bf16 v[46:49], v[160:163], v[184:187], v[46:49]
	v_mfma_f32_16x16x32_bf16 v[42:45], v[168:171], v[184:187], v[42:45]
	v_mfma_f32_16x16x32_bf16 v[30:33], v[160:163], v[192:195], v[30:33]
	v_mfma_f32_16x16x32_bf16 v[26:29], v[168:171], v[192:195], v[26:29]
	v_mfma_f32_16x16x32_bf16 v[14:17], v[160:163], v[210:213], v[14:17]
	v_mfma_f32_16x16x32_bf16 v[10:13], v[168:171], v[210:213], v[10:13]
	v_mfma_f32_16x16x32_bf16 v[62:65], v[164:167], v[180:183], v[62:65]
	v_mfma_f32_16x16x32_bf16 v[58:61], v[172:175], v[180:183], v[58:61]
	v_mfma_f32_16x16x32_bf16 v[46:49], v[164:167], v[188:191], v[46:49]
	v_mfma_f32_16x16x32_bf16 v[42:45], v[172:175], v[188:191], v[42:45]
	v_mfma_f32_16x16x32_bf16 v[30:33], v[164:167], v[196:199], v[30:33]
	v_mfma_f32_16x16x32_bf16 v[26:29], v[172:175], v[196:199], v[26:29]
	v_mfma_f32_16x16x32_bf16 v[14:17], v[164:167], v[214:217], v[14:17]
	v_mfma_f32_16x16x32_bf16 v[10:13], v[172:175], v[214:217], v[10:13]
	s_barrier
	s_add_u32 s48, s18, 0x80000
	s_addc_u32 s49, s19, 0
	s_add_i32 s45, s47, s26
	v_lshl_add_u64 v[160:161], s[48:49], 0, v[0:1]
	s_mov_b32 m0, s45
	s_nop 0
	global_load_lds_dwordx4 v[160:161], off
	v_lshl_add_u64 v[160:161], s[48:49], 0, v[134:135]
	s_add_i32 m0, s45, 0x2000
	s_nop 0
	global_load_lds_dwordx4 v[160:161], off
	s_waitcnt vmcnt(6)
	s_barrier
	v_mfma_f32_16x16x32_bf16 v[54:57], v[218:221], v[176:179], v[54:57]
	v_mfma_f32_16x16x32_bf16 v[50:53], v[226:229], v[176:179], v[50:53]
	v_mfma_f32_16x16x32_bf16 v[38:41], v[218:221], v[184:187], v[38:41]
	v_mfma_f32_16x16x32_bf16 v[34:37], v[226:229], v[184:187], v[34:37]
	v_mfma_f32_16x16x32_bf16 v[22:25], v[218:221], v[192:195], v[22:25]
	v_mfma_f32_16x16x32_bf16 v[18:21], v[226:229], v[192:195], v[18:21]
	v_mfma_f32_16x16x32_bf16 v[6:9], v[218:221], v[210:213], v[6:9]
	v_mfma_f32_16x16x32_bf16 v[2:5], v[226:229], v[210:213], v[2:5]
	v_mfma_f32_16x16x32_bf16 v[54:57], v[222:225], v[180:183], v[54:57]
	v_mfma_f32_16x16x32_bf16 v[50:53], v[230:233], v[180:183], v[50:53]
	v_mfma_f32_16x16x32_bf16 v[38:41], v[222:225], v[188:191], v[38:41]
	v_mfma_f32_16x16x32_bf16 v[34:37], v[230:233], v[188:191], v[34:37]
	v_mfma_f32_16x16x32_bf16 v[22:25], v[222:225], v[196:199], v[22:25]
	v_mfma_f32_16x16x32_bf16 v[18:21], v[230:233], v[196:199], v[18:21]
	v_mfma_f32_16x16x32_bf16 v[6:9], v[222:225], v[214:217], v[6:9]
	v_mfma_f32_16x16x32_bf16 v[2:5], v[230:233], v[214:217], v[2:5]
	s_add_i32 s45, 0, 0x18000
	v_add_u32_e32 v159, s45, v144
	s_barrier
	ds_read_b128 v[160:163], v159
	ds_read_b128 v[164:167], v159 offset:1024
	ds_read_b128 v[168:171], v159 offset:2048
	ds_read_b128 v[172:175], v159 offset:3072
	s_add_u32 s20, s20, 0x80000
	s_addc_u32 s21, s21, 0
	s_mov_b32 m0, s28
	v_lshl_add_u64 v[218:219], s[20:21], 0, v[130:131]
	ds_read_b128 v[176:179], v145 offset:32768
	ds_read_b128 v[180:183], v145 offset:33792
	ds_read_b128 v[184:187], v145 offset:34816
	ds_read_b128 v[188:191], v145 offset:35840
	ds_read_b128 v[192:195], v145 offset:36864
	ds_read_b128 v[196:199], v145 offset:37888
	ds_read_b128 v[210:213], v145 offset:38912
	ds_read_b128 v[214:217], v145 offset:39936
	global_load_lds_dwordx4 v[218:219], off
	v_lshl_add_u64 v[218:219], s[20:21], 0, v[132:133]
	s_mov_b32 m0, s29
	s_nop 0
	global_load_lds_dwordx4 v[218:219], off
	s_waitcnt lgkmcnt(8)
	s_barrier
; #define PG8_STAGE(bufoff, gbase, voff) do { _Pragma("unroll") for (int _i = 0; _i < 2; ++_i) \
;         __builtin_amdgcn_global_load_lds((const unsigned*)((const char*)(gbase) + (voff)[_i]), (LAS unsigned*)(lds + (bufoff) + ldsw + _i * 8192), 16, 0, 0); } while (0)
; #define PG8_LDA(dst, b, h) do { _Pragma("unroll") for (int m = 0; m < 4; ++m) _Pragma("unroll") for (int k = 0; k < 2; ++k) dst[m][k] = *(const LAS bf16x8*)(lds + PG8_SA(b, h) + aoff + m * 2048 + k * 1024); } while (0)
; #define PG8_LDB(dst, b, h) do { _Pragma("unroll") for (int n = 0; n < 2; ++n) _Pragma("unroll") for (int k = 0; k < 2; ++k) dst[n][k] = *(const LAS bf16x8*)(lds + PG8_SB(b, h) + boff + n * 2048 + k * 1024); } while (0)
; #define PG8_MMA(ai, bj, At, Bt) do { __builtin_amdgcn_s_setprio(1); _Pragma("unroll") for (int m = 0; m < 4; ++m) _Pragma("unroll") for (int n = 0; n < 2; ++n) _Pragma("unroll") for (int k = 0; k < 2; ++k) \
;         acc[ai][bj][m][n] = __builtin_amdgcn_mfma_f32_16x16x32_bf16(Bt[n][k], At[m][k], acc[ai][bj][m][n], 0, 0, 0); __builtin_amdgcn_s_setprio(0); } while (0)
; #define PG8_WAIT_V(n) asm volatile("s_waitcnt vmcnt(" #n ")" ::: "memory")
; #define PG8_WAIT_L(n) asm volatile("s_waitcnt lgkmcnt(" #n ")" ::: "memory")
; #define PG8_BAR __builtin_amdgcn_s_barrier()
; #define PG8_SCHED __builtin_amdgcn_sched_barrier(0)
; template <class Epi>
; __device__ __forceinline__ void gemm_phase(LAS unsigned char* lds, const Gemm g, const StaticOrder& S, const Epi& E, const int tid) {
;     ...
;             PG8_WAIT_L(8); PG8_BAR; PG8_WAIT_L(0); PG8_MMA(0, 0, At, B0); PG8_BAR; PG8_SCHED;
;             PG8_LDB(B1, 1, 1); PG8_STAGE(PG8_SB(1, 0), b3, voffB);
;             PG8_BAR; PG8_WAIT_L(0); PG8_MMA(0, 1, At, B1); PG8_BAR;
;             PG8_LDA(At, 1, 1); PG8_STAGE(PG8_SA(1, 0), a3, voffA);
;             PG8_BAR; PG8_WAIT_L(0); PG8_MMA(1, 0, At, B0); PG8_BAR; PG8_SCHED;
;             PG8_STAGE(PG8_SB(1, 1), b3 + hstep, voffB);
;             PG8_WAIT_V(6); PG8_BAR; PG8_MMA(1, 1, At, B1); PG8_BAR;
	s_waitcnt lgkmcnt(0)
	v_mfma_f32_16x16x32_bf16 v[126:129], v[160:163], v[176:179], v[126:129]
	v_mfma_f32_16x16x32_bf16 v[122:125], v[168:171], v[176:179], v[122:125]
	v_mfma_f32_16x16x32_bf16 v[110:113], v[160:163], v[184:187], v[110:113]
	v_mfma_f32_16x16x32_bf16 v[106:109], v[168:171], v[184:187], v[106:109]
	v_mfma_f32_16x16x32_bf16 v[94:97], v[160:163], v[192:195], v[94:97]
	v_mfma_f32_16x16x32_bf16 v[90:93], v[168:171], v[192:195], v[90:93]
	v_mfma_f32_16x16x32_bf16 v[78:81], v[160:163], v[210:213], v[78:81]
	v_mfma_f32_16x16x32_bf16 v[74:77], v[168:171], v[210:213], v[74:77]
	v_mfma_f32_16x16x32_bf16 v[126:129], v[164:167], v[180:183], v[126:129]
	v_mfma_f32_16x16x32_bf16 v[122:125], v[172:175], v[180:183], v[122:125]
	v_mfma_f32_16x16x32_bf16 v[110:113], v[164:167], v[188:191], v[110:113]
	v_mfma_f32_16x16x32_bf16 v[106:109], v[172:175], v[188:191], v[106:109]
	v_mfma_f32_16x16x32_bf16 v[94:97], v[164:167], v[196:199], v[94:97]
	v_mfma_f32_16x16x32_bf16 v[90:93], v[172:175], v[196:199], v[90:93]
	v_mfma_f32_16x16x32_bf16 v[78:81], v[164:167], v[214:217], v[78:81]
	v_mfma_f32_16x16x32_bf16 v[74:77], v[172:175], v[214:217], v[74:77]
	s_barrier
	s_add_i32 s20, 0, 0x1c000
	s_add_i32 s21, s45, s26
	v_add_u32_e32 v159, s20, v144
	v_lshl_add_u64 v[140:141], v[140:141], 0, s[56:57]
	s_mov_b32 m0, s21
	ds_read_b128 v[218:221], v159
	ds_read_b128 v[222:225], v159 offset:1024
	ds_read_b128 v[226:229], v159 offset:2048
	ds_read_b128 v[230:233], v159 offset:3072
	global_load_lds_dwordx4 v[140:141], off
	v_lshl_add_u64 v[140:141], v[200:201], 0, s[56:57]
	s_add_i32 m0, s21, 0x2000
	s_nop 0
	global_load_lds_dwordx4 v[140:141], off
	s_barrier
	s_waitcnt lgkmcnt(0)
	v_mfma_f32_16x16x32_bf16 v[118:121], v[218:221], v[176:179], v[118:121]
	v_mfma_f32_16x16x32_bf16 v[114:117], v[226:229], v[176:179], v[114:117]
	v_mfma_f32_16x16x32_bf16 v[102:105], v[218:221], v[184:187], v[102:105]
	v_mfma_f32_16x16x32_bf16 v[98:101], v[226:229], v[184:187], v[98:101]
	v_mfma_f32_16x16x32_bf16 v[86:89], v[218:221], v[192:195], v[86:89]
	v_mfma_f32_16x16x32_bf16 v[82:85], v[226:229], v[192:195], v[82:85]
	v_mfma_f32_16x16x32_bf16 v[70:73], v[218:221], v[210:213], v[70:73]
	v_mfma_f32_16x16x32_bf16 v[66:69], v[226:229], v[210:213], v[66:69]
	v_mfma_f32_16x16x32_bf16 v[118:121], v[222:225], v[180:183], v[118:121]
	v_mfma_f32_16x16x32_bf16 v[114:117], v[230:233], v[180:183], v[114:117]
	v_mfma_f32_16x16x32_bf16 v[102:105], v[222:225], v[188:191], v[102:105]
	v_mfma_f32_16x16x32_bf16 v[98:101], v[230:233], v[188:191], v[98:101]
	v_mfma_f32_16x16x32_bf16 v[86:89], v[222:225], v[196:199], v[86:89]
	v_mfma_f32_16x16x32_bf16 v[82:85], v[230:233], v[196:199], v[82:85]
	v_mfma_f32_16x16x32_bf16 v[70:73], v[222:225], v[214:217], v[70:73]
	v_mfma_f32_16x16x32_bf16 v[66:69], v[230:233], v[214:217], v[66:69]
	s_mov_b32 m0, s35
	v_lshl_add_u64 v[140:141], v[234:235], 0, s[56:57]
	s_barrier
	ds_read_b128 v[176:179], v145 offset:49152
	ds_read_b128 v[180:183], v145 offset:50176
	ds_read_b128 v[184:187], v145 offset:51200
	ds_read_b128 v[188:191], v145 offset:52224
	ds_read_b128 v[192:195], v145 offset:53248
	ds_read_b128 v[196:199], v145 offset:54272
	ds_read_b128 v[210:213], v145 offset:55296
	ds_read_b128 v[214:217], v145 offset:56320
	global_load_lds_dwordx4 v[140:141], off
	v_lshl_add_u64 v[140:141], v[236:237], 0, s[56:57]
	s_mov_b32 m0, s36
	s_nop 0
	global_load_lds_dwordx4 v[140:141], off
	s_barrier
	s_waitcnt lgkmcnt(0)
	v_mfma_f32_16x16x32_bf16 v[62:65], v[160:163], v[176:179], v[62:65]
	v_mfma_f32_16x16x32_bf16 v[58:61], v[168:171], v[176:179], v[58:61]
	v_mfma_f32_16x16x32_bf16 v[46:49], v[160:163], v[184:187], v[46:49]
	v_mfma_f32_16x16x32_bf16 v[42:45], v[168:171], v[184:187], v[42:45]
	v_mfma_f32_16x16x32_bf16 v[30:33], v[160:163], v[192:195], v[30:33]
	v_mfma_f32_16x16x32_bf16 v[26:29], v[168:171], v[192:195], v[26:29]
	v_mfma_f32_16x16x32_bf16 v[14:17], v[160:163], v[210:213], v[14:17]
	v_mfma_f32_16x16x32_bf16 v[10:13], v[168:171], v[210:213], v[10:13]
	v_mfma_f32_16x16x32_bf16 v[62:65], v[164:167], v[180:183], v[62:65]
	v_mfma_f32_16x16x32_bf16 v[58:61], v[172:175], v[180:183], v[58:61]
	v_mfma_f32_16x16x32_bf16 v[46:49], v[164:167], v[188:191], v[46:49]
	v_mfma_f32_16x16x32_bf16 v[42:45], v[172:175], v[188:191], v[42:45]
	v_mfma_f32_16x16x32_bf16 v[30:33], v[164:167], v[196:199], v[30:33]
	v_mfma_f32_16x16x32_bf16 v[26:29], v[172:175], v[196:199], v[26:29]
	v_mfma_f32_16x16x32_bf16 v[14:17], v[164:167], v[214:217], v[14:17]
	v_mfma_f32_16x16x32_bf16 v[10:13], v[172:175], v[214:217], v[10:13]
	s_barrier
	s_add_u32 s18, s18, 0x80080
	s_addc_u32 s19, s19, 0
	s_add_i32 s20, s20, s26
	v_lshl_add_u64 v[140:141], s[18:19], 0, v[0:1]
	s_mov_b32 m0, s20
	s_nop 0
	global_load_lds_dwordx4 v[140:141], off
	v_lshl_add_u64 v[140:141], s[18:19], 0, v[134:135]
	s_add_i32 m0, s20, 0x2000
	s_nop 0
	global_load_lds_dwordx4 v[140:141], off
	s_waitcnt vmcnt(6)
	s_barrier
	v_mfma_f32_16x16x32_bf16 v[54:57], v[218:221], v[176:179], v[54:57]
	v_mfma_f32_16x16x32_bf16 v[50:53], v[226:229], v[176:179], v[50:53]
	v_mfma_f32_16x16x32_bf16 v[38:41], v[218:221], v[184:187], v[38:41]
	v_mfma_f32_16x16x32_bf16 v[34:37], v[226:229], v[184:187], v[34:37]
	v_mfma_f32_16x16x32_bf16 v[22:25], v[218:221], v[192:195], v[22:25]
	v_mfma_f32_16x16x32_bf16 v[18:21], v[226:229], v[192:195], v[18:21]
	v_mfma_f32_16x16x32_bf16 v[6:9], v[218:221], v[210:213], v[6:9]
	v_mfma_f32_16x16x32_bf16 v[2:5], v[226:229], v[210:213], v[2:5]
	v_mfma_f32_16x16x32_bf16 v[54:57], v[222:225], v[180:183], v[54:57]
	v_mfma_f32_16x16x32_bf16 v[50:53], v[230:233], v[180:183], v[50:53]
	v_mfma_f32_16x16x32_bf16 v[38:41], v[222:225], v[188:191], v[38:41]
	v_mfma_f32_16x16x32_bf16 v[34:37], v[230:233], v[188:191], v[34:37]
	v_mfma_f32_16x16x32_bf16 v[22:25], v[222:225], v[196:199], v[22:25]
	v_mfma_f32_16x16x32_bf16 v[18:21], v[230:233], v[196:199], v[18:21]
	v_mfma_f32_16x16x32_bf16 v[6:9], v[222:225], v[214:217], v[6:9]
	v_mfma_f32_16x16x32_bf16 v[2:5], v[230:233], v[214:217], v[2:5]
	s_add_i32 s44, s44, 2
	s_add_u32 s42, s42, 0x100
	s_addc_u32 s43, s43, 0
	s_add_u32 s16, s16, 0x100
	s_addc_u32 s17, s17, 0
	s_cmp_gt_u32 s44, 29
	s_barrier
; __device__ __forceinline__ unsigned pk2(float lo, float hi) { f32x2 v = {lo, hi}; return __builtin_bit_cast(unsigned, __builtin_convertvector(v, bf16x2_t)); }
;     __device__ __forceinline__ void operator()(const f32x4 (&acc)[2][2][4][2], const Unit& u, int wr, int wc, int fr, int fq) const {
;     ...
;         const int row0 = u.pm * BM + wr * 64 + fr, col0 = u.pn * BM + wc * 32 + 8 * fq;
; #pragma unroll
;         for (int ai = 0; ai < 2; ++ai)
; #pragma unroll
;             for (int m = 0; m < 4; ++m) {
;                 bf16_t* rowp = O + (size_t)(row0 + ai * HALF + m * 16) * ldc + col0;
; #pragma unroll
;                 for (int bj = 0; bj < 2; ++bj) {
;                     f32x4 v0 = acc[ai][bj][m][0], v1 = acc[ai][bj][m][1];
; #pragma unroll
;                     for (int j = 0; j < 4; ++j) { const float a = fmaxf(v0[j], 0.f), b = fmaxf(v1[j], 0.f); v0[j] = a * a; v1[j] = b * b; }
;                     u32x4 w; w.x = pk2(v0[0], v0[1]); w.y = pk2(v0[2], v0[3]); w.z = pk2(v1[0], v1[1]); w.w = pk2(v1[2], v1[3]);
;                     *(u32x4*)(rowp + bj * HALF) = w;
	s_cbranch_scc0 .LBB0_84
	s_setprio 0
	v_mov_b32_e32 v141, v143
	v_mov_b32_e32 v140, v142
	s_lshl_b32 s7, s14, 8
	s_add_i32 s7, s7, s31
	v_add_u32_e32 v140, s7, v140
	s_lshl_b32 s7, s39, 8
	s_or_b32 s7, s7, s34
	v_lshl_add_u32 v160, v141, 3, s7
	v_ashrrev_i32_e32 v141, 31, v140
	v_lshlrev_b64 v[140:141], 14, v[140:141]
	v_max_f32_e32 v122, v122, v122
	v_max_f32_e32 v123, v123, v123
	v_ashrrev_i32_e32 v161, 31, v160
	v_lshl_add_u64 v[140:141], s[2:3], 0, v[140:141]
	v_max_f32_e32 v122, 0, v122
	v_max_f32_e32 v123, 0, v123
	v_lshl_add_u64 v[140:141], v[160:161], 1, v[140:141]
	v_pk_mul_f32 v[160:161], v[122:123], v[122:123]
	v_max_f32_e32 v123, v124, v124
	v_max_f32_e32 v126, v126, v126
	v_max_f32_e32 v127, v127, v127
	v_max_f32_e32 v122, v128, v128
	v_max_f32_e32 v124, 0, v123
	v_max_f32_e32 v123, v129, v129
	v_max_f32_e32 v125, v125, v125
	v_max_f32_e32 v126, 0, v126
	v_max_f32_e32 v127, 0, v127
	v_max_f32_e32 v122, 0, v122
	v_max_f32_e32 v123, 0, v123
	v_max_f32_e32 v125, 0, v125
	v_pk_mul_f32 v[126:127], v[126:127], v[126:127]
	v_pk_mul_f32 v[128:129], v[122:123], v[122:123]
	v_pk_mul_f32 v[162:163], v[124:125], v[124:125]
	v_max_f32_e32 v114, v114, v114
	v_max_f32_e32 v115, v115, v115
	v_cvt_pk_bf16_f32 v122, v126, v127
	v_cvt_pk_bf16_f32 v123, v128, v129
	v_cvt_pk_bf16_f32 v124, v160, v161
	v_cvt_pk_bf16_f32 v125, v162, v163
	v_max_f32_e32 v114, 0, v114
	v_max_f32_e32 v115, 0, v115
	global_store_dwordx4 v[140:141], v[122:125], off
	v_max_f32_e32 v118, v118, v118
	v_max_f32_e32 v119, v119, v119
	v_pk_mul_f32 v[122:123], v[114:115], v[114:115]
	v_max_f32_e32 v115, v116, v116
	v_max_f32_e32 v114, v120, v120
	v_max_f32_e32 v116, 0, v115
	v_max_f32_e32 v115, v121, v121
	v_max_f32_e32 v117, v117, v117
	v_max_f32_e32 v118, 0, v118
	v_max_f32_e32 v119, 0, v119
	v_max_f32_e32 v114, 0, v114
	v_max_f32_e32 v115, 0, v115
	v_max_f32_e32 v117, 0, v117
	v_pk_mul_f32 v[118:119], v[118:119], v[118:119]
	v_pk_mul_f32 v[120:121], v[114:115], v[114:115]
	v_pk_mul_f32 v[124:125], v[116:117], v[116:117]
	v_max_f32_e32 v106, v106, v106
	v_max_f32_e32 v107, v107, v107
	v_cvt_pk_bf16_f32 v114, v118, v119
	v_cvt_pk_bf16_f32 v115, v120, v121
	v_cvt_pk_bf16_f32 v116, v122, v123
	v_cvt_pk_bf16_f32 v117, v124, v125
	v_max_f32_e32 v106, 0, v106
	v_max_f32_e32 v107, 0, v107
	global_store_dwordx4 v[140:141], v[114:117], off offset:256
	v_max_f32_e32 v110, v110, v110
	v_max_f32_e32 v111, v111, v111
	v_pk_mul_f32 v[116:117], v[106:107], v[106:107]
	v_max_f32_e32 v107, v108, v108
	v_max_f32_e32 v110, 0, v110
	v_max_f32_e32 v111, 0, v111
	v_max_f32_e32 v106, v112, v112
	v_max_f32_e32 v108, 0, v107
	v_max_f32_e32 v107, v113, v113
	v_max_f32_e32 v109, v109, v109
	v_pk_mul_f32 v[110:111], v[110:111], v[110:111]
	v_max_f32_e32 v106, 0, v106
	v_max_f32_e32 v107, 0, v107
	v_max_f32_e32 v109, 0, v109
	s_mov_b32 s7, 0x40000
	v_pk_mul_f32 v[112:113], v[106:107], v[106:107]
	v_pk_mul_f32 v[118:119], v[108:109], v[108:109]
	v_cvt_pk_bf16_f32 v106, v110, v111
	v_add_co_u32_e32 v110, vcc, s7, v140
	v_max_f32_e32 v98, v98, v98
	v_max_f32_e32 v99, v99, v99
	v_cvt_pk_bf16_f32 v107, v112, v113
	v_cvt_pk_bf16_f32 v108, v116, v117
	v_cvt_pk_bf16_f32 v109, v118, v119
	v_addc_co_u32_e32 v111, vcc, 0, v141, vcc
	v_max_f32_e32 v98, 0, v98
	v_max_f32_e32 v99, 0, v99
	global_store_dwordx4 v[110:111], v[106:109], off
	v_max_f32_e32 v102, v102, v102
	v_max_f32_e32 v103, v103, v103
	v_pk_mul_f32 v[106:107], v[98:99], v[98:99]
	v_max_f32_e32 v99, v100, v100
	v_max_f32_e32 v98, v104, v104
	v_max_f32_e32 v100, 0, v99
	v_max_f32_e32 v99, v105, v105
	v_max_f32_e32 v101, v101, v101
	v_max_f32_e32 v102, 0, v102
	v_max_f32_e32 v103, 0, v103
	v_max_f32_e32 v98, 0, v98
	v_max_f32_e32 v99, 0, v99
	v_max_f32_e32 v101, 0, v101
	s_mov_b64 s[16:17], 0x40000
	v_pk_mul_f32 v[102:103], v[102:103], v[102:103]
	v_pk_mul_f32 v[104:105], v[98:99], v[98:99]
	v_pk_mul_f32 v[108:109], v[100:101], v[100:101]
	v_max_f32_e32 v90, v90, v90
	v_max_f32_e32 v91, v91, v91
	v_lshl_add_u64 v[114:115], v[140:141], 0, s[16:17]
	v_cvt_pk_bf16_f32 v98, v102, v103
	v_cvt_pk_bf16_f32 v99, v104, v105
	v_cvt_pk_bf16_f32 v100, v106, v107
	v_cvt_pk_bf16_f32 v101, v108, v109
	v_max_f32_e32 v90, 0, v90
	v_max_f32_e32 v91, 0, v91
	global_store_dwordx4 v[114:115], v[98:101], off offset:256
	v_max_f32_e32 v94, v94, v94
	v_max_f32_e32 v95, v95, v95
	v_pk_mul_f32 v[100:101], v[90:91], v[90:91]
	v_max_f32_e32 v91, v92, v92
	v_max_f32_e32 v94, 0, v94
	v_max_f32_e32 v95, 0, v95
	v_max_f32_e32 v90, v96, v96
	v_max_f32_e32 v92, 0, v91
	v_max_f32_e32 v91, v97, v97
	v_max_f32_e32 v93, v93, v93
	v_pk_mul_f32 v[94:95], v[94:95], v[94:95]
	v_max_f32_e32 v90, 0, v90
	v_max_f32_e32 v91, 0, v91
	v_max_f32_e32 v93, 0, v93
	s_mov_b32 s7, 0x80000
	v_pk_mul_f32 v[96:97], v[90:91], v[90:91]
	v_pk_mul_f32 v[102:103], v[92:93], v[92:93]
	v_cvt_pk_bf16_f32 v90, v94, v95
	v_add_co_u32_e32 v94, vcc, s7, v140
	v_max_f32_e32 v82, v82, v82
	v_max_f32_e32 v83, v83, v83
	v_cvt_pk_bf16_f32 v91, v96, v97
	v_cvt_pk_bf16_f32 v92, v100, v101
	v_cvt_pk_bf16_f32 v93, v102, v103
	v_addc_co_u32_e32 v95, vcc, 0, v141, vcc
	v_max_f32_e32 v82, 0, v82
	v_max_f32_e32 v83, 0, v83
	global_store_dwordx4 v[94:95], v[90:93], off
	v_max_f32_e32 v86, v86, v86
	v_max_f32_e32 v87, v87, v87
	v_pk_mul_f32 v[90:91], v[82:83], v[82:83]
	v_max_f32_e32 v83, v84, v84
	v_max_f32_e32 v82, v88, v88
	v_max_f32_e32 v84, 0, v83
	v_max_f32_e32 v83, v89, v89
	v_max_f32_e32 v85, v85, v85
	v_max_f32_e32 v86, 0, v86
	v_max_f32_e32 v87, 0, v87
	v_max_f32_e32 v82, 0, v82
	v_max_f32_e32 v83, 0, v83
	v_max_f32_e32 v85, 0, v85
	s_mov_b64 s[16:17], 0x80000
	v_pk_mul_f32 v[86:87], v[86:87], v[86:87]
; __device__ __forceinline__ unsigned pk2(float lo, float hi) { f32x2 v = {lo, hi}; return __builtin_bit_cast(unsigned, __builtin_convertvector(v, bf16x2_t)); }
;     __device__ __forceinline__ void operator()(const f32x4 (&acc)[2][2][4][2], const Unit& u, int wr, int wc, int fr, int fq) const {
;     ...
;         for (int ai = 0; ai < 2; ++ai)
; #pragma unroll
;             for (int m = 0; m < 4; ++m) {
;                 bf16_t* rowp = O + (size_t)(row0 + ai * HALF + m * 16) * ldc + col0;
; #pragma unroll
;                 for (int bj = 0; bj < 2; ++bj) {
;                     f32x4 v0 = acc[ai][bj][m][0], v1 = acc[ai][bj][m][1];
; #pragma unroll
;                     for (int j = 0; j < 4; ++j) { const float a = fmaxf(v0[j], 0.f), b = fmaxf(v1[j], 0.f); v0[j] = a * a; v1[j] = b * b; }
;                     u32x4 w; w.x = pk2(v0[0], v0[1]); w.y = pk2(v0[2], v0[3]); w.z = pk2(v1[0], v1[1]); w.w = pk2(v1[2], v1[3]);
;                     *(u32x4*)(rowp + bj * HALF) = w;
	v_pk_mul_f32 v[88:89], v[82:83], v[82:83]
	v_pk_mul_f32 v[92:93], v[84:85], v[84:85]
	v_max_f32_e32 v74, v74, v74
	v_max_f32_e32 v75, v75, v75
	v_lshl_add_u64 v[98:99], v[140:141], 0, s[16:17]
	v_cvt_pk_bf16_f32 v82, v86, v87
	v_cvt_pk_bf16_f32 v83, v88, v89
	v_cvt_pk_bf16_f32 v84, v90, v91
	v_cvt_pk_bf16_f32 v85, v92, v93
	v_max_f32_e32 v74, 0, v74
	v_max_f32_e32 v75, 0, v75
	global_store_dwordx4 v[98:99], v[82:85], off offset:256
	v_max_f32_e32 v78, v78, v78
	v_max_f32_e32 v79, v79, v79
	v_pk_mul_f32 v[84:85], v[74:75], v[74:75]
	v_max_f32_e32 v75, v76, v76
	v_max_f32_e32 v78, 0, v78
	v_max_f32_e32 v79, 0, v79
	v_max_f32_e32 v74, v80, v80
	v_max_f32_e32 v76, 0, v75
	v_max_f32_e32 v75, v81, v81
	v_max_f32_e32 v77, v77, v77
	v_pk_mul_f32 v[78:79], v[78:79], v[78:79]
	v_max_f32_e32 v74, 0, v74
	v_max_f32_e32 v75, 0, v75
	v_max_f32_e32 v77, 0, v77
	s_mov_b32 s7, 0xc0000
	v_pk_mul_f32 v[80:81], v[74:75], v[74:75]
	v_pk_mul_f32 v[86:87], v[76:77], v[76:77]
	v_cvt_pk_bf16_f32 v74, v78, v79
	v_add_co_u32_e32 v78, vcc, s7, v140
	v_max_f32_e32 v66, v66, v66
	v_max_f32_e32 v67, v67, v67
	v_cvt_pk_bf16_f32 v75, v80, v81
	v_cvt_pk_bf16_f32 v76, v84, v85
	v_cvt_pk_bf16_f32 v77, v86, v87
	v_addc_co_u32_e32 v79, vcc, 0, v141, vcc
	v_max_f32_e32 v66, 0, v66
	v_max_f32_e32 v67, 0, v67
	global_store_dwordx4 v[78:79], v[74:77], off
	v_max_f32_e32 v70, v70, v70
	v_max_f32_e32 v71, v71, v71
	v_pk_mul_f32 v[74:75], v[66:67], v[66:67]
	v_max_f32_e32 v67, v68, v68
	v_max_f32_e32 v66, v72, v72
	v_max_f32_e32 v68, 0, v67
	v_max_f32_e32 v67, v73, v73
	v_max_f32_e32 v69, v69, v69
	v_max_f32_e32 v70, 0, v70
	v_max_f32_e32 v71, 0, v71
	v_max_f32_e32 v66, 0, v66
	v_max_f32_e32 v67, 0, v67
	v_max_f32_e32 v69, 0, v69
	s_mov_b64 s[16:17], 0xc0000
	v_pk_mul_f32 v[70:71], v[70:71], v[70:71]
	v_pk_mul_f32 v[72:73], v[66:67], v[66:67]
	v_pk_mul_f32 v[76:77], v[68:69], v[68:69]
	v_max_f32_e32 v58, v58, v58
	v_max_f32_e32 v59, v59, v59
	v_lshl_add_u64 v[82:83], v[140:141], 0, s[16:17]
	v_cvt_pk_bf16_f32 v66, v70, v71
	v_cvt_pk_bf16_f32 v67, v72, v73
	v_cvt_pk_bf16_f32 v68, v74, v75
	v_cvt_pk_bf16_f32 v69, v76, v77
	v_max_f32_e32 v58, 0, v58
	v_max_f32_e32 v59, 0, v59
	global_store_dwordx4 v[82:83], v[66:69], off offset:256
	v_max_f32_e32 v62, v62, v62
	v_max_f32_e32 v63, v63, v63
	v_pk_mul_f32 v[68:69], v[58:59], v[58:59]
	v_max_f32_e32 v59, v60, v60
	v_max_f32_e32 v62, 0, v62
	v_max_f32_e32 v63, 0, v63
	v_max_f32_e32 v58, v64, v64
	v_max_f32_e32 v60, 0, v59
	v_max_f32_e32 v59, v65, v65
	v_max_f32_e32 v61, v61, v61
	v_pk_mul_f32 v[62:63], v[62:63], v[62:63]
	v_max_f32_e32 v58, 0, v58
	v_max_f32_e32 v59, 0, v59
	v_max_f32_e32 v61, 0, v61
	s_mov_b32 s7, 0x200000
	v_pk_mul_f32 v[64:65], v[58:59], v[58:59]
	v_pk_mul_f32 v[70:71], v[60:61], v[60:61]
	v_cvt_pk_bf16_f32 v58, v62, v63
	v_add_co_u32_e32 v62, vcc, s7, v140
	v_max_f32_e32 v50, v50, v50
	v_max_f32_e32 v51, v51, v51
	v_cvt_pk_bf16_f32 v59, v64, v65
	v_cvt_pk_bf16_f32 v60, v68, v69
	v_cvt_pk_bf16_f32 v61, v70, v71
	v_addc_co_u32_e32 v63, vcc, 0, v141, vcc
	v_max_f32_e32 v50, 0, v50
	v_max_f32_e32 v51, 0, v51
	global_store_dwordx4 v[62:63], v[58:61], off
	v_max_f32_e32 v54, v54, v54
	v_max_f32_e32 v55, v55, v55
	v_pk_mul_f32 v[58:59], v[50:51], v[50:51]
	v_max_f32_e32 v51, v52, v52
	v_max_f32_e32 v50, v56, v56
	v_max_f32_e32 v52, 0, v51
	v_max_f32_e32 v51, v57, v57
	v_max_f32_e32 v53, v53, v53
	v_max_f32_e32 v54, 0, v54
	v_max_f32_e32 v55, 0, v55
	v_max_f32_e32 v50, 0, v50
	v_max_f32_e32 v51, 0, v51
	v_max_f32_e32 v53, 0, v53
	s_mov_b64 s[16:17], 0x200000
	v_pk_mul_f32 v[54:55], v[54:55], v[54:55]
	v_pk_mul_f32 v[56:57], v[50:51], v[50:51]
	v_pk_mul_f32 v[60:61], v[52:53], v[52:53]
	v_max_f32_e32 v42, v42, v42
	v_max_f32_e32 v43, v43, v43
	v_lshl_add_u64 v[66:67], v[140:141], 0, s[16:17]
	v_cvt_pk_bf16_f32 v50, v54, v55
	v_cvt_pk_bf16_f32 v51, v56, v57
	v_cvt_pk_bf16_f32 v52, v58, v59
	v_cvt_pk_bf16_f32 v53, v60, v61
	v_max_f32_e32 v42, 0, v42
	v_max_f32_e32 v43, 0, v43
	global_store_dwordx4 v[66:67], v[50:53], off offset:256
	v_max_f32_e32 v46, v46, v46
	v_max_f32_e32 v47, v47, v47
	v_pk_mul_f32 v[52:53], v[42:43], v[42:43]
	v_max_f32_e32 v43, v44, v44
	v_max_f32_e32 v46, 0, v46
	v_max_f32_e32 v47, 0, v47
	v_max_f32_e32 v42, v48, v48
	v_max_f32_e32 v44, 0, v43
	v_max_f32_e32 v43, v49, v49
	v_max_f32_e32 v45, v45, v45
	v_pk_mul_f32 v[46:47], v[46:47], v[46:47]
	v_max_f32_e32 v42, 0, v42
	v_max_f32_e32 v43, 0, v43
	v_max_f32_e32 v45, 0, v45
	s_mov_b32 s7, 0x240000
	v_pk_mul_f32 v[48:49], v[42:43], v[42:43]
	v_pk_mul_f32 v[54:55], v[44:45], v[44:45]
	v_cvt_pk_bf16_f32 v42, v46, v47
	v_add_co_u32_e32 v46, vcc, s7, v140
	v_max_f32_e32 v34, v34, v34
	v_max_f32_e32 v35, v35, v35
	v_cvt_pk_bf16_f32 v43, v48, v49
; __device__ __forceinline__ unsigned pk2(float lo, float hi) { f32x2 v = {lo, hi}; return __builtin_bit_cast(unsigned, __builtin_convertvector(v, bf16x2_t)); }
; #define PG8_WAIT_V(n) asm volatile("s_waitcnt vmcnt(" #n ")" ::: "memory")
; #define PG8_BAR __builtin_amdgcn_s_barrier()
;     __device__ __forceinline__ void operator()(const f32x4 (&acc)[2][2][4][2], const Unit& u, int wr, int wc, int fr, int fq) const {
;     ...
;         for (int ai = 0; ai < 2; ++ai)
; #pragma unroll
;             for (int m = 0; m < 4; ++m) {
;                 bf16_t* rowp = O + (size_t)(row0 + ai * HALF + m * 16) * ldc + col0;
; #pragma unroll
;                 for (int bj = 0; bj < 2; ++bj) {
;                     f32x4 v0 = acc[ai][bj][m][0], v1 = acc[ai][bj][m][1];
; #pragma unroll
;                     for (int j = 0; j < 4; ++j) { const float a = fmaxf(v0[j], 0.f), b = fmaxf(v1[j], 0.f); v0[j] = a * a; v1[j] = b * b; }
;                     u32x4 w; w.x = pk2(v0[0], v0[1]); w.y = pk2(v0[2], v0[3]); w.z = pk2(v1[0], v1[1]); w.w = pk2(v1[2], v1[3]);
;                     *(u32x4*)(rowp + bj * HALF) = w;
;                 }
;             }
; template <class Epi>
; __device__ __forceinline__ void gemm_phase(LAS unsigned char* lds, const Gemm g, const StaticOrder& S, const Epi& E, const int tid) {
;     ...
;         E(acc, cur, wr, wc, fr, fq);
;         if (!has_next) break;
; #pragma unroll
;         for (int a = 0; a < 2; ++a)
; #pragma unroll
;             for (int b = 0; b < 2; ++b)
; #pragma unroll
;                 for (int m = 0; m < 4; ++m)
; #pragma unroll
;                     for (int n = 0; n < 2; ++n) acc[a][b][m][n] = (f32x4){0.f, 0.f, 0.f, 0.f};
;         cur = nxt; cA = nA; cB = nB; ++ui;
;     }
;     PG8_WAIT_V(0);
;     if (wr == 0) PG8_BAR;
	v_cvt_pk_bf16_f32 v44, v52, v53
	v_cvt_pk_bf16_f32 v45, v54, v55
	v_addc_co_u32_e32 v47, vcc, 0, v141, vcc
	v_max_f32_e32 v34, 0, v34
	v_max_f32_e32 v35, 0, v35
	global_store_dwordx4 v[46:47], v[42:45], off
	v_max_f32_e32 v38, v38, v38
	v_max_f32_e32 v39, v39, v39
	v_pk_mul_f32 v[42:43], v[34:35], v[34:35]
	v_max_f32_e32 v35, v36, v36
	v_max_f32_e32 v34, v40, v40
	v_max_f32_e32 v36, 0, v35
	v_max_f32_e32 v35, v41, v41
	v_max_f32_e32 v37, v37, v37
	v_max_f32_e32 v38, 0, v38
	v_max_f32_e32 v39, 0, v39
	v_max_f32_e32 v34, 0, v34
	v_max_f32_e32 v35, 0, v35
	v_max_f32_e32 v37, 0, v37
	s_mov_b64 s[16:17], 0x240000
	v_pk_mul_f32 v[38:39], v[38:39], v[38:39]
	v_pk_mul_f32 v[40:41], v[34:35], v[34:35]
	v_pk_mul_f32 v[44:45], v[36:37], v[36:37]
	v_max_f32_e32 v26, v26, v26
	v_max_f32_e32 v27, v27, v27
	v_lshl_add_u64 v[50:51], v[140:141], 0, s[16:17]
	v_cvt_pk_bf16_f32 v34, v38, v39
	v_cvt_pk_bf16_f32 v35, v40, v41
	v_cvt_pk_bf16_f32 v36, v42, v43
	v_cvt_pk_bf16_f32 v37, v44, v45
	v_max_f32_e32 v26, 0, v26
	v_max_f32_e32 v27, 0, v27
	global_store_dwordx4 v[50:51], v[34:37], off offset:256
	v_max_f32_e32 v30, v30, v30
	v_max_f32_e32 v31, v31, v31
	v_pk_mul_f32 v[36:37], v[26:27], v[26:27]
	v_max_f32_e32 v27, v28, v28
	v_max_f32_e32 v30, 0, v30
	v_max_f32_e32 v31, 0, v31
	v_max_f32_e32 v26, v32, v32
	v_max_f32_e32 v28, 0, v27
	v_max_f32_e32 v27, v33, v33
	v_max_f32_e32 v29, v29, v29
	v_pk_mul_f32 v[30:31], v[30:31], v[30:31]
	v_max_f32_e32 v26, 0, v26
	v_max_f32_e32 v27, 0, v27
	v_max_f32_e32 v29, 0, v29
	s_mov_b32 s7, 0x280000
	v_pk_mul_f32 v[32:33], v[26:27], v[26:27]
	v_pk_mul_f32 v[38:39], v[28:29], v[28:29]
	v_cvt_pk_bf16_f32 v26, v30, v31
	v_add_co_u32_e32 v30, vcc, s7, v140
	v_max_f32_e32 v18, v18, v18
	v_max_f32_e32 v19, v19, v19
	v_cvt_pk_bf16_f32 v27, v32, v33
	v_cvt_pk_bf16_f32 v28, v36, v37
	v_cvt_pk_bf16_f32 v29, v38, v39
	v_addc_co_u32_e32 v31, vcc, 0, v141, vcc
	v_max_f32_e32 v18, 0, v18
	v_max_f32_e32 v19, 0, v19
	global_store_dwordx4 v[30:31], v[26:29], off
	v_max_f32_e32 v22, v22, v22
	v_max_f32_e32 v23, v23, v23
	v_pk_mul_f32 v[26:27], v[18:19], v[18:19]
	v_max_f32_e32 v19, v20, v20
	v_max_f32_e32 v18, v24, v24
	v_max_f32_e32 v20, 0, v19
	v_max_f32_e32 v19, v25, v25
	v_max_f32_e32 v21, v21, v21
	v_max_f32_e32 v22, 0, v22
	v_max_f32_e32 v23, 0, v23
	v_max_f32_e32 v18, 0, v18
	v_max_f32_e32 v19, 0, v19
	v_max_f32_e32 v21, 0, v21
	s_mov_b64 s[16:17], 0x280000
	v_pk_mul_f32 v[22:23], v[22:23], v[22:23]
	v_pk_mul_f32 v[24:25], v[18:19], v[18:19]
	v_pk_mul_f32 v[28:29], v[20:21], v[20:21]
	v_max_f32_e32 v10, v10, v10
	v_max_f32_e32 v11, v11, v11
	v_lshl_add_u64 v[34:35], v[140:141], 0, s[16:17]
	v_cvt_pk_bf16_f32 v18, v22, v23
	v_cvt_pk_bf16_f32 v19, v24, v25
	v_cvt_pk_bf16_f32 v20, v26, v27
	v_cvt_pk_bf16_f32 v21, v28, v29
	v_max_f32_e32 v10, 0, v10
	v_max_f32_e32 v11, 0, v11
	global_store_dwordx4 v[34:35], v[18:21], off offset:256
	v_max_f32_e32 v14, v14, v14
	v_max_f32_e32 v15, v15, v15
	v_pk_mul_f32 v[20:21], v[10:11], v[10:11]
	v_max_f32_e32 v11, v12, v12
	v_max_f32_e32 v14, 0, v14
	v_max_f32_e32 v15, 0, v15
	v_max_f32_e32 v10, v16, v16
	v_max_f32_e32 v12, 0, v11
	v_max_f32_e32 v11, v17, v17
	v_max_f32_e32 v13, v13, v13
	v_pk_mul_f32 v[14:15], v[14:15], v[14:15]
	v_max_f32_e32 v10, 0, v10
	v_max_f32_e32 v11, 0, v11
	v_max_f32_e32 v13, 0, v13
	s_mov_b32 s7, 0x2c0000
	v_pk_mul_f32 v[16:17], v[10:11], v[10:11]
	v_pk_mul_f32 v[22:23], v[12:13], v[12:13]
	v_cvt_pk_bf16_f32 v10, v14, v15
	v_add_co_u32_e32 v14, vcc, s7, v140
	v_max_f32_e32 v2, v2, v2
	v_max_f32_e32 v3, v3, v3
	v_cvt_pk_bf16_f32 v11, v16, v17
	v_cvt_pk_bf16_f32 v12, v20, v21
	v_cvt_pk_bf16_f32 v13, v22, v23
	v_addc_co_u32_e32 v15, vcc, 0, v141, vcc
	v_max_f32_e32 v2, 0, v2
	v_max_f32_e32 v3, 0, v3
	global_store_dwordx4 v[14:15], v[10:13], off
	v_max_f32_e32 v6, v6, v6
	v_max_f32_e32 v7, v7, v7
	v_pk_mul_f32 v[10:11], v[2:3], v[2:3]
	v_max_f32_e32 v3, v4, v4
	v_max_f32_e32 v2, v8, v8
	v_max_f32_e32 v4, 0, v3
	v_max_f32_e32 v3, v9, v9
	v_max_f32_e32 v5, v5, v5
	v_max_f32_e32 v6, 0, v6
	v_max_f32_e32 v7, 0, v7
	v_max_f32_e32 v2, 0, v2
	v_max_f32_e32 v3, 0, v3
	v_max_f32_e32 v5, 0, v5
	s_mov_b64 s[16:17], 0x2c0000
	v_pk_mul_f32 v[6:7], v[6:7], v[6:7]
	v_pk_mul_f32 v[8:9], v[2:3], v[2:3]
	v_pk_mul_f32 v[12:13], v[4:5], v[4:5]
	v_lshl_add_u64 v[18:19], v[140:141], 0, s[16:17]
	v_cvt_pk_bf16_f32 v2, v6, v7
	v_cvt_pk_bf16_f32 v3, v8, v9
	v_cvt_pk_bf16_f32 v4, v10, v11
	v_cvt_pk_bf16_f32 v5, v12, v13
	s_and_b64 vcc, exec, s[4:5]
	s_mov_b32 s39, s6
	s_mov_b32 s14, s8
	s_mov_b64 s[16:17], s[12:13]
	s_mov_b64 s[18:19], s[10:11]
	global_store_dwordx4 v[18:19], v[2:5], off offset:256
	s_cbranch_vccz .LBB0_77
	s_waitcnt vmcnt(0)
	s_cmpk_gt_u32 s0, 0xff
	s_cbranch_scc1 .LBB0_88
	s_barrier

; #define PG8_STAGE(bufoff, gbase, voff) do { _Pragma("unroll") for (int _i = 0; _i < 2; ++_i) \
;         __builtin_amdgcn_global_load_lds((const unsigned*)((const char*)(gbase) + (voff)[_i]), (LAS unsigned*)(lds + (bufoff) + ldsw + _i * 8192), 16, 0, 0); } while (0)
; #define PG8_LDA(dst, b, h) do { _Pragma("unroll") for (int m = 0; m < 4; ++m) _Pragma("unroll") for (int k = 0; k < 2; ++k) dst[m][k] = *(const LAS bf16x8*)(lds + PG8_SA(b, h) + aoff + m * 2048 + k * 1024); } while (0)
; #define PG8_LDB(dst, b, h) do { _Pragma("unroll") for (int n = 0; n < 2; ++n) _Pragma("unroll") for (int k = 0; k < 2; ++k) dst[n][k] = *(const LAS bf16x8*)(lds + PG8_SB(b, h) + boff + n * 2048 + k * 1024); } while (0)
; #define PG8_MMA(ai, bj, At, Bt) do { __builtin_amdgcn_s_setprio(1); _Pragma("unroll") for (int m = 0; m < 4; ++m) _Pragma("unroll") for (int n = 0; n < 2; ++n) _Pragma("unroll") for (int k = 0; k < 2; ++k) \
;         acc[ai][bj][m][n] = __builtin_amdgcn_mfma_f32_16x16x32_bf16(Bt[n][k], At[m][k], acc[ai][bj][m][n], 0, 0, 0); __builtin_amdgcn_s_setprio(0); } while (0)
; #define PG8_BAR __builtin_amdgcn_s_barrier()
; template <class Epi>
; __device__ __forceinline__ void gemm_phase(LAS unsigned char* lds, const Gemm g, const StaticOrder& S, const Epi& E, const int tid) {
;     ...
;         const bool has_next = S.next(ui + 1, nxt);
;         const char* nA = has_next ? (const char*)g.A + (size_t)nxt.pm * tstep : cA; const char* nB = has_next ? (const char*)g.Bt + (size_t)nxt.pn * tstep : cB;
;         for (int t = 0; t < nt; t += 2) {
;             const bool last = (t == nt - 2);
;             const char* a1 = cA + (size_t)(t + 1) * kstep;
;             const char* a2 = last ? nA : cA + (size_t)(t + 2) * kstep; const char* b2 = last ? nB : cB + (size_t)(t + 2) * kstep;
;             const char* a3 = a2 + kstep; const char* b3 = b2 + kstep;
;             PG8_LDB(B0, 0, 0); PG8_SCHED; PG8_LDA(At, 0, 0); PG8_STAGE(PG8_SA(1, 1), a1 + hstep, voffA);
;             PG8_WAIT_L(8); PG8_BAR; PG8_WAIT_L(0); PG8_MMA(0, 0, At, B0); PG8_BAR; PG8_SCHED;
;     ...
; #pragma unroll
;         for (int a = 0; a < 2; ++a)
; #pragma unroll
;             for (int b = 0; b < 2; ++b)
; #pragma unroll
;                 for (int m = 0; m < 4; ++m)
; #pragma unroll
;                     for (int n = 0; n < 2; ++n) acc[a][b][m][n] = (f32x4){0.f, 0.f, 0.f, 0.f};
;         cur = nxt; cA = nA; cB = nB; ++ui;
.LBB0_118:
	s_ashr_i32 s13, s12, 31
	v_cmp_lt_i64_e32 vcc, s[14:15], v[146:147]
	s_lshl_b64 s[14:15], s[12:13], 20
	s_add_u32 s14, s0, s14
	s_addc_u32 s15, s1, s15
	s_and_b64 s[16:17], vcc, exec
	s_cselect_b32 s13, s15, s21
	s_cselect_b32 s44, s14, s20
	s_ashr_i32 s11, s10, 31
	s_lshl_b64 s[16:17], s[10:11], 20
	s_add_u32 s16, s24, s16
	s_addc_u32 s17, s25, s17
	s_and_b64 s[22:23], vcc, exec
	s_cselect_b32 s11, s17, s19
	s_cselect_b32 s45, s16, s18
	s_add_u32 s47, s18, 0x100
	s_addc_u32 s48, s19, 0
	s_add_u32 s18, s20, 0x80080
	v_mov_b32_e32 v2, 0
	s_addc_u32 s19, s21, 0
	s_mov_b32 s49, -2
	v_mov_b32_e32 v3, v2
	v_mov_b32_e32 v4, v2
	v_mov_b32_e32 v5, v2
	v_mov_b32_e32 v6, v2
	v_mov_b32_e32 v7, v2
	v_mov_b32_e32 v8, v2
	v_mov_b32_e32 v9, v2
	v_mov_b32_e32 v18, v2
	v_mov_b32_e32 v19, v2
	v_mov_b32_e32 v20, v2
	v_mov_b32_e32 v21, v2
	v_mov_b32_e32 v22, v2
	v_mov_b32_e32 v23, v2
	v_mov_b32_e32 v24, v2
	v_mov_b32_e32 v25, v2
	v_mov_b32_e32 v34, v2
	v_mov_b32_e32 v35, v2
	v_mov_b32_e32 v36, v2
	v_mov_b32_e32 v37, v2
	v_mov_b32_e32 v38, v2
	v_mov_b32_e32 v39, v2
	v_mov_b32_e32 v40, v2
	v_mov_b32_e32 v41, v2
	v_mov_b32_e32 v66, v2
	v_mov_b32_e32 v67, v2
	v_mov_b32_e32 v68, v2
	v_mov_b32_e32 v69, v2
	v_mov_b32_e32 v70, v2
	v_mov_b32_e32 v71, v2
	v_mov_b32_e32 v72, v2
	v_mov_b32_e32 v73, v2
	v_mov_b32_e32 v10, v2
	v_mov_b32_e32 v11, v2
	v_mov_b32_e32 v12, v2
	v_mov_b32_e32 v13, v2
	v_mov_b32_e32 v14, v2
	v_mov_b32_e32 v15, v2
	v_mov_b32_e32 v16, v2
	v_mov_b32_e32 v17, v2
	v_mov_b32_e32 v26, v2
	v_mov_b32_e32 v27, v2
	v_mov_b32_e32 v28, v2
	v_mov_b32_e32 v29, v2
	v_mov_b32_e32 v30, v2
	v_mov_b32_e32 v31, v2
	v_mov_b32_e32 v32, v2
	v_mov_b32_e32 v33, v2
	v_mov_b32_e32 v50, v2
	v_mov_b32_e32 v51, v2
	v_mov_b32_e32 v52, v2
	v_mov_b32_e32 v53, v2
	v_mov_b32_e32 v54, v2
	v_mov_b32_e32 v55, v2
	v_mov_b32_e32 v56, v2
	v_mov_b32_e32 v57, v2
	v_mov_b32_e32 v74, v2
	v_mov_b32_e32 v75, v2
	v_mov_b32_e32 v76, v2
	v_mov_b32_e32 v77, v2
	v_mov_b32_e32 v78, v2
	v_mov_b32_e32 v79, v2
	v_mov_b32_e32 v80, v2
	v_mov_b32_e32 v81, v2
	v_mov_b32_e32 v82, v2
	v_mov_b32_e32 v83, v2
	v_mov_b32_e32 v84, v2
	v_mov_b32_e32 v85, v2
	v_mov_b32_e32 v86, v2
	v_mov_b32_e32 v87, v2
	v_mov_b32_e32 v88, v2
	v_mov_b32_e32 v89, v2
	v_mov_b32_e32 v98, v2
	v_mov_b32_e32 v99, v2
	v_mov_b32_e32 v100, v2
	v_mov_b32_e32 v101, v2
	v_mov_b32_e32 v102, v2
	v_mov_b32_e32 v103, v2
	v_mov_b32_e32 v104, v2
	v_mov_b32_e32 v105, v2
	v_mov_b32_e32 v114, v2
	v_mov_b32_e32 v115, v2
	v_mov_b32_e32 v116, v2
	v_mov_b32_e32 v117, v2
	v_mov_b32_e32 v118, v2
	v_mov_b32_e32 v119, v2
	v_mov_b32_e32 v120, v2
	v_mov_b32_e32 v121, v2
	v_mov_b32_e32 v130, v2
	v_mov_b32_e32 v131, v2
	v_mov_b32_e32 v132, v2
	v_mov_b32_e32 v133, v2
	v_mov_b32_e32 v134, v2
	v_mov_b32_e32 v135, v2
	v_mov_b32_e32 v136, v2
	v_mov_b32_e32 v137, v2
	v_mov_b32_e32 v90, v2
	v_mov_b32_e32 v91, v2
	v_mov_b32_e32 v92, v2
	v_mov_b32_e32 v93, v2
	v_mov_b32_e32 v94, v2
	v_mov_b32_e32 v95, v2
	v_mov_b32_e32 v96, v2
	v_mov_b32_e32 v97, v2
	v_mov_b32_e32 v106, v2
	v_mov_b32_e32 v107, v2
	v_mov_b32_e32 v108, v2
	v_mov_b32_e32 v109, v2
	v_mov_b32_e32 v110, v2
	v_mov_b32_e32 v111, v2
	v_mov_b32_e32 v112, v2
	v_mov_b32_e32 v113, v2
	v_mov_b32_e32 v122, v2
	v_mov_b32_e32 v123, v2
	v_mov_b32_e32 v124, v2
	v_mov_b32_e32 v125, v2
	v_mov_b32_e32 v126, v2
	v_mov_b32_e32 v127, v2
	v_mov_b32_e32 v128, v2
	v_mov_b32_e32 v129, v2
	s_waitcnt vmcnt(0)
	v_mov_b32_e32 v138, v2
	v_mov_b32_e32 v139, v2
	v_mov_b32_e32 v140, v2
	v_mov_b32_e32 v141, v2
	v_mov_b32_e32 v142, v2
	v_mov_b32_e32 v143, v2
	v_mov_b32_e32 v144, v2
	v_mov_b32_e32 v145, v2
	v_readfirstlane_b32 s32, v158
	s_cmpk_lt_u32 s32, 0x100
	s_cbranch_scc1 .Lgprio3
	s_setprio 1
.Lgprio3:
.LBB0_119:
	s_add_u32 s20, s18, 0xfff80080
	s_addc_u32 s21, s19, -1
	s_add_i32 s50, 0, 0x10000
	v_add_u32_e32 v62, s50, v173
	ds_read_b128 v[42:45], v62
	ds_read_b128 v[46:49], v62 offset:1024
	ds_read_b128 v[58:61], v62 offset:2048
	ds_read_b128 v[62:65], v62 offset:3072
	s_cmp_eq_u32 s49, 28
	s_cselect_b32 s23, s13, s21
	s_cselect_b32 s22, s44, s20
	s_cselect_b32 s21, s11, s48
	s_cselect_b32 s20, s45, s47
	v_lshl_add_u64 v[170:171], s[18:19], 0, v[168:169]
	s_add_i32 m0, s3, 0xc000
	ds_read_b128 v[176:179], v174
	ds_read_b128 v[180:183], v174 offset:1024
	ds_read_b128 v[184:187], v174 offset:2048
	ds_read_b128 v[188:191], v174 offset:3072
	ds_read_b128 v[192:195], v174 offset:4096
	ds_read_b128 v[196:199], v174 offset:5120
	ds_read_b128 v[210:213], v174 offset:6144
	ds_read_b128 v[214:217], v174 offset:7168
	global_load_lds_dwordx4 v[170:171], off
	v_lshl_add_u64 v[170:171], s[18:19], 0, v[166:167]
	s_add_i32 m0, s3, 0xe000
	s_nop 0
	global_load_lds_dwordx4 v[170:171], off
	s_waitcnt lgkmcnt(8)
	s_barrier
	s_waitcnt lgkmcnt(0)
	v_mfma_f32_16x16x32_bf16 v[142:145], v[42:45], v[176:179], v[142:145]
	v_mfma_f32_16x16x32_bf16 v[138:141], v[58:61], v[176:179], v[138:141]
	v_mfma_f32_16x16x32_bf16 v[126:129], v[42:45], v[184:187], v[126:129]
	v_mfma_f32_16x16x32_bf16 v[122:125], v[58:61], v[184:187], v[122:125]
	v_mfma_f32_16x16x32_bf16 v[110:113], v[42:45], v[192:195], v[110:113]
	v_mfma_f32_16x16x32_bf16 v[106:109], v[58:61], v[192:195], v[106:109]
	v_mfma_f32_16x16x32_bf16 v[94:97], v[42:45], v[210:213], v[94:97]
	v_mfma_f32_16x16x32_bf16 v[90:93], v[58:61], v[210:213], v[90:93]
	v_mfma_f32_16x16x32_bf16 v[142:145], v[46:49], v[180:183], v[142:145]
	v_mfma_f32_16x16x32_bf16 v[138:141], v[62:65], v[180:183], v[138:141]
	v_mfma_f32_16x16x32_bf16 v[126:129], v[46:49], v[188:191], v[126:129]
	v_mfma_f32_16x16x32_bf16 v[122:125], v[62:65], v[188:191], v[122:125]
	v_mfma_f32_16x16x32_bf16 v[110:113], v[46:49], v[196:199], v[110:113]
	v_mfma_f32_16x16x32_bf16 v[106:109], v[62:65], v[196:199], v[106:109]
	v_mfma_f32_16x16x32_bf16 v[94:97], v[46:49], v[214:217], v[94:97]
	v_mfma_f32_16x16x32_bf16 v[90:93], v[62:65], v[214:217], v[90:93]
	s_barrier
; #define PG8_STAGE(bufoff, gbase, voff) do { _Pragma("unroll") for (int _i = 0; _i < 2; ++_i) \
;         __builtin_amdgcn_global_load_lds((const unsigned*)((const char*)(gbase) + (voff)[_i]), (LAS unsigned*)(lds + (bufoff) + ldsw + _i * 8192), 16, 0, 0); } while (0)
; #define PG8_LDA(dst, b, h) do { _Pragma("unroll") for (int m = 0; m < 4; ++m) _Pragma("unroll") for (int k = 0; k < 2; ++k) dst[m][k] = *(const LAS bf16x8*)(lds + PG8_SA(b, h) + aoff + m * 2048 + k * 1024); } while (0)
; #define PG8_LDB(dst, b, h) do { _Pragma("unroll") for (int n = 0; n < 2; ++n) _Pragma("unroll") for (int k = 0; k < 2; ++k) dst[n][k] = *(const LAS bf16x8*)(lds + PG8_SB(b, h) + boff + n * 2048 + k * 1024); } while (0)
; #define PG8_MMA(ai, bj, At, Bt) do { __builtin_amdgcn_s_setprio(1); _Pragma("unroll") for (int m = 0; m < 4; ++m) _Pragma("unroll") for (int n = 0; n < 2; ++n) _Pragma("unroll") for (int k = 0; k < 2; ++k) \
;         acc[ai][bj][m][n] = __builtin_amdgcn_mfma_f32_16x16x32_bf16(Bt[n][k], At[m][k], acc[ai][bj][m][n], 0, 0, 0); __builtin_amdgcn_s_setprio(0); } while (0)
; #define PG8_WAIT_V(n) asm volatile("s_waitcnt vmcnt(" #n ")" ::: "memory")
; #define PG8_WAIT_L(n) asm volatile("s_waitcnt lgkmcnt(" #n ")" ::: "memory")
; #define PG8_BAR __builtin_amdgcn_s_barrier()
; #define PG8_SCHED __builtin_amdgcn_sched_barrier(0)
; template <class Epi>
; __device__ __forceinline__ void gemm_phase(LAS unsigned char* lds, const Gemm g, const StaticOrder& S, const Epi& E, const int tid) {
;     ...
;             PG8_LDB(B1, 0, 1); PG8_STAGE(PG8_SB(0, 0), b2, voffB);
;             PG8_BAR; PG8_WAIT_L(0); PG8_MMA(0, 1, At, B1); PG8_BAR;
;             PG8_LDA(At, 0, 1); PG8_STAGE(PG8_SA(0, 0), a2, voffA);
;             PG8_BAR; PG8_WAIT_L(0); PG8_MMA(1, 0, At, B0); PG8_BAR; PG8_SCHED;
;             PG8_STAGE(PG8_SB(0, 1), b2 + hstep, voffB);
;             PG8_WAIT_V(6); PG8_BAR; PG8_MMA(1, 1, At, B1); PG8_BAR;
;             PG8_LDB(B0, 1, 0); PG8_SCHED; PG8_LDA(At, 1, 0); PG8_STAGE(PG8_SA(0, 1), a2 + hstep, voffA);
;             PG8_WAIT_L(8); PG8_BAR; PG8_WAIT_L(0); PG8_MMA(0, 0, At, B0); PG8_BAR; PG8_SCHED;
	s_add_i32 s54, 0, 0x14000
	v_add_u32_e32 v170, s54, v173
	s_add_i32 s50, s50, s31
	ds_read_b128 v[218:221], v170
	ds_read_b128 v[222:225], v170 offset:1024
	ds_read_b128 v[226:229], v170 offset:2048
	ds_read_b128 v[230:233], v170 offset:3072
	v_lshl_add_u64 v[170:171], s[20:21], 0, v[0:1]
	s_mov_b32 m0, s50
	v_lshl_add_u64 v[200:201], s[20:21], 0, v[164:165]
	global_load_lds_dwordx4 v[170:171], off
	s_add_i32 m0, s50, 0x2000
	s_nop 0
	global_load_lds_dwordx4 v[200:201], off
	s_barrier
	s_waitcnt lgkmcnt(0)
	v_mfma_f32_16x16x32_bf16 v[134:137], v[218:221], v[176:179], v[134:137]
	v_mfma_f32_16x16x32_bf16 v[130:133], v[226:229], v[176:179], v[130:133]
	v_mfma_f32_16x16x32_bf16 v[118:121], v[218:221], v[184:187], v[118:121]
	v_mfma_f32_16x16x32_bf16 v[114:117], v[226:229], v[184:187], v[114:117]
	v_mfma_f32_16x16x32_bf16 v[102:105], v[218:221], v[192:195], v[102:105]
	v_mfma_f32_16x16x32_bf16 v[98:101], v[226:229], v[192:195], v[98:101]
	v_mfma_f32_16x16x32_bf16 v[86:89], v[218:221], v[210:213], v[86:89]
	v_mfma_f32_16x16x32_bf16 v[82:85], v[226:229], v[210:213], v[82:85]
	v_mfma_f32_16x16x32_bf16 v[134:137], v[222:225], v[180:183], v[134:137]
	v_mfma_f32_16x16x32_bf16 v[130:133], v[230:233], v[180:183], v[130:133]
	v_mfma_f32_16x16x32_bf16 v[118:121], v[222:225], v[188:191], v[118:121]
	v_mfma_f32_16x16x32_bf16 v[114:117], v[230:233], v[188:191], v[114:117]
	v_mfma_f32_16x16x32_bf16 v[102:105], v[222:225], v[196:199], v[102:105]
	v_mfma_f32_16x16x32_bf16 v[98:101], v[230:233], v[196:199], v[98:101]
	v_mfma_f32_16x16x32_bf16 v[86:89], v[222:225], v[214:217], v[86:89]
	v_mfma_f32_16x16x32_bf16 v[82:85], v[230:233], v[214:217], v[82:85]
	s_mov_b32 m0, s3
	v_lshl_add_u64 v[234:235], s[22:23], 0, v[160:161]
	s_barrier
	ds_read_b128 v[176:179], v174 offset:16384
	ds_read_b128 v[180:183], v174 offset:17408
	ds_read_b128 v[184:187], v174 offset:18432
	ds_read_b128 v[188:191], v174 offset:19456
	ds_read_b128 v[192:195], v174 offset:20480
	ds_read_b128 v[196:199], v174 offset:21504
	ds_read_b128 v[210:213], v174 offset:22528
	ds_read_b128 v[214:217], v174 offset:23552
	global_load_lds_dwordx4 v[234:235], off
	v_lshl_add_u64 v[236:237], s[22:23], 0, v[162:163]
	s_mov_b32 m0, s34
	s_nop 0
	global_load_lds_dwordx4 v[236:237], off
	s_barrier
	s_waitcnt lgkmcnt(0)
	v_mfma_f32_16x16x32_bf16 v[78:81], v[42:45], v[176:179], v[78:81]
	v_mfma_f32_16x16x32_bf16 v[74:77], v[58:61], v[176:179], v[74:77]
	v_mfma_f32_16x16x32_bf16 v[54:57], v[42:45], v[184:187], v[54:57]
	v_mfma_f32_16x16x32_bf16 v[50:53], v[58:61], v[184:187], v[50:53]
	v_mfma_f32_16x16x32_bf16 v[30:33], v[42:45], v[192:195], v[30:33]
	v_mfma_f32_16x16x32_bf16 v[26:29], v[58:61], v[192:195], v[26:29]
	v_mfma_f32_16x16x32_bf16 v[14:17], v[42:45], v[210:213], v[14:17]
	v_mfma_f32_16x16x32_bf16 v[10:13], v[58:61], v[210:213], v[10:13]
	v_mfma_f32_16x16x32_bf16 v[78:81], v[46:49], v[180:183], v[78:81]
	v_mfma_f32_16x16x32_bf16 v[74:77], v[62:65], v[180:183], v[74:77]
	v_mfma_f32_16x16x32_bf16 v[54:57], v[46:49], v[188:191], v[54:57]
	v_mfma_f32_16x16x32_bf16 v[50:53], v[62:65], v[188:191], v[50:53]
	v_mfma_f32_16x16x32_bf16 v[30:33], v[46:49], v[196:199], v[30:33]
	v_mfma_f32_16x16x32_bf16 v[26:29], v[62:65], v[196:199], v[26:29]
	v_mfma_f32_16x16x32_bf16 v[14:17], v[46:49], v[214:217], v[14:17]
	v_mfma_f32_16x16x32_bf16 v[10:13], v[62:65], v[214:217], v[10:13]
	s_barrier
	s_add_u32 s52, s20, 0x80000
	s_addc_u32 s53, s21, 0
	s_add_i32 s50, s54, s31
	v_lshl_add_u64 v[42:43], s[52:53], 0, v[0:1]
	s_mov_b32 m0, s50
	s_nop 0
	global_load_lds_dwordx4 v[42:43], off
	v_lshl_add_u64 v[42:43], s[52:53], 0, v[164:165]
	s_add_i32 m0, s50, 0x2000
	s_nop 0
	global_load_lds_dwordx4 v[42:43], off
	s_waitcnt vmcnt(6)
	s_barrier
	v_mfma_f32_16x16x32_bf16 v[38:41], v[218:221], v[184:187], v[38:41]
	v_mfma_f32_16x16x32_bf16 v[34:37], v[226:229], v[184:187], v[34:37]
	v_mfma_f32_16x16x32_bf16 v[22:25], v[218:221], v[192:195], v[22:25]
	v_mfma_f32_16x16x32_bf16 v[18:21], v[226:229], v[192:195], v[18:21]
	v_mfma_f32_16x16x32_bf16 v[6:9], v[218:221], v[210:213], v[6:9]
	v_mfma_f32_16x16x32_bf16 v[2:5], v[226:229], v[210:213], v[2:5]
	v_mfma_f32_16x16x32_bf16 v[42:45], v[218:221], v[176:179], v[70:73]
	v_mfma_f32_16x16x32_bf16 v[46:49], v[226:229], v[176:179], v[66:69]
	v_mfma_f32_16x16x32_bf16 v[38:41], v[222:225], v[188:191], v[38:41]
	v_mfma_f32_16x16x32_bf16 v[34:37], v[230:233], v[188:191], v[34:37]
	v_mfma_f32_16x16x32_bf16 v[22:25], v[222:225], v[196:199], v[22:25]
	v_mfma_f32_16x16x32_bf16 v[18:21], v[230:233], v[196:199], v[18:21]
	v_mfma_f32_16x16x32_bf16 v[6:9], v[222:225], v[214:217], v[6:9]
	v_mfma_f32_16x16x32_bf16 v[2:5], v[230:233], v[214:217], v[2:5]
	v_mfma_f32_16x16x32_bf16 v[42:45], v[222:225], v[180:183], v[42:45]
	v_mfma_f32_16x16x32_bf16 v[46:49], v[230:233], v[180:183], v[46:49]
	s_add_i32 s50, 0, 0x18000
	v_add_u32_e32 v70, s50, v173
	s_barrier
	ds_read_b128 v[58:61], v70
	ds_read_b128 v[62:65], v70 offset:1024
	ds_read_b128 v[66:69], v70 offset:2048
	ds_read_b128 v[70:73], v70 offset:3072
	s_add_u32 s22, s22, 0x80000
	s_addc_u32 s23, s23, 0
	s_mov_b32 m0, s35
	v_lshl_add_u64 v[218:219], s[22:23], 0, v[160:161]
	ds_read_b128 v[176:179], v174 offset:32768
	ds_read_b128 v[180:183], v174 offset:33792
	ds_read_b128 v[184:187], v174 offset:34816
	ds_read_b128 v[188:191], v174 offset:35840
	ds_read_b128 v[192:195], v174 offset:36864
	ds_read_b128 v[196:199], v174 offset:37888
	ds_read_b128 v[210:213], v174 offset:38912
	ds_read_b128 v[214:217], v174 offset:39936
	global_load_lds_dwordx4 v[218:219], off
	v_lshl_add_u64 v[218:219], s[22:23], 0, v[162:163]
	s_mov_b32 m0, s36
	s_nop 0
	global_load_lds_dwordx4 v[218:219], off
	s_waitcnt lgkmcnt(8)
	s_barrier
; #define PG8_STAGE(bufoff, gbase, voff) do { _Pragma("unroll") for (int _i = 0; _i < 2; ++_i) \
;         __builtin_amdgcn_global_load_lds((const unsigned*)((const char*)(gbase) + (voff)[_i]), (LAS unsigned*)(lds + (bufoff) + ldsw + _i * 8192), 16, 0, 0); } while (0)
; #define PG8_LDA(dst, b, h) do { _Pragma("unroll") for (int m = 0; m < 4; ++m) _Pragma("unroll") for (int k = 0; k < 2; ++k) dst[m][k] = *(const LAS bf16x8*)(lds + PG8_SA(b, h) + aoff + m * 2048 + k * 1024); } while (0)
; #define PG8_LDB(dst, b, h) do { _Pragma("unroll") for (int n = 0; n < 2; ++n) _Pragma("unroll") for (int k = 0; k < 2; ++k) dst[n][k] = *(const LAS bf16x8*)(lds + PG8_SB(b, h) + boff + n * 2048 + k * 1024); } while (0)
; #define PG8_MMA(ai, bj, At, Bt) do { __builtin_amdgcn_s_setprio(1); _Pragma("unroll") for (int m = 0; m < 4; ++m) _Pragma("unroll") for (int n = 0; n < 2; ++n) _Pragma("unroll") for (int k = 0; k < 2; ++k) \
;         acc[ai][bj][m][n] = __builtin_amdgcn_mfma_f32_16x16x32_bf16(Bt[n][k], At[m][k], acc[ai][bj][m][n], 0, 0, 0); __builtin_amdgcn_s_setprio(0); } while (0)
; #define PG8_WAIT_V(n) asm volatile("s_waitcnt vmcnt(" #n ")" ::: "memory")
; #define PG8_WAIT_L(n) asm volatile("s_waitcnt lgkmcnt(" #n ")" ::: "memory")
; #define PG8_BAR __builtin_amdgcn_s_barrier()
; #define PG8_SCHED __builtin_amdgcn_sched_barrier(0)
; template <class Epi>
; __device__ __forceinline__ void gemm_phase(LAS unsigned char* lds, const Gemm g, const StaticOrder& S, const Epi& E, const int tid) {
;     ...
;             PG8_WAIT_L(8); PG8_BAR; PG8_WAIT_L(0); PG8_MMA(0, 0, At, B0); PG8_BAR; PG8_SCHED;
;             PG8_LDB(B1, 1, 1); PG8_STAGE(PG8_SB(1, 0), b3, voffB);
;             PG8_BAR; PG8_WAIT_L(0); PG8_MMA(0, 1, At, B1); PG8_BAR;
;             PG8_LDA(At, 1, 1); PG8_STAGE(PG8_SA(1, 0), a3, voffA);
;             PG8_BAR; PG8_WAIT_L(0); PG8_MMA(1, 0, At, B0); PG8_BAR; PG8_SCHED;
;             PG8_STAGE(PG8_SB(1, 1), b3 + hstep, voffB);
;             PG8_WAIT_V(6); PG8_BAR; PG8_MMA(1, 1, At, B1); PG8_BAR;
	s_waitcnt lgkmcnt(0)
	v_mfma_f32_16x16x32_bf16 v[142:145], v[58:61], v[176:179], v[142:145]
	v_mfma_f32_16x16x32_bf16 v[138:141], v[66:69], v[176:179], v[138:141]
	v_mfma_f32_16x16x32_bf16 v[126:129], v[58:61], v[184:187], v[126:129]
	v_mfma_f32_16x16x32_bf16 v[122:125], v[66:69], v[184:187], v[122:125]
	v_mfma_f32_16x16x32_bf16 v[110:113], v[58:61], v[192:195], v[110:113]
	v_mfma_f32_16x16x32_bf16 v[106:109], v[66:69], v[192:195], v[106:109]
	v_mfma_f32_16x16x32_bf16 v[94:97], v[58:61], v[210:213], v[94:97]
	v_mfma_f32_16x16x32_bf16 v[90:93], v[66:69], v[210:213], v[90:93]
	v_mfma_f32_16x16x32_bf16 v[142:145], v[62:65], v[180:183], v[142:145]
	v_mfma_f32_16x16x32_bf16 v[138:141], v[70:73], v[180:183], v[138:141]
	v_mfma_f32_16x16x32_bf16 v[126:129], v[62:65], v[188:191], v[126:129]
	v_mfma_f32_16x16x32_bf16 v[122:125], v[70:73], v[188:191], v[122:125]
	v_mfma_f32_16x16x32_bf16 v[110:113], v[62:65], v[196:199], v[110:113]
	v_mfma_f32_16x16x32_bf16 v[106:109], v[70:73], v[196:199], v[106:109]
	v_mfma_f32_16x16x32_bf16 v[94:97], v[62:65], v[214:217], v[94:97]
	v_mfma_f32_16x16x32_bf16 v[90:93], v[70:73], v[214:217], v[90:93]
	s_barrier
	s_add_i32 s22, 0, 0x1c000
	s_add_i32 s23, s50, s31
	v_add_u32_e32 v175, s22, v173
	v_lshl_add_u64 v[170:171], v[170:171], 0, s[56:57]
	s_mov_b32 m0, s23
	ds_read_b128 v[218:221], v175
	ds_read_b128 v[222:225], v175 offset:1024
	ds_read_b128 v[226:229], v175 offset:2048
	ds_read_b128 v[230:233], v175 offset:3072
	global_load_lds_dwordx4 v[170:171], off
	v_lshl_add_u64 v[170:171], v[200:201], 0, s[56:57]
	s_add_i32 m0, s23, 0x2000
	s_nop 0
	global_load_lds_dwordx4 v[170:171], off
	s_barrier
	s_waitcnt lgkmcnt(0)
	v_mfma_f32_16x16x32_bf16 v[134:137], v[218:221], v[176:179], v[134:137]
	v_mfma_f32_16x16x32_bf16 v[130:133], v[226:229], v[176:179], v[130:133]
	v_mfma_f32_16x16x32_bf16 v[118:121], v[218:221], v[184:187], v[118:121]
	v_mfma_f32_16x16x32_bf16 v[114:117], v[226:229], v[184:187], v[114:117]
	v_mfma_f32_16x16x32_bf16 v[102:105], v[218:221], v[192:195], v[102:105]
	v_mfma_f32_16x16x32_bf16 v[98:101], v[226:229], v[192:195], v[98:101]
	v_mfma_f32_16x16x32_bf16 v[86:89], v[218:221], v[210:213], v[86:89]
	v_mfma_f32_16x16x32_bf16 v[82:85], v[226:229], v[210:213], v[82:85]
	v_mfma_f32_16x16x32_bf16 v[134:137], v[222:225], v[180:183], v[134:137]
	v_mfma_f32_16x16x32_bf16 v[130:133], v[230:233], v[180:183], v[130:133]
	v_mfma_f32_16x16x32_bf16 v[118:121], v[222:225], v[188:191], v[118:121]
	v_mfma_f32_16x16x32_bf16 v[114:117], v[230:233], v[188:191], v[114:117]
	v_mfma_f32_16x16x32_bf16 v[102:105], v[222:225], v[196:199], v[102:105]
	v_mfma_f32_16x16x32_bf16 v[98:101], v[230:233], v[196:199], v[98:101]
	v_mfma_f32_16x16x32_bf16 v[86:89], v[222:225], v[214:217], v[86:89]
	v_mfma_f32_16x16x32_bf16 v[82:85], v[230:233], v[214:217], v[82:85]
	s_mov_b32 m0, s39
	v_lshl_add_u64 v[170:171], v[234:235], 0, s[56:57]
	s_barrier
	ds_read_b128 v[176:179], v174 offset:49152
	ds_read_b128 v[180:183], v174 offset:50176
	ds_read_b128 v[184:187], v174 offset:51200
	ds_read_b128 v[188:191], v174 offset:52224
	ds_read_b128 v[192:195], v174 offset:53248
	ds_read_b128 v[196:199], v174 offset:54272
	ds_read_b128 v[210:213], v174 offset:55296
	ds_read_b128 v[214:217], v174 offset:56320
	global_load_lds_dwordx4 v[170:171], off
	v_lshl_add_u64 v[170:171], v[236:237], 0, s[56:57]
	s_mov_b32 m0, s40
	s_nop 0
	global_load_lds_dwordx4 v[170:171], off
	s_barrier
	s_waitcnt lgkmcnt(0)
	v_mfma_f32_16x16x32_bf16 v[78:81], v[58:61], v[176:179], v[78:81]
	v_mfma_f32_16x16x32_bf16 v[74:77], v[66:69], v[176:179], v[74:77]
	v_mfma_f32_16x16x32_bf16 v[54:57], v[58:61], v[184:187], v[54:57]
	v_mfma_f32_16x16x32_bf16 v[50:53], v[66:69], v[184:187], v[50:53]
	v_mfma_f32_16x16x32_bf16 v[30:33], v[58:61], v[192:195], v[30:33]
	v_mfma_f32_16x16x32_bf16 v[26:29], v[66:69], v[192:195], v[26:29]
	v_mfma_f32_16x16x32_bf16 v[14:17], v[58:61], v[210:213], v[14:17]
	v_mfma_f32_16x16x32_bf16 v[10:13], v[66:69], v[210:213], v[10:13]
	v_mfma_f32_16x16x32_bf16 v[78:81], v[62:65], v[180:183], v[78:81]
	v_mfma_f32_16x16x32_bf16 v[74:77], v[70:73], v[180:183], v[74:77]
	v_mfma_f32_16x16x32_bf16 v[54:57], v[62:65], v[188:191], v[54:57]
	v_mfma_f32_16x16x32_bf16 v[50:53], v[70:73], v[188:191], v[50:53]
	v_mfma_f32_16x16x32_bf16 v[30:33], v[62:65], v[196:199], v[30:33]
	v_mfma_f32_16x16x32_bf16 v[26:29], v[70:73], v[196:199], v[26:29]
	v_mfma_f32_16x16x32_bf16 v[14:17], v[62:65], v[214:217], v[14:17]
	v_mfma_f32_16x16x32_bf16 v[10:13], v[70:73], v[214:217], v[10:13]
	s_barrier
	s_add_u32 s20, s20, 0x80080
	s_addc_u32 s21, s21, 0
	s_add_i32 s22, s22, s31
	v_lshl_add_u64 v[58:59], s[20:21], 0, v[0:1]
	s_mov_b32 m0, s22
	s_nop 0
	global_load_lds_dwordx4 v[58:59], off
	v_lshl_add_u64 v[58:59], s[20:21], 0, v[164:165]
	s_add_i32 m0, s22, 0x2000
	s_nop 0
	global_load_lds_dwordx4 v[58:59], off
	s_waitcnt vmcnt(6)
	s_barrier
	v_mfma_f32_16x16x32_bf16 v[42:45], v[218:221], v[176:179], v[42:45]
	v_mfma_f32_16x16x32_bf16 v[70:73], v[222:225], v[180:183], v[42:45]
	v_mfma_f32_16x16x32_bf16 v[42:45], v[226:229], v[176:179], v[46:49]
	v_mfma_f32_16x16x32_bf16 v[38:41], v[218:221], v[184:187], v[38:41]
	v_mfma_f32_16x16x32_bf16 v[34:37], v[226:229], v[184:187], v[34:37]
	v_mfma_f32_16x16x32_bf16 v[22:25], v[218:221], v[192:195], v[22:25]
	v_mfma_f32_16x16x32_bf16 v[18:21], v[226:229], v[192:195], v[18:21]
	v_mfma_f32_16x16x32_bf16 v[6:9], v[218:221], v[210:213], v[6:9]
	v_mfma_f32_16x16x32_bf16 v[2:5], v[226:229], v[210:213], v[2:5]
	v_mfma_f32_16x16x32_bf16 v[66:69], v[230:233], v[180:183], v[42:45]
	v_mfma_f32_16x16x32_bf16 v[38:41], v[222:225], v[188:191], v[38:41]
	v_mfma_f32_16x16x32_bf16 v[34:37], v[230:233], v[188:191], v[34:37]
	v_mfma_f32_16x16x32_bf16 v[22:25], v[222:225], v[196:199], v[22:25]
	v_mfma_f32_16x16x32_bf16 v[18:21], v[230:233], v[196:199], v[18:21]
	v_mfma_f32_16x16x32_bf16 v[6:9], v[222:225], v[214:217], v[6:9]
	v_mfma_f32_16x16x32_bf16 v[2:5], v[230:233], v[214:217], v[2:5]
	s_add_i32 s49, s49, 2
	s_add_u32 s47, s47, 0x100
	s_addc_u32 s48, s48, 0
	s_add_u32 s18, s18, 0x100
	s_addc_u32 s19, s19, 0
	s_cmp_gt_u32 s49, 29
	s_barrier
; __device__ __forceinline__ unsigned pk2(float lo, float hi) { f32x2 v = {lo, hi}; return __builtin_bit_cast(unsigned, __builtin_convertvector(v, bf16x2_t)); }
; __device__ __forceinline__ float bf_lo(unsigned w) { return __uint_as_float(w << 16); }
; __device__ __forceinline__ float bf_hi(unsigned w) { return __uint_as_float(w & 0xffff0000u); }
;     __device__ __forceinline__ void operator()(const f32x4 (&acc)[2][2][4][2], const Unit& u, int wr, int wc, int fr, int fq) const {
;         asm volatile("" : "+v"(fr), "+v"(fq));
;         const int row0 = u.pm * BM + wr * 64 + fr, col0 = u.pn * BM + wc * 32 + 8 * fq;
;         const float* gp = gate + (size_t)(u.pm >> 5) * 12288 + col0;
;         f32x4 gv[2][2];
; #pragma unroll
;         for (int bj = 0; bj < 2; ++bj)
; #pragma unroll
;             for (int n = 0; n < 2; ++n) gv[bj][n] = *(const f32x4*)(gp + bj * HALF + 4 * n);
; #pragma unroll
;         for (int ai = 0; ai < 2; ++ai)
; #pragma unroll
;             for (int m = 0; m < 4; ++m) {
;                 const size_t ro = (size_t)(row0 + ai * HALF + m * 16) * DM + col0;
; #pragma unroll
;                 for (int bj = 0; bj < 2; ++bj) {
;                     f32x4 r0, r1;
;                     if (RB) { const u32x4 rw = *(const u32x4*)((const bf16_t*)resid + ro + bj * HALF);
;                         r0 = (f32x4){bf_lo(rw.x), bf_hi(rw.x), bf_lo(rw.y), bf_hi(rw.y)}; r1 = (f32x4){bf_lo(rw.z), bf_hi(rw.z), bf_lo(rw.w), bf_hi(rw.w)}; }
;                     else { r0 = *(const f32x4*)((const float*)resid + ro + bj * HALF); r1 = *(const f32x4*)((const float*)resid + ro + bj * HALF + 4); }
;                     const f32x4 v0 = r0 + gv[bj][0] * acc[ai][bj][m][0], v1 = r1 + gv[bj][1] * acc[ai][bj][m][1];
;                     if (OB) { u32x4 w; w.x = pk2(v0[0], v0[1]); w.y = pk2(v0[2], v0[3]); w.z = pk2(v1[0], v1[1]); w.w = pk2(v1[2], v1[3]); *(u32x4*)((bf16_t*)out + ro + bj * HALF) = w; }
;                     else { *(f32x4*)((float*)out + ro + bj * HALF) = v0; *(f32x4*)((float*)out + ro + bj * HALF + 4) = v1; }
;                 }
	s_cbranch_scc0 .LBB0_119
	s_setprio 0
	s_lshl_b32 s11, s2, 8
	s_lshl_b32 s13, s43, 8
	v_mov_b32_e32 v175, v172
	v_mov_b32_e32 v42, v159
	s_add_i32 s11, s11, s37
	s_or_b32 s13, s13, s38
	s_ashr_i32 s2, s2, 5
	s_mov_b32 s43, s10
	v_lshl_add_u32 v170, v42, 3, s13
	s_mul_hi_i32 s13, s2, 0xc000
	s_mul_i32 s2, s2, 0xc000
	v_add_u32_e32 v176, s11, v175
	s_add_u32 s18, s27, s2
	v_ashrrev_i32_e32 v177, 31, v176
	s_addc_u32 s19, s28, s13
	v_ashrrev_i32_e32 v171, 31, v170
	v_lshlrev_b64 v[176:177], 11, v[176:177]
	v_lshl_add_u64 v[46:47], v[170:171], 2, s[18:19]
	v_lshl_add_u64 v[170:171], v[176:177], 0, v[170:171]
	v_lshlrev_b64 v[170:171], 1, v[170:171]
	v_lshl_add_u64 v[180:181], s[8:9], 0, v[170:171]
	global_load_dwordx4 v[58:61], v[46:47], off offset:16
	global_load_dwordx4 v[62:65], v[46:47], off
	global_load_dwordx4 v[42:45], v[46:47], off offset:528
	s_nop 0
	global_load_dwordx4 v[46:49], v[46:47], off offset:512
	s_mov_b64 s[92:93], s[8:9]
	s_mov_b64 s[94:95], s[6:7]
	global_load_dwordx4 v[184:187], v170, s[92:93]
	global_load_dwordx4 v[188:191], v170, s[92:93] offset:256
	s_add_u32 s92, s92, 0x10000
	s_addc_u32 s93, s93, 0
	global_load_dwordx4 v[192:195], v170, s[92:93]
	global_load_dwordx4 v[196:199], v170, s[92:93] offset:256
	s_add_u32 s92, s92, 0x10000
	s_addc_u32 s93, s93, 0
	global_load_dwordx4 v[210:213], v170, s[92:93]
	global_load_dwordx4 v[214:217], v170, s[92:93] offset:256
	s_add_u32 s92, s92, 0x10000
	s_addc_u32 s93, s93, 0
	global_load_dwordx4 v[218:221], v170, s[92:93]
	global_load_dwordx4 v[222:225], v170, s[92:93] offset:256
	s_add_u32 s92, s92, 0x50000
	s_addc_u32 s93, s93, 0
	global_load_dwordx4 v[226:229], v170, s[92:93]
	global_load_dwordx4 v[230:233], v170, s[92:93] offset:256
	s_add_u32 s92, s92, 0x10000
	s_addc_u32 s93, s93, 0
	global_load_dwordx4 v[234:237], v170, s[92:93]
	s_waitcnt vmcnt(10)
	v_lshlrev_b32_e32 v176, 16, v184
	v_and_b32_e32 v177, 0xffff0000, v184
	v_lshlrev_b32_e32 v178, 16, v185
	v_and_b32_e32 v179, 0xffff0000, v185
	v_lshlrev_b32_e32 v180, 16, v186
	v_and_b32_e32 v181, 0xffff0000, v186
	v_lshlrev_b32_e32 v182, 16, v187
	v_and_b32_e32 v183, 0xffff0000, v187
	v_pk_fma_f32 v[142:143], v[142:143], v[62:63], v[176:177]
	v_pk_fma_f32 v[144:145], v[144:145], v[64:65], v[178:179]
	v_pk_fma_f32 v[138:139], v[138:139], v[58:59], v[180:181]
	v_pk_fma_f32 v[140:141], v[140:141], v[60:61], v[182:183]
	global_load_dwordx4 v[184:187], v170, s[92:93] offset:256
	v_cvt_pk_bf16_f32 v142, v142, v143
	v_cvt_pk_bf16_f32 v143, v144, v145
	v_cvt_pk_bf16_f32 v144, v138, v139
	v_cvt_pk_bf16_f32 v145, v140, v141
	global_store_dwordx4 v170, v[142:145], s[94:95]
	s_waitcnt vmcnt(11)
	v_lshlrev_b32_e32 v176, 16, v188
	v_and_b32_e32 v177, 0xffff0000, v188
	v_lshlrev_b32_e32 v178, 16, v189
	v_and_b32_e32 v179, 0xffff0000, v189
	v_lshlrev_b32_e32 v180, 16, v190
	v_and_b32_e32 v181, 0xffff0000, v190
	v_lshlrev_b32_e32 v182, 16, v191
	v_and_b32_e32 v183, 0xffff0000, v191
	v_pk_fma_f32 v[134:135], v[134:135], v[46:47], v[176:177]
	v_pk_fma_f32 v[136:137], v[136:137], v[48:49], v[178:179]
	v_pk_fma_f32 v[130:131], v[130:131], v[42:43], v[180:181]
	v_pk_fma_f32 v[132:133], v[132:133], v[44:45], v[182:183]
	s_add_u32 s92, s92, 0x10000
	s_addc_u32 s93, s93, 0
	global_load_dwordx4 v[188:191], v170, s[92:93]
	v_cvt_pk_bf16_f32 v134, v134, v135
	v_cvt_pk_bf16_f32 v135, v136, v137
	v_cvt_pk_bf16_f32 v136, v130, v131
	v_cvt_pk_bf16_f32 v137, v132, v133
	global_store_dwordx4 v170, v[134:137], s[94:95] offset:256
	s_waitcnt vmcnt(12)
	v_lshlrev_b32_e32 v176, 16, v192
	v_and_b32_e32 v177, 0xffff0000, v192
	v_lshlrev_b32_e32 v178, 16, v193
	v_and_b32_e32 v179, 0xffff0000, v193
	v_lshlrev_b32_e32 v180, 16, v194
	v_and_b32_e32 v181, 0xffff0000, v194
	v_lshlrev_b32_e32 v182, 16, v195
	v_and_b32_e32 v183, 0xffff0000, v195
	v_pk_fma_f32 v[126:127], v[126:127], v[62:63], v[176:177]
	v_pk_fma_f32 v[128:129], v[128:129], v[64:65], v[178:179]
	v_pk_fma_f32 v[122:123], v[122:123], v[58:59], v[180:181]
	v_pk_fma_f32 v[124:125], v[124:125], v[60:61], v[182:183]
	global_load_dwordx4 v[192:195], v170, s[92:93] offset:256
	s_add_u32 s94, s94, 0x10000
	s_addc_u32 s95, s95, 0
	v_cvt_pk_bf16_f32 v126, v126, v127
	v_cvt_pk_bf16_f32 v127, v128, v129
	v_cvt_pk_bf16_f32 v128, v122, v123
	v_cvt_pk_bf16_f32 v129, v124, v125
	global_store_dwordx4 v170, v[126:129], s[94:95]
	s_waitcnt vmcnt(13)
	v_lshlrev_b32_e32 v176, 16, v196
	v_and_b32_e32 v177, 0xffff0000, v196
	v_lshlrev_b32_e32 v178, 16, v197
	v_and_b32_e32 v179, 0xffff0000, v197
	v_lshlrev_b32_e32 v180, 16, v198
	v_and_b32_e32 v181, 0xffff0000, v198
	v_lshlrev_b32_e32 v182, 16, v199
	v_and_b32_e32 v183, 0xffff0000, v199
	v_pk_fma_f32 v[118:119], v[118:119], v[46:47], v[176:177]
	v_pk_fma_f32 v[120:121], v[120:121], v[48:49], v[178:179]
	v_pk_fma_f32 v[114:115], v[114:115], v[42:43], v[180:181]
	v_pk_fma_f32 v[116:117], v[116:117], v[44:45], v[182:183]
	s_add_u32 s92, s92, 0x10000
	s_addc_u32 s93, s93, 0
	global_load_dwordx4 v[196:199], v170, s[92:93]
	v_cvt_pk_bf16_f32 v118, v118, v119
	v_cvt_pk_bf16_f32 v119, v120, v121
	v_cvt_pk_bf16_f32 v120, v114, v115
	v_cvt_pk_bf16_f32 v121, v116, v117
	global_store_dwordx4 v170, v[118:121], s[94:95] offset:256
	s_waitcnt vmcnt(14)
	v_lshlrev_b32_e32 v176, 16, v210
	v_and_b32_e32 v177, 0xffff0000, v210
	v_lshlrev_b32_e32 v178, 16, v211
	v_and_b32_e32 v179, 0xffff0000, v211
	v_lshlrev_b32_e32 v180, 16, v212
	v_and_b32_e32 v181, 0xffff0000, v212
	v_lshlrev_b32_e32 v182, 16, v213
	v_and_b32_e32 v183, 0xffff0000, v213
	v_pk_fma_f32 v[110:111], v[110:111], v[62:63], v[176:177]
	v_pk_fma_f32 v[112:113], v[112:113], v[64:65], v[178:179]
	v_pk_fma_f32 v[106:107], v[106:107], v[58:59], v[180:181]
	v_pk_fma_f32 v[108:109], v[108:109], v[60:61], v[182:183]
	global_load_dwordx4 v[210:213], v170, s[92:93] offset:256
	s_add_u32 s94, s94, 0x10000
	s_addc_u32 s95, s95, 0
	v_cvt_pk_bf16_f32 v110, v110, v111
	v_cvt_pk_bf16_f32 v111, v112, v113
	v_cvt_pk_bf16_f32 v112, v106, v107
	v_cvt_pk_bf16_f32 v113, v108, v109
	global_store_dwordx4 v170, v[110:113], s[94:95]
	s_waitcnt vmcnt(15)
; __device__ __forceinline__ unsigned pk2(float lo, float hi) { f32x2 v = {lo, hi}; return __builtin_bit_cast(unsigned, __builtin_convertvector(v, bf16x2_t)); }
; __device__ __forceinline__ float bf_lo(unsigned w) { return __uint_as_float(w << 16); }
; __device__ __forceinline__ float bf_hi(unsigned w) { return __uint_as_float(w & 0xffff0000u); }
;     __device__ __forceinline__ void operator()(const f32x4 (&acc)[2][2][4][2], const Unit& u, int wr, int wc, int fr, int fq) const {
;     ...
;             for (int m = 0; m < 4; ++m) {
;                 const size_t ro = (size_t)(row0 + ai * HALF + m * 16) * DM + col0;
; #pragma unroll
;                 for (int bj = 0; bj < 2; ++bj) {
;                     f32x4 r0, r1;
;                     if (RB) { const u32x4 rw = *(const u32x4*)((const bf16_t*)resid + ro + bj * HALF);
;                         r0 = (f32x4){bf_lo(rw.x), bf_hi(rw.x), bf_lo(rw.y), bf_hi(rw.y)}; r1 = (f32x4){bf_lo(rw.z), bf_hi(rw.z), bf_lo(rw.w), bf_hi(rw.w)}; }
;                     else { r0 = *(const f32x4*)((const float*)resid + ro + bj * HALF); r1 = *(const f32x4*)((const float*)resid + ro + bj * HALF + 4); }
;                     const f32x4 v0 = r0 + gv[bj][0] * acc[ai][bj][m][0], v1 = r1 + gv[bj][1] * acc[ai][bj][m][1];
;                     if (OB) { u32x4 w; w.x = pk2(v0[0], v0[1]); w.y = pk2(v0[2], v0[3]); w.z = pk2(v1[0], v1[1]); w.w = pk2(v1[2], v1[3]); *(u32x4*)((bf16_t*)out + ro + bj * HALF) = w; }
;                     else { *(f32x4*)((float*)out + ro + bj * HALF) = v0; *(f32x4*)((float*)out + ro + bj * HALF + 4) = v1; }
;                 }
	v_lshlrev_b32_e32 v176, 16, v214
	v_and_b32_e32 v177, 0xffff0000, v214
	v_lshlrev_b32_e32 v178, 16, v215
	v_and_b32_e32 v179, 0xffff0000, v215
	v_lshlrev_b32_e32 v180, 16, v216
	v_and_b32_e32 v181, 0xffff0000, v216
	v_lshlrev_b32_e32 v182, 16, v217
	v_and_b32_e32 v183, 0xffff0000, v217
	v_pk_fma_f32 v[102:103], v[102:103], v[46:47], v[176:177]
	v_pk_fma_f32 v[104:105], v[104:105], v[48:49], v[178:179]
	v_pk_fma_f32 v[98:99], v[98:99], v[42:43], v[180:181]
	v_pk_fma_f32 v[100:101], v[100:101], v[44:45], v[182:183]
	v_cvt_pk_bf16_f32 v102, v102, v103
	v_cvt_pk_bf16_f32 v103, v104, v105
	v_cvt_pk_bf16_f32 v104, v98, v99
	v_cvt_pk_bf16_f32 v105, v100, v101
	global_store_dwordx4 v170, v[102:105], s[94:95] offset:256
	s_waitcnt vmcnt(15)
	v_lshlrev_b32_e32 v176, 16, v218
	v_and_b32_e32 v177, 0xffff0000, v218
	v_lshlrev_b32_e32 v178, 16, v219
	v_and_b32_e32 v179, 0xffff0000, v219
	v_lshlrev_b32_e32 v180, 16, v220
	v_and_b32_e32 v181, 0xffff0000, v220
	v_lshlrev_b32_e32 v182, 16, v221
	v_and_b32_e32 v183, 0xffff0000, v221
	v_pk_fma_f32 v[94:95], v[94:95], v[62:63], v[176:177]
	v_pk_fma_f32 v[96:97], v[96:97], v[64:65], v[178:179]
	v_pk_fma_f32 v[90:91], v[90:91], v[58:59], v[180:181]
	v_pk_fma_f32 v[92:93], v[92:93], v[60:61], v[182:183]
	s_add_u32 s94, s94, 0x10000
	s_addc_u32 s95, s95, 0
	v_cvt_pk_bf16_f32 v94, v94, v95
	v_cvt_pk_bf16_f32 v95, v96, v97
	v_cvt_pk_bf16_f32 v96, v90, v91
	v_cvt_pk_bf16_f32 v97, v92, v93
	global_store_dwordx4 v170, v[94:97], s[94:95]
	s_waitcnt vmcnt(15)
	v_lshlrev_b32_e32 v176, 16, v222
	v_and_b32_e32 v177, 0xffff0000, v222
	v_lshlrev_b32_e32 v178, 16, v223
	v_and_b32_e32 v179, 0xffff0000, v223
	v_lshlrev_b32_e32 v180, 16, v224
	v_and_b32_e32 v181, 0xffff0000, v224
	v_lshlrev_b32_e32 v182, 16, v225
	v_and_b32_e32 v183, 0xffff0000, v225
	v_pk_fma_f32 v[86:87], v[86:87], v[46:47], v[176:177]
	v_pk_fma_f32 v[88:89], v[88:89], v[48:49], v[178:179]
	v_pk_fma_f32 v[82:83], v[82:83], v[42:43], v[180:181]
	v_pk_fma_f32 v[84:85], v[84:85], v[44:45], v[182:183]
	v_cvt_pk_bf16_f32 v86, v86, v87
	v_cvt_pk_bf16_f32 v87, v88, v89
	v_cvt_pk_bf16_f32 v88, v82, v83
	v_cvt_pk_bf16_f32 v89, v84, v85
	global_store_dwordx4 v170, v[86:89], s[94:95] offset:256
	s_waitcnt vmcnt(15)
	v_lshlrev_b32_e32 v176, 16, v226
	v_and_b32_e32 v177, 0xffff0000, v226
	v_lshlrev_b32_e32 v178, 16, v227
	v_and_b32_e32 v179, 0xffff0000, v227
	v_lshlrev_b32_e32 v180, 16, v228
	v_and_b32_e32 v181, 0xffff0000, v228
	v_lshlrev_b32_e32 v182, 16, v229
	v_and_b32_e32 v183, 0xffff0000, v229
	v_pk_fma_f32 v[78:79], v[78:79], v[62:63], v[176:177]
	v_pk_fma_f32 v[80:81], v[80:81], v[64:65], v[178:179]
	v_pk_fma_f32 v[74:75], v[74:75], v[58:59], v[180:181]
	v_pk_fma_f32 v[76:77], v[76:77], v[60:61], v[182:183]
	s_add_u32 s94, s94, 0x50000
	s_addc_u32 s95, s95, 0
	v_cvt_pk_bf16_f32 v78, v78, v79
	v_cvt_pk_bf16_f32 v79, v80, v81
	v_cvt_pk_bf16_f32 v80, v74, v75
	v_cvt_pk_bf16_f32 v81, v76, v77
	global_store_dwordx4 v170, v[78:81], s[94:95]
	s_waitcnt vmcnt(15)
	v_lshlrev_b32_e32 v176, 16, v230
	v_and_b32_e32 v177, 0xffff0000, v230
	v_lshlrev_b32_e32 v178, 16, v231
	v_and_b32_e32 v179, 0xffff0000, v231
	v_lshlrev_b32_e32 v180, 16, v232
	v_and_b32_e32 v181, 0xffff0000, v232
	v_lshlrev_b32_e32 v182, 16, v233
	v_and_b32_e32 v183, 0xffff0000, v233
	v_pk_fma_f32 v[70:71], v[70:71], v[46:47], v[176:177]
	v_pk_fma_f32 v[72:73], v[72:73], v[48:49], v[178:179]
	v_pk_fma_f32 v[66:67], v[66:67], v[42:43], v[180:181]
	v_pk_fma_f32 v[68:69], v[68:69], v[44:45], v[182:183]
	v_cvt_pk_bf16_f32 v70, v70, v71
	v_cvt_pk_bf16_f32 v71, v72, v73
	v_cvt_pk_bf16_f32 v72, v66, v67
	v_cvt_pk_bf16_f32 v73, v68, v69
	global_store_dwordx4 v170, v[70:73], s[94:95] offset:256
	s_waitcnt vmcnt(15)
	v_lshlrev_b32_e32 v176, 16, v234
	v_and_b32_e32 v177, 0xffff0000, v234
	v_lshlrev_b32_e32 v178, 16, v235
	v_and_b32_e32 v179, 0xffff0000, v235
	v_lshlrev_b32_e32 v180, 16, v236
	v_and_b32_e32 v181, 0xffff0000, v236
	v_lshlrev_b32_e32 v182, 16, v237
	v_and_b32_e32 v183, 0xffff0000, v237
	v_pk_fma_f32 v[54:55], v[54:55], v[62:63], v[176:177]
	v_pk_fma_f32 v[56:57], v[56:57], v[64:65], v[178:179]
	v_pk_fma_f32 v[50:51], v[50:51], v[58:59], v[180:181]
	v_pk_fma_f32 v[52:53], v[52:53], v[60:61], v[182:183]
	s_add_u32 s94, s94, 0x10000
	s_addc_u32 s95, s95, 0
	v_cvt_pk_bf16_f32 v54, v54, v55
	v_cvt_pk_bf16_f32 v55, v56, v57
	v_cvt_pk_bf16_f32 v56, v50, v51
	v_cvt_pk_bf16_f32 v57, v52, v53
	global_store_dwordx4 v170, v[54:57], s[94:95]
	s_waitcnt vmcnt(15)
; __device__ __forceinline__ unsigned pk2(float lo, float hi) { f32x2 v = {lo, hi}; return __builtin_bit_cast(unsigned, __builtin_convertvector(v, bf16x2_t)); }
; __device__ __forceinline__ float bf_lo(unsigned w) { return __uint_as_float(w << 16); }
; __device__ __forceinline__ float bf_hi(unsigned w) { return __uint_as_float(w & 0xffff0000u); }
; #define PG8_WAIT_V(n) asm volatile("s_waitcnt vmcnt(" #n ")" ::: "memory")
; #define PG8_BAR __builtin_amdgcn_s_barrier()
;     __device__ __forceinline__ void operator()(const f32x4 (&acc)[2][2][4][2], const Unit& u, int wr, int wc, int fr, int fq) const {
;     ...
;                     if (RB) { const u32x4 rw = *(const u32x4*)((const bf16_t*)resid + ro + bj * HALF);
;                         r0 = (f32x4){bf_lo(rw.x), bf_hi(rw.x), bf_lo(rw.y), bf_hi(rw.y)}; r1 = (f32x4){bf_lo(rw.z), bf_hi(rw.z), bf_lo(rw.w), bf_hi(rw.w)}; }
;                     else { r0 = *(const f32x4*)((const float*)resid + ro + bj * HALF); r1 = *(const f32x4*)((const float*)resid + ro + bj * HALF + 4); }
;                     const f32x4 v0 = r0 + gv[bj][0] * acc[ai][bj][m][0], v1 = r1 + gv[bj][1] * acc[ai][bj][m][1];
;                     if (OB) { u32x4 w; w.x = pk2(v0[0], v0[1]); w.y = pk2(v0[2], v0[3]); w.z = pk2(v1[0], v1[1]); w.w = pk2(v1[2], v1[3]); *(u32x4*)((bf16_t*)out + ro + bj * HALF) = w; }
;                     else { *(f32x4*)((float*)out + ro + bj * HALF) = v0; *(f32x4*)((float*)out + ro + bj * HALF + 4) = v1; }
;                 }
; template <class Epi>
; __device__ __forceinline__ void gemm_phase(LAS unsigned char* lds, const Gemm g, const StaticOrder& S, const Epi& E, const int tid) {
;     ...
;         E(acc, cur, wr, wc, fr, fq);
;         if (!has_next) break;
; #pragma unroll
;         for (int a = 0; a < 2; ++a)
; #pragma unroll
;             for (int b = 0; b < 2; ++b)
; #pragma unroll
;                 for (int m = 0; m < 4; ++m)
; #pragma unroll
;                     for (int n = 0; n < 2; ++n) acc[a][b][m][n] = (f32x4){0.f, 0.f, 0.f, 0.f};
;         cur = nxt; cA = nA; cB = nB; ++ui;
;     }
;     PG8_WAIT_V(0);
;     if (wr == 0) PG8_BAR;
	v_lshlrev_b32_e32 v176, 16, v184
	v_and_b32_e32 v177, 0xffff0000, v184
	v_lshlrev_b32_e32 v178, 16, v185
	v_and_b32_e32 v179, 0xffff0000, v185
	v_lshlrev_b32_e32 v180, 16, v186
	v_and_b32_e32 v181, 0xffff0000, v186
	v_lshlrev_b32_e32 v182, 16, v187
	v_and_b32_e32 v183, 0xffff0000, v187
	v_pk_fma_f32 v[38:39], v[38:39], v[46:47], v[176:177]
	v_pk_fma_f32 v[40:41], v[40:41], v[48:49], v[178:179]
	v_pk_fma_f32 v[34:35], v[34:35], v[42:43], v[180:181]
	v_pk_fma_f32 v[36:37], v[36:37], v[44:45], v[182:183]
	v_cvt_pk_bf16_f32 v38, v38, v39
	v_cvt_pk_bf16_f32 v39, v40, v41
	v_cvt_pk_bf16_f32 v40, v34, v35
	v_cvt_pk_bf16_f32 v41, v36, v37
	global_store_dwordx4 v170, v[38:41], s[94:95] offset:256
	s_waitcnt vmcnt(14)
	v_lshlrev_b32_e32 v176, 16, v188
	v_and_b32_e32 v177, 0xffff0000, v188
	v_lshlrev_b32_e32 v178, 16, v189
	v_and_b32_e32 v179, 0xffff0000, v189
	v_lshlrev_b32_e32 v180, 16, v190
	v_and_b32_e32 v181, 0xffff0000, v190
	v_lshlrev_b32_e32 v182, 16, v191
	v_and_b32_e32 v183, 0xffff0000, v191
	v_pk_fma_f32 v[30:31], v[30:31], v[62:63], v[176:177]
	v_pk_fma_f32 v[32:33], v[32:33], v[64:65], v[178:179]
	v_pk_fma_f32 v[26:27], v[26:27], v[58:59], v[180:181]
	v_pk_fma_f32 v[28:29], v[28:29], v[60:61], v[182:183]
	s_add_u32 s94, s94, 0x10000
	s_addc_u32 s95, s95, 0
	v_cvt_pk_bf16_f32 v30, v30, v31
	v_cvt_pk_bf16_f32 v31, v32, v33
	v_cvt_pk_bf16_f32 v32, v26, v27
	v_cvt_pk_bf16_f32 v33, v28, v29
	global_store_dwordx4 v170, v[30:33], s[94:95]
	s_waitcnt vmcnt(13)
	v_lshlrev_b32_e32 v176, 16, v192
	v_and_b32_e32 v177, 0xffff0000, v192
	v_lshlrev_b32_e32 v178, 16, v193
	v_and_b32_e32 v179, 0xffff0000, v193
	v_lshlrev_b32_e32 v180, 16, v194
	v_and_b32_e32 v181, 0xffff0000, v194
	v_lshlrev_b32_e32 v182, 16, v195
	v_and_b32_e32 v183, 0xffff0000, v195
	v_pk_fma_f32 v[22:23], v[22:23], v[46:47], v[176:177]
	v_pk_fma_f32 v[24:25], v[24:25], v[48:49], v[178:179]
	v_pk_fma_f32 v[18:19], v[18:19], v[42:43], v[180:181]
	v_pk_fma_f32 v[20:21], v[20:21], v[44:45], v[182:183]
	v_cvt_pk_bf16_f32 v22, v22, v23
	v_cvt_pk_bf16_f32 v23, v24, v25
	v_cvt_pk_bf16_f32 v24, v18, v19
	v_cvt_pk_bf16_f32 v25, v20, v21
	global_store_dwordx4 v170, v[22:25], s[94:95] offset:256
	s_waitcnt vmcnt(12)
	v_lshlrev_b32_e32 v176, 16, v196
	v_and_b32_e32 v177, 0xffff0000, v196
	v_lshlrev_b32_e32 v178, 16, v197
	v_and_b32_e32 v179, 0xffff0000, v197
	v_lshlrev_b32_e32 v180, 16, v198
	v_and_b32_e32 v181, 0xffff0000, v198
	v_lshlrev_b32_e32 v182, 16, v199
	v_and_b32_e32 v183, 0xffff0000, v199
	v_pk_fma_f32 v[14:15], v[14:15], v[62:63], v[176:177]
	v_pk_fma_f32 v[16:17], v[16:17], v[64:65], v[178:179]
	v_pk_fma_f32 v[10:11], v[10:11], v[58:59], v[180:181]
	v_pk_fma_f32 v[12:13], v[12:13], v[60:61], v[182:183]
	s_add_u32 s94, s94, 0x10000
	s_addc_u32 s95, s95, 0
	v_cvt_pk_bf16_f32 v14, v14, v15
	v_cvt_pk_bf16_f32 v15, v16, v17
	v_cvt_pk_bf16_f32 v16, v10, v11
	v_cvt_pk_bf16_f32 v17, v12, v13
	global_store_dwordx4 v170, v[14:17], s[94:95]
	s_waitcnt vmcnt(11)
	v_lshlrev_b32_e32 v176, 16, v210
	v_and_b32_e32 v177, 0xffff0000, v210
	v_lshlrev_b32_e32 v178, 16, v211
	v_and_b32_e32 v179, 0xffff0000, v211
	v_lshlrev_b32_e32 v180, 16, v212
	v_and_b32_e32 v181, 0xffff0000, v212
	v_lshlrev_b32_e32 v182, 16, v213
	v_and_b32_e32 v183, 0xffff0000, v213
	v_pk_fma_f32 v[6:7], v[6:7], v[46:47], v[176:177]
	v_pk_fma_f32 v[8:9], v[8:9], v[48:49], v[178:179]
	v_pk_fma_f32 v[2:3], v[2:3], v[42:43], v[180:181]
	v_pk_fma_f32 v[4:5], v[4:5], v[44:45], v[182:183]
	v_cvt_pk_bf16_f32 v6, v6, v7
	v_cvt_pk_bf16_f32 v7, v8, v9
	v_cvt_pk_bf16_f32 v8, v2, v3
	v_cvt_pk_bf16_f32 v9, v4, v5
	global_store_dwordx4 v170, v[6:9], s[94:95] offset:256
	s_mov_b32 s2, s12
	s_mov_b64 s[20:21], s[14:15]
	s_mov_b64 s[18:19], s[16:17]
	s_and_b64 vcc, exec, s[4:5]
	s_nop 1
	s_cbranch_vccz .LBB0_112
	s_waitcnt vmcnt(0)
	s_cmpk_gt_u32 s29, 0xff
	s_cbranch_scc1 .LBB0_123
	s_barrier

; #define PG8_STAGE(bufoff, gbase, voff) do { _Pragma("unroll") for (int _i = 0; _i < 2; ++_i) \
;         __builtin_amdgcn_global_load_lds((const unsigned*)((const char*)(gbase) + (voff)[_i]), (LAS unsigned*)(lds + (bufoff) + ldsw + _i * 8192), 16, 0, 0); } while (0)
; #define PG8_LDA(dst, b, h) do { _Pragma("unroll") for (int m = 0; m < 4; ++m) _Pragma("unroll") for (int k = 0; k < 2; ++k) dst[m][k] = *(const LAS bf16x8*)(lds + PG8_SA(b, h) + aoff + m * 2048 + k * 1024); } while (0)
; #define PG8_LDB(dst, b, h) do { _Pragma("unroll") for (int n = 0; n < 2; ++n) _Pragma("unroll") for (int k = 0; k < 2; ++k) dst[n][k] = *(const LAS bf16x8*)(lds + PG8_SB(b, h) + boff + n * 2048 + k * 1024); } while (0)
; #define PG8_MMA(ai, bj, At, Bt) do { __builtin_amdgcn_s_setprio(1); _Pragma("unroll") for (int m = 0; m < 4; ++m) _Pragma("unroll") for (int n = 0; n < 2; ++n) _Pragma("unroll") for (int k = 0; k < 2; ++k) \
;         acc[ai][bj][m][n] = __builtin_amdgcn_mfma_f32_16x16x32_bf16(Bt[n][k], At[m][k], acc[ai][bj][m][n], 0, 0, 0); __builtin_amdgcn_s_setprio(0); } while (0)
; #define PG8_BAR __builtin_amdgcn_s_barrier()
; template <class Epi>
; __device__ __forceinline__ void gemm_phase(LAS unsigned char* lds, const Gemm g, const StaticOrder& S, const Epi& E, const int tid) {
;     ...
;         const bool has_next = S.next(ui + 1, nxt);
;         const char* nA = has_next ? (const char*)g.A + (size_t)nxt.pm * tstep : cA; const char* nB = has_next ? (const char*)g.Bt + (size_t)nxt.pn * tstep : cB;
;         for (int t = 0; t < nt; t += 2) {
;             const bool last = (t == nt - 2);
;             const char* a1 = cA + (size_t)(t + 1) * kstep;
;             const char* a2 = last ? nA : cA + (size_t)(t + 2) * kstep; const char* b2 = last ? nB : cB + (size_t)(t + 2) * kstep;
;             const char* a3 = a2 + kstep; const char* b3 = b2 + kstep;
;             PG8_LDB(B0, 0, 0); PG8_SCHED; PG8_LDA(At, 0, 0); PG8_STAGE(PG8_SA(1, 1), a1 + hstep, voffA);
;             PG8_WAIT_L(8); PG8_BAR; PG8_WAIT_L(0); PG8_MMA(0, 0, At, B0); PG8_BAR; PG8_SCHED;
;     ...
; #pragma unroll
;         for (int a = 0; a < 2; ++a)
; #pragma unroll
;             for (int b = 0; b < 2; ++b)
; #pragma unroll
;                 for (int m = 0; m < 4; ++m)
; #pragma unroll
;                     for (int n = 0; n < 2; ++n) acc[a][b][m][n] = (f32x4){0.f, 0.f, 0.f, 0.f};
;         cur = nxt; cA = nA; cB = nB; ++ui;
.LBB0_140:
	s_ashr_i32 s13, s12, 31
	v_cmp_lt_i64_e32 vcc, s[14:15], v[146:147]
	s_lshl_b64 s[14:15], s[12:13], 20
	s_add_u32 s14, s0, s14
	s_addc_u32 s15, s1, s15
	s_and_b64 s[16:17], vcc, exec
	s_cselect_b32 s13, s15, s21
	s_cselect_b32 s44, s14, s20
	s_ashr_i32 s11, s10, 31
	s_lshl_b64 s[16:17], s[10:11], 20
	s_add_u32 s16, s24, s16
	s_addc_u32 s17, s25, s17
	s_and_b64 s[22:23], vcc, exec
	s_cselect_b32 s11, s17, s19
	s_cselect_b32 s45, s16, s18
	s_add_u32 s47, s18, 0x100
	s_addc_u32 s48, s19, 0
	s_add_u32 s18, s20, 0x80080
	v_mov_b32_e32 v2, 0
	s_addc_u32 s19, s21, 0
	s_mov_b32 s49, -2
	v_mov_b32_e32 v3, v2
	v_mov_b32_e32 v4, v2
	v_mov_b32_e32 v5, v2
	v_mov_b32_e32 v6, v2
	v_mov_b32_e32 v7, v2
	v_mov_b32_e32 v8, v2
	v_mov_b32_e32 v9, v2
	v_mov_b32_e32 v18, v2
	v_mov_b32_e32 v19, v2
	v_mov_b32_e32 v20, v2
	v_mov_b32_e32 v21, v2
	v_mov_b32_e32 v22, v2
	v_mov_b32_e32 v23, v2
	v_mov_b32_e32 v24, v2
	v_mov_b32_e32 v25, v2
	v_mov_b32_e32 v34, v2
	v_mov_b32_e32 v35, v2
	v_mov_b32_e32 v36, v2
	v_mov_b32_e32 v37, v2
	v_mov_b32_e32 v38, v2
	v_mov_b32_e32 v39, v2
	v_mov_b32_e32 v40, v2
	v_mov_b32_e32 v41, v2
	v_mov_b32_e32 v50, v2
	v_mov_b32_e32 v51, v2
	v_mov_b32_e32 v52, v2
	v_mov_b32_e32 v53, v2
	v_mov_b32_e32 v54, v2
	v_mov_b32_e32 v55, v2
	v_mov_b32_e32 v56, v2
	v_mov_b32_e32 v57, v2
	v_mov_b32_e32 v10, v2
	v_mov_b32_e32 v11, v2
	v_mov_b32_e32 v12, v2
	v_mov_b32_e32 v13, v2
	v_mov_b32_e32 v14, v2
	v_mov_b32_e32 v15, v2
	v_mov_b32_e32 v16, v2
	v_mov_b32_e32 v17, v2
	v_mov_b32_e32 v26, v2
	v_mov_b32_e32 v27, v2
	v_mov_b32_e32 v28, v2
	v_mov_b32_e32 v29, v2
	v_mov_b32_e32 v30, v2
	v_mov_b32_e32 v31, v2
	v_mov_b32_e32 v32, v2
	v_mov_b32_e32 v33, v2
	v_mov_b32_e32 v42, v2
	v_mov_b32_e32 v43, v2
	v_mov_b32_e32 v44, v2
	v_mov_b32_e32 v45, v2
	v_mov_b32_e32 v46, v2
	v_mov_b32_e32 v47, v2
	v_mov_b32_e32 v48, v2
	v_mov_b32_e32 v49, v2
	v_mov_b32_e32 v58, v2
	v_mov_b32_e32 v59, v2
	v_mov_b32_e32 v60, v2
	v_mov_b32_e32 v61, v2
	v_mov_b32_e32 v62, v2
	v_mov_b32_e32 v63, v2
	v_mov_b32_e32 v64, v2
	v_mov_b32_e32 v65, v2
	v_mov_b32_e32 v74, v2
	v_mov_b32_e32 v75, v2
	v_mov_b32_e32 v76, v2
	v_mov_b32_e32 v77, v2
	v_mov_b32_e32 v78, v2
	v_mov_b32_e32 v79, v2
	v_mov_b32_e32 v80, v2
	v_mov_b32_e32 v81, v2
	v_mov_b32_e32 v98, v2
	v_mov_b32_e32 v99, v2
	v_mov_b32_e32 v100, v2
	v_mov_b32_e32 v101, v2
	v_mov_b32_e32 v102, v2
	v_mov_b32_e32 v103, v2
	v_mov_b32_e32 v104, v2
	v_mov_b32_e32 v105, v2
	v_mov_b32_e32 v114, v2
	v_mov_b32_e32 v115, v2
	v_mov_b32_e32 v116, v2
	v_mov_b32_e32 v117, v2
	v_mov_b32_e32 v118, v2
	v_mov_b32_e32 v119, v2
	v_mov_b32_e32 v120, v2
	v_mov_b32_e32 v121, v2
	v_mov_b32_e32 v130, v2
	v_mov_b32_e32 v131, v2
	v_mov_b32_e32 v132, v2
	v_mov_b32_e32 v133, v2
	v_mov_b32_e32 v134, v2
	v_mov_b32_e32 v135, v2
	v_mov_b32_e32 v136, v2
	v_mov_b32_e32 v137, v2
	v_mov_b32_e32 v90, v2
	v_mov_b32_e32 v91, v2
	v_mov_b32_e32 v92, v2
	v_mov_b32_e32 v93, v2
	v_mov_b32_e32 v94, v2
	v_mov_b32_e32 v95, v2
	v_mov_b32_e32 v96, v2
	v_mov_b32_e32 v97, v2
	v_mov_b32_e32 v106, v2
	v_mov_b32_e32 v107, v2
	v_mov_b32_e32 v108, v2
	v_mov_b32_e32 v109, v2
	v_mov_b32_e32 v110, v2
	v_mov_b32_e32 v111, v2
	v_mov_b32_e32 v112, v2
	v_mov_b32_e32 v113, v2
	v_mov_b32_e32 v122, v2
	v_mov_b32_e32 v123, v2
	v_mov_b32_e32 v124, v2
	v_mov_b32_e32 v125, v2
	v_mov_b32_e32 v126, v2
	v_mov_b32_e32 v127, v2
	v_mov_b32_e32 v128, v2
	v_mov_b32_e32 v129, v2
	s_waitcnt vmcnt(0)
	v_mov_b32_e32 v138, v2
	v_mov_b32_e32 v139, v2
	v_mov_b32_e32 v140, v2
	v_mov_b32_e32 v141, v2
	v_mov_b32_e32 v142, v2
	v_mov_b32_e32 v143, v2
	v_mov_b32_e32 v144, v2
	v_mov_b32_e32 v145, v2
	v_readfirstlane_b32 s32, v158
	s_cmpk_lt_u32 s32, 0x100
	s_cbranch_scc1 .Lgprio4
	s_setprio 1
.Lgprio4:
.LBB0_141:
	s_add_u32 s20, s18, 0xfff80080
	s_addc_u32 s21, s19, -1
	s_add_i32 s50, 0, 0x10000
	v_add_u32_e32 v86, s50, v173
	ds_read_b128 v[66:69], v86
	ds_read_b128 v[70:73], v86 offset:1024
	ds_read_b128 v[82:85], v86 offset:2048
	ds_read_b128 v[86:89], v86 offset:3072
	s_cmp_eq_u32 s49, 28
	s_cselect_b32 s23, s13, s21
	s_cselect_b32 s22, s44, s20
	s_cselect_b32 s21, s11, s48
	s_cselect_b32 s20, s45, s47
	v_lshl_add_u64 v[170:171], s[18:19], 0, v[168:169]
	s_add_i32 m0, s3, 0xc000
	ds_read_b128 v[176:179], v174
	ds_read_b128 v[180:183], v174 offset:1024
	ds_read_b128 v[184:187], v174 offset:2048
	ds_read_b128 v[188:191], v174 offset:3072
	ds_read_b128 v[192:195], v174 offset:4096
	ds_read_b128 v[196:199], v174 offset:5120
	ds_read_b128 v[210:213], v174 offset:6144
	ds_read_b128 v[214:217], v174 offset:7168
	global_load_lds_dwordx4 v[170:171], off
	v_lshl_add_u64 v[170:171], s[18:19], 0, v[166:167]
	s_add_i32 m0, s3, 0xe000
	s_nop 0
	global_load_lds_dwordx4 v[170:171], off
	s_waitcnt lgkmcnt(8)
	s_barrier
	s_waitcnt lgkmcnt(0)
	v_mfma_f32_16x16x32_bf16 v[142:145], v[66:69], v[176:179], v[142:145]
	v_mfma_f32_16x16x32_bf16 v[138:141], v[82:85], v[176:179], v[138:141]
	v_mfma_f32_16x16x32_bf16 v[126:129], v[66:69], v[184:187], v[126:129]
	v_mfma_f32_16x16x32_bf16 v[122:125], v[82:85], v[184:187], v[122:125]
	v_mfma_f32_16x16x32_bf16 v[110:113], v[66:69], v[192:195], v[110:113]
	v_mfma_f32_16x16x32_bf16 v[106:109], v[82:85], v[192:195], v[106:109]
	v_mfma_f32_16x16x32_bf16 v[94:97], v[66:69], v[210:213], v[94:97]
	v_mfma_f32_16x16x32_bf16 v[90:93], v[82:85], v[210:213], v[90:93]
	v_mfma_f32_16x16x32_bf16 v[142:145], v[70:73], v[180:183], v[142:145]
	v_mfma_f32_16x16x32_bf16 v[138:141], v[86:89], v[180:183], v[138:141]
	v_mfma_f32_16x16x32_bf16 v[126:129], v[70:73], v[188:191], v[126:129]
	v_mfma_f32_16x16x32_bf16 v[122:125], v[86:89], v[188:191], v[122:125]
	v_mfma_f32_16x16x32_bf16 v[110:113], v[70:73], v[196:199], v[110:113]
	v_mfma_f32_16x16x32_bf16 v[106:109], v[86:89], v[196:199], v[106:109]
	v_mfma_f32_16x16x32_bf16 v[94:97], v[70:73], v[214:217], v[94:97]
	v_mfma_f32_16x16x32_bf16 v[90:93], v[86:89], v[214:217], v[90:93]
	s_barrier
; #define PG8_STAGE(bufoff, gbase, voff) do { _Pragma("unroll") for (int _i = 0; _i < 2; ++_i) \
;         __builtin_amdgcn_global_load_lds((const unsigned*)((const char*)(gbase) + (voff)[_i]), (LAS unsigned*)(lds + (bufoff) + ldsw + _i * 8192), 16, 0, 0); } while (0)
; #define PG8_LDA(dst, b, h) do { _Pragma("unroll") for (int m = 0; m < 4; ++m) _Pragma("unroll") for (int k = 0; k < 2; ++k) dst[m][k] = *(const LAS bf16x8*)(lds + PG8_SA(b, h) + aoff + m * 2048 + k * 1024); } while (0)
; #define PG8_LDB(dst, b, h) do { _Pragma("unroll") for (int n = 0; n < 2; ++n) _Pragma("unroll") for (int k = 0; k < 2; ++k) dst[n][k] = *(const LAS bf16x8*)(lds + PG8_SB(b, h) + boff + n * 2048 + k * 1024); } while (0)
; #define PG8_MMA(ai, bj, At, Bt) do { __builtin_amdgcn_s_setprio(1); _Pragma("unroll") for (int m = 0; m < 4; ++m) _Pragma("unroll") for (int n = 0; n < 2; ++n) _Pragma("unroll") for (int k = 0; k < 2; ++k) \
;         acc[ai][bj][m][n] = __builtin_amdgcn_mfma_f32_16x16x32_bf16(Bt[n][k], At[m][k], acc[ai][bj][m][n], 0, 0, 0); __builtin_amdgcn_s_setprio(0); } while (0)
; #define PG8_WAIT_V(n) asm volatile("s_waitcnt vmcnt(" #n ")" ::: "memory")
; #define PG8_WAIT_L(n) asm volatile("s_waitcnt lgkmcnt(" #n ")" ::: "memory")
; #define PG8_BAR __builtin_amdgcn_s_barrier()
; #define PG8_SCHED __builtin_amdgcn_sched_barrier(0)
; template <class Epi>
; __device__ __forceinline__ void gemm_phase(LAS unsigned char* lds, const Gemm g, const StaticOrder& S, const Epi& E, const int tid) {
;     ...
;             PG8_LDB(B1, 0, 1); PG8_STAGE(PG8_SB(0, 0), b2, voffB);
;             PG8_BAR; PG8_WAIT_L(0); PG8_MMA(0, 1, At, B1); PG8_BAR;
;             PG8_LDA(At, 0, 1); PG8_STAGE(PG8_SA(0, 0), a2, voffA);
;             PG8_BAR; PG8_WAIT_L(0); PG8_MMA(1, 0, At, B0); PG8_BAR; PG8_SCHED;
;             PG8_STAGE(PG8_SB(0, 1), b2 + hstep, voffB);
;             PG8_WAIT_V(6); PG8_BAR; PG8_MMA(1, 1, At, B1); PG8_BAR;
;             PG8_LDB(B0, 1, 0); PG8_SCHED; PG8_LDA(At, 1, 0); PG8_STAGE(PG8_SA(0, 1), a2 + hstep, voffA);
;             PG8_WAIT_L(8); PG8_BAR; PG8_WAIT_L(0); PG8_MMA(0, 0, At, B0); PG8_BAR; PG8_SCHED;
	s_add_i32 s54, 0, 0x14000
	v_add_u32_e32 v170, s54, v173
	s_add_i32 s50, s50, s31
	ds_read_b128 v[218:221], v170
	ds_read_b128 v[222:225], v170 offset:1024
	ds_read_b128 v[226:229], v170 offset:2048
	ds_read_b128 v[230:233], v170 offset:3072
	v_lshl_add_u64 v[170:171], s[20:21], 0, v[0:1]
	s_mov_b32 m0, s50
	v_lshl_add_u64 v[200:201], s[20:21], 0, v[164:165]
	global_load_lds_dwordx4 v[170:171], off
	s_add_i32 m0, s50, 0x2000
	s_nop 0
	global_load_lds_dwordx4 v[200:201], off
	s_barrier
	s_waitcnt lgkmcnt(0)
	v_mfma_f32_16x16x32_bf16 v[134:137], v[218:221], v[176:179], v[134:137]
	v_mfma_f32_16x16x32_bf16 v[130:133], v[226:229], v[176:179], v[130:133]
	v_mfma_f32_16x16x32_bf16 v[118:121], v[218:221], v[184:187], v[118:121]
	v_mfma_f32_16x16x32_bf16 v[114:117], v[226:229], v[184:187], v[114:117]
	v_mfma_f32_16x16x32_bf16 v[102:105], v[218:221], v[192:195], v[102:105]
	v_mfma_f32_16x16x32_bf16 v[98:101], v[226:229], v[192:195], v[98:101]
	v_mfma_f32_16x16x32_bf16 v[78:81], v[218:221], v[210:213], v[78:81]
	v_mfma_f32_16x16x32_bf16 v[74:77], v[226:229], v[210:213], v[74:77]
	v_mfma_f32_16x16x32_bf16 v[134:137], v[222:225], v[180:183], v[134:137]
	v_mfma_f32_16x16x32_bf16 v[130:133], v[230:233], v[180:183], v[130:133]
	v_mfma_f32_16x16x32_bf16 v[118:121], v[222:225], v[188:191], v[118:121]
	v_mfma_f32_16x16x32_bf16 v[114:117], v[230:233], v[188:191], v[114:117]
	v_mfma_f32_16x16x32_bf16 v[102:105], v[222:225], v[196:199], v[102:105]
	v_mfma_f32_16x16x32_bf16 v[98:101], v[230:233], v[196:199], v[98:101]
	v_mfma_f32_16x16x32_bf16 v[78:81], v[222:225], v[214:217], v[78:81]
	v_mfma_f32_16x16x32_bf16 v[74:77], v[230:233], v[214:217], v[74:77]
	s_mov_b32 m0, s3
	v_lshl_add_u64 v[234:235], s[22:23], 0, v[160:161]
	s_barrier
	ds_read_b128 v[176:179], v174 offset:16384
	ds_read_b128 v[180:183], v174 offset:17408
	ds_read_b128 v[184:187], v174 offset:18432
	ds_read_b128 v[188:191], v174 offset:19456
	ds_read_b128 v[192:195], v174 offset:20480
	ds_read_b128 v[196:199], v174 offset:21504
	ds_read_b128 v[210:213], v174 offset:22528
	ds_read_b128 v[214:217], v174 offset:23552
	global_load_lds_dwordx4 v[234:235], off
	v_lshl_add_u64 v[236:237], s[22:23], 0, v[162:163]
	s_mov_b32 m0, s34
	s_nop 0
	global_load_lds_dwordx4 v[236:237], off
	s_barrier
	s_waitcnt lgkmcnt(0)
	v_mfma_f32_16x16x32_bf16 v[62:65], v[66:69], v[176:179], v[62:65]
	v_mfma_f32_16x16x32_bf16 v[58:61], v[82:85], v[176:179], v[58:61]
	v_mfma_f32_16x16x32_bf16 v[46:49], v[66:69], v[184:187], v[46:49]
	v_mfma_f32_16x16x32_bf16 v[42:45], v[82:85], v[184:187], v[42:45]
	v_mfma_f32_16x16x32_bf16 v[30:33], v[66:69], v[192:195], v[30:33]
	v_mfma_f32_16x16x32_bf16 v[26:29], v[82:85], v[192:195], v[26:29]
	v_mfma_f32_16x16x32_bf16 v[14:17], v[66:69], v[210:213], v[14:17]
	v_mfma_f32_16x16x32_bf16 v[10:13], v[82:85], v[210:213], v[10:13]
	v_mfma_f32_16x16x32_bf16 v[62:65], v[70:73], v[180:183], v[62:65]
	v_mfma_f32_16x16x32_bf16 v[58:61], v[86:89], v[180:183], v[58:61]
	v_mfma_f32_16x16x32_bf16 v[46:49], v[70:73], v[188:191], v[46:49]
	v_mfma_f32_16x16x32_bf16 v[42:45], v[86:89], v[188:191], v[42:45]
	v_mfma_f32_16x16x32_bf16 v[30:33], v[70:73], v[196:199], v[30:33]
	v_mfma_f32_16x16x32_bf16 v[26:29], v[86:89], v[196:199], v[26:29]
	v_mfma_f32_16x16x32_bf16 v[14:17], v[70:73], v[214:217], v[14:17]
	v_mfma_f32_16x16x32_bf16 v[10:13], v[86:89], v[214:217], v[10:13]
	s_barrier
	s_add_u32 s52, s20, 0x80000
	s_addc_u32 s53, s21, 0
	s_add_i32 s50, s54, s31
	v_lshl_add_u64 v[66:67], s[52:53], 0, v[0:1]
	s_mov_b32 m0, s50
	s_nop 0
	global_load_lds_dwordx4 v[66:67], off
	v_lshl_add_u64 v[66:67], s[52:53], 0, v[164:165]
	s_add_i32 m0, s50, 0x2000
	s_nop 0
	global_load_lds_dwordx4 v[66:67], off
	s_waitcnt vmcnt(6)
	s_barrier
	v_mfma_f32_16x16x32_bf16 v[54:57], v[218:221], v[176:179], v[54:57]
	v_mfma_f32_16x16x32_bf16 v[50:53], v[226:229], v[176:179], v[50:53]
	v_mfma_f32_16x16x32_bf16 v[38:41], v[218:221], v[184:187], v[38:41]
	v_mfma_f32_16x16x32_bf16 v[34:37], v[226:229], v[184:187], v[34:37]
	v_mfma_f32_16x16x32_bf16 v[22:25], v[218:221], v[192:195], v[22:25]
	v_mfma_f32_16x16x32_bf16 v[18:21], v[226:229], v[192:195], v[18:21]
	v_mfma_f32_16x16x32_bf16 v[6:9], v[218:221], v[210:213], v[6:9]
	v_mfma_f32_16x16x32_bf16 v[2:5], v[226:229], v[210:213], v[2:5]
	v_mfma_f32_16x16x32_bf16 v[54:57], v[222:225], v[180:183], v[54:57]
	v_mfma_f32_16x16x32_bf16 v[50:53], v[230:233], v[180:183], v[50:53]
	v_mfma_f32_16x16x32_bf16 v[38:41], v[222:225], v[188:191], v[38:41]
	v_mfma_f32_16x16x32_bf16 v[34:37], v[230:233], v[188:191], v[34:37]
	v_mfma_f32_16x16x32_bf16 v[22:25], v[222:225], v[196:199], v[22:25]
	v_mfma_f32_16x16x32_bf16 v[18:21], v[230:233], v[196:199], v[18:21]
	v_mfma_f32_16x16x32_bf16 v[6:9], v[222:225], v[214:217], v[6:9]
	v_mfma_f32_16x16x32_bf16 v[2:5], v[230:233], v[214:217], v[2:5]
	s_add_i32 s50, 0, 0x18000
	v_add_u32_e32 v86, s50, v173
	s_barrier
	ds_read_b128 v[66:69], v86
	ds_read_b128 v[70:73], v86 offset:1024
	ds_read_b128 v[82:85], v86 offset:2048
	ds_read_b128 v[86:89], v86 offset:3072
	s_add_u32 s22, s22, 0x80000
	s_addc_u32 s23, s23, 0
	s_mov_b32 m0, s35
	v_lshl_add_u64 v[218:219], s[22:23], 0, v[160:161]
	ds_read_b128 v[176:179], v174 offset:32768
	ds_read_b128 v[180:183], v174 offset:33792
	ds_read_b128 v[184:187], v174 offset:34816
	ds_read_b128 v[188:191], v174 offset:35840
	ds_read_b128 v[192:195], v174 offset:36864
	ds_read_b128 v[196:199], v174 offset:37888
	ds_read_b128 v[210:213], v174 offset:38912
	ds_read_b128 v[214:217], v174 offset:39936
	global_load_lds_dwordx4 v[218:219], off
	v_lshl_add_u64 v[218:219], s[22:23], 0, v[162:163]
	s_mov_b32 m0, s36
	s_nop 0
	global_load_lds_dwordx4 v[218:219], off
	s_waitcnt lgkmcnt(8)
	s_barrier
; #define PG8_STAGE(bufoff, gbase, voff) do { _Pragma("unroll") for (int _i = 0; _i < 2; ++_i) \
;         __builtin_amdgcn_global_load_lds((const unsigned*)((const char*)(gbase) + (voff)[_i]), (LAS unsigned*)(lds + (bufoff) + ldsw + _i * 8192), 16, 0, 0); } while (0)
; #define PG8_LDA(dst, b, h) do { _Pragma("unroll") for (int m = 0; m < 4; ++m) _Pragma("unroll") for (int k = 0; k < 2; ++k) dst[m][k] = *(const LAS bf16x8*)(lds + PG8_SA(b, h) + aoff + m * 2048 + k * 1024); } while (0)
; #define PG8_LDB(dst, b, h) do { _Pragma("unroll") for (int n = 0; n < 2; ++n) _Pragma("unroll") for (int k = 0; k < 2; ++k) dst[n][k] = *(const LAS bf16x8*)(lds + PG8_SB(b, h) + boff + n * 2048 + k * 1024); } while (0)
; #define PG8_MMA(ai, bj, At, Bt) do { __builtin_amdgcn_s_setprio(1); _Pragma("unroll") for (int m = 0; m < 4; ++m) _Pragma("unroll") for (int n = 0; n < 2; ++n) _Pragma("unroll") for (int k = 0; k < 2; ++k) \
;         acc[ai][bj][m][n] = __builtin_amdgcn_mfma_f32_16x16x32_bf16(Bt[n][k], At[m][k], acc[ai][bj][m][n], 0, 0, 0); __builtin_amdgcn_s_setprio(0); } while (0)
; #define PG8_WAIT_V(n) asm volatile("s_waitcnt vmcnt(" #n ")" ::: "memory")
; #define PG8_WAIT_L(n) asm volatile("s_waitcnt lgkmcnt(" #n ")" ::: "memory")
; #define PG8_BAR __builtin_amdgcn_s_barrier()
; #define PG8_SCHED __builtin_amdgcn_sched_barrier(0)
; template <class Epi>
; __device__ __forceinline__ void gemm_phase(LAS unsigned char* lds, const Gemm g, const StaticOrder& S, const Epi& E, const int tid) {
;     ...
;             PG8_WAIT_L(8); PG8_BAR; PG8_WAIT_L(0); PG8_MMA(0, 0, At, B0); PG8_BAR; PG8_SCHED;
;             PG8_LDB(B1, 1, 1); PG8_STAGE(PG8_SB(1, 0), b3, voffB);
;             PG8_BAR; PG8_WAIT_L(0); PG8_MMA(0, 1, At, B1); PG8_BAR;
;             PG8_LDA(At, 1, 1); PG8_STAGE(PG8_SA(1, 0), a3, voffA);
;             PG8_BAR; PG8_WAIT_L(0); PG8_MMA(1, 0, At, B0); PG8_BAR; PG8_SCHED;
;             PG8_STAGE(PG8_SB(1, 1), b3 + hstep, voffB);
;             PG8_WAIT_V(6); PG8_BAR; PG8_MMA(1, 1, At, B1); PG8_BAR;
	s_waitcnt lgkmcnt(0)
	v_mfma_f32_16x16x32_bf16 v[142:145], v[66:69], v[176:179], v[142:145]
	v_mfma_f32_16x16x32_bf16 v[138:141], v[82:85], v[176:179], v[138:141]
	v_mfma_f32_16x16x32_bf16 v[126:129], v[66:69], v[184:187], v[126:129]
	v_mfma_f32_16x16x32_bf16 v[122:125], v[82:85], v[184:187], v[122:125]
	v_mfma_f32_16x16x32_bf16 v[110:113], v[66:69], v[192:195], v[110:113]
	v_mfma_f32_16x16x32_bf16 v[106:109], v[82:85], v[192:195], v[106:109]
	v_mfma_f32_16x16x32_bf16 v[94:97], v[66:69], v[210:213], v[94:97]
	v_mfma_f32_16x16x32_bf16 v[90:93], v[82:85], v[210:213], v[90:93]
	v_mfma_f32_16x16x32_bf16 v[142:145], v[70:73], v[180:183], v[142:145]
	v_mfma_f32_16x16x32_bf16 v[138:141], v[86:89], v[180:183], v[138:141]
	v_mfma_f32_16x16x32_bf16 v[126:129], v[70:73], v[188:191], v[126:129]
	v_mfma_f32_16x16x32_bf16 v[122:125], v[86:89], v[188:191], v[122:125]
	v_mfma_f32_16x16x32_bf16 v[110:113], v[70:73], v[196:199], v[110:113]
	v_mfma_f32_16x16x32_bf16 v[106:109], v[86:89], v[196:199], v[106:109]
	v_mfma_f32_16x16x32_bf16 v[94:97], v[70:73], v[214:217], v[94:97]
	v_mfma_f32_16x16x32_bf16 v[90:93], v[86:89], v[214:217], v[90:93]
	s_barrier
	s_add_i32 s22, 0, 0x1c000
	s_add_i32 s23, s50, s31
	v_add_u32_e32 v175, s22, v173
	v_lshl_add_u64 v[170:171], v[170:171], 0, s[56:57]
	s_mov_b32 m0, s23
	ds_read_b128 v[218:221], v175
	ds_read_b128 v[222:225], v175 offset:1024
	ds_read_b128 v[226:229], v175 offset:2048
	ds_read_b128 v[230:233], v175 offset:3072
	global_load_lds_dwordx4 v[170:171], off
	v_lshl_add_u64 v[170:171], v[200:201], 0, s[56:57]
	s_add_i32 m0, s23, 0x2000
	s_nop 0
	global_load_lds_dwordx4 v[170:171], off
	s_barrier
	s_waitcnt lgkmcnt(0)
	v_mfma_f32_16x16x32_bf16 v[134:137], v[218:221], v[176:179], v[134:137]
	v_mfma_f32_16x16x32_bf16 v[130:133], v[226:229], v[176:179], v[130:133]
	v_mfma_f32_16x16x32_bf16 v[118:121], v[218:221], v[184:187], v[118:121]
	v_mfma_f32_16x16x32_bf16 v[114:117], v[226:229], v[184:187], v[114:117]
	v_mfma_f32_16x16x32_bf16 v[102:105], v[218:221], v[192:195], v[102:105]
	v_mfma_f32_16x16x32_bf16 v[98:101], v[226:229], v[192:195], v[98:101]
	v_mfma_f32_16x16x32_bf16 v[78:81], v[218:221], v[210:213], v[78:81]
	v_mfma_f32_16x16x32_bf16 v[74:77], v[226:229], v[210:213], v[74:77]
	v_mfma_f32_16x16x32_bf16 v[134:137], v[222:225], v[180:183], v[134:137]
	v_mfma_f32_16x16x32_bf16 v[130:133], v[230:233], v[180:183], v[130:133]
	v_mfma_f32_16x16x32_bf16 v[118:121], v[222:225], v[188:191], v[118:121]
	v_mfma_f32_16x16x32_bf16 v[114:117], v[230:233], v[188:191], v[114:117]
	v_mfma_f32_16x16x32_bf16 v[102:105], v[222:225], v[196:199], v[102:105]
	v_mfma_f32_16x16x32_bf16 v[98:101], v[230:233], v[196:199], v[98:101]
	v_mfma_f32_16x16x32_bf16 v[78:81], v[222:225], v[214:217], v[78:81]
	v_mfma_f32_16x16x32_bf16 v[74:77], v[230:233], v[214:217], v[74:77]
	s_mov_b32 m0, s39
	v_lshl_add_u64 v[170:171], v[234:235], 0, s[56:57]
	s_barrier
	ds_read_b128 v[176:179], v174 offset:49152
	ds_read_b128 v[180:183], v174 offset:50176
	ds_read_b128 v[184:187], v174 offset:51200
	ds_read_b128 v[188:191], v174 offset:52224
	ds_read_b128 v[192:195], v174 offset:53248
	ds_read_b128 v[196:199], v174 offset:54272
	ds_read_b128 v[210:213], v174 offset:55296
	ds_read_b128 v[214:217], v174 offset:56320
	global_load_lds_dwordx4 v[170:171], off
	v_lshl_add_u64 v[170:171], v[236:237], 0, s[56:57]
	s_mov_b32 m0, s40
	s_nop 0
	global_load_lds_dwordx4 v[170:171], off
	s_barrier
	s_waitcnt lgkmcnt(0)
	v_mfma_f32_16x16x32_bf16 v[62:65], v[66:69], v[176:179], v[62:65]
	v_mfma_f32_16x16x32_bf16 v[58:61], v[82:85], v[176:179], v[58:61]
	v_mfma_f32_16x16x32_bf16 v[46:49], v[66:69], v[184:187], v[46:49]
	v_mfma_f32_16x16x32_bf16 v[42:45], v[82:85], v[184:187], v[42:45]
	v_mfma_f32_16x16x32_bf16 v[30:33], v[66:69], v[192:195], v[30:33]
	v_mfma_f32_16x16x32_bf16 v[26:29], v[82:85], v[192:195], v[26:29]
	v_mfma_f32_16x16x32_bf16 v[14:17], v[66:69], v[210:213], v[14:17]
	v_mfma_f32_16x16x32_bf16 v[10:13], v[82:85], v[210:213], v[10:13]
	v_mfma_f32_16x16x32_bf16 v[62:65], v[70:73], v[180:183], v[62:65]
	v_mfma_f32_16x16x32_bf16 v[58:61], v[86:89], v[180:183], v[58:61]
	v_mfma_f32_16x16x32_bf16 v[46:49], v[70:73], v[188:191], v[46:49]
	v_mfma_f32_16x16x32_bf16 v[42:45], v[86:89], v[188:191], v[42:45]
	v_mfma_f32_16x16x32_bf16 v[30:33], v[70:73], v[196:199], v[30:33]
	v_mfma_f32_16x16x32_bf16 v[26:29], v[86:89], v[196:199], v[26:29]
	v_mfma_f32_16x16x32_bf16 v[14:17], v[70:73], v[214:217], v[14:17]
	v_mfma_f32_16x16x32_bf16 v[10:13], v[86:89], v[214:217], v[10:13]
	s_barrier
	s_add_u32 s20, s20, 0x80080
	s_addc_u32 s21, s21, 0
	s_add_i32 s22, s22, s31
	v_lshl_add_u64 v[66:67], s[20:21], 0, v[0:1]
	s_mov_b32 m0, s22
	s_nop 0
	global_load_lds_dwordx4 v[66:67], off
	v_lshl_add_u64 v[66:67], s[20:21], 0, v[164:165]
	s_add_i32 m0, s22, 0x2000
	s_nop 0
	global_load_lds_dwordx4 v[66:67], off
	s_waitcnt vmcnt(6)
	s_barrier
	v_mfma_f32_16x16x32_bf16 v[54:57], v[218:221], v[176:179], v[54:57]
	v_mfma_f32_16x16x32_bf16 v[50:53], v[226:229], v[176:179], v[50:53]
	v_mfma_f32_16x16x32_bf16 v[38:41], v[218:221], v[184:187], v[38:41]
	v_mfma_f32_16x16x32_bf16 v[34:37], v[226:229], v[184:187], v[34:37]
	v_mfma_f32_16x16x32_bf16 v[22:25], v[218:221], v[192:195], v[22:25]
	v_mfma_f32_16x16x32_bf16 v[18:21], v[226:229], v[192:195], v[18:21]
	v_mfma_f32_16x16x32_bf16 v[6:9], v[218:221], v[210:213], v[6:9]
	v_mfma_f32_16x16x32_bf16 v[2:5], v[226:229], v[210:213], v[2:5]
	v_mfma_f32_16x16x32_bf16 v[54:57], v[222:225], v[180:183], v[54:57]
	v_mfma_f32_16x16x32_bf16 v[50:53], v[230:233], v[180:183], v[50:53]
	v_mfma_f32_16x16x32_bf16 v[38:41], v[222:225], v[188:191], v[38:41]
	v_mfma_f32_16x16x32_bf16 v[34:37], v[230:233], v[188:191], v[34:37]
	v_mfma_f32_16x16x32_bf16 v[22:25], v[222:225], v[196:199], v[22:25]
	v_mfma_f32_16x16x32_bf16 v[18:21], v[230:233], v[196:199], v[18:21]
	v_mfma_f32_16x16x32_bf16 v[6:9], v[222:225], v[214:217], v[6:9]
	v_mfma_f32_16x16x32_bf16 v[2:5], v[230:233], v[214:217], v[2:5]
	s_add_i32 s49, s49, 2
	s_add_u32 s47, s47, 0x100
	s_addc_u32 s48, s48, 0
	s_add_u32 s18, s18, 0x100
	s_addc_u32 s19, s19, 0
	s_cmp_gt_u32 s49, 29
	s_barrier
; __device__ __forceinline__ unsigned pk2(float lo, float hi) { f32x2 v = {lo, hi}; return __builtin_bit_cast(unsigned, __builtin_convertvector(v, bf16x2_t)); }
; __device__ __forceinline__ float bf_lo(unsigned w) { return __uint_as_float(w << 16); }
; __device__ __forceinline__ float bf_hi(unsigned w) { return __uint_as_float(w & 0xffff0000u); }
;     __device__ __forceinline__ void operator()(const f32x4 (&acc)[2][2][4][2], const Unit& u, int wr, int wc, int fr, int fq) const {
;         asm volatile("" : "+v"(fr), "+v"(fq));
;         const int row0 = u.pm * BM + wr * 64 + fr, col0 = u.pn * BM + wc * 32 + 8 * fq;
;         const float* gp = gate + (size_t)(u.pm >> 5) * 12288 + col0;
;         f32x4 gv[2][2];
; #pragma unroll
;         for (int bj = 0; bj < 2; ++bj)
; #pragma unroll
;             for (int n = 0; n < 2; ++n) gv[bj][n] = *(const f32x4*)(gp + bj * HALF + 4 * n);
; #pragma unroll
;         for (int ai = 0; ai < 2; ++ai)
; #pragma unroll
;             for (int m = 0; m < 4; ++m) {
;                 const size_t ro = (size_t)(row0 + ai * HALF + m * 16) * DM + col0;
; #pragma unroll
;                 for (int bj = 0; bj < 2; ++bj) {
;                     f32x4 r0, r1;
;                     if (RB) { const u32x4 rw = *(const u32x4*)((const bf16_t*)resid + ro + bj * HALF);
;                         r0 = (f32x4){bf_lo(rw.x), bf_hi(rw.x), bf_lo(rw.y), bf_hi(rw.y)}; r1 = (f32x4){bf_lo(rw.z), bf_hi(rw.z), bf_lo(rw.w), bf_hi(rw.w)}; }
;                     else { r0 = *(const f32x4*)((const float*)resid + ro + bj * HALF); r1 = *(const f32x4*)((const float*)resid + ro + bj * HALF + 4); }
;                     const f32x4 v0 = r0 + gv[bj][0] * acc[ai][bj][m][0], v1 = r1 + gv[bj][1] * acc[ai][bj][m][1];
;                     if (OB) { u32x4 w; w.x = pk2(v0[0], v0[1]); w.y = pk2(v0[2], v0[3]); w.z = pk2(v1[0], v1[1]); w.w = pk2(v1[2], v1[3]); *(u32x4*)((bf16_t*)out + ro + bj * HALF) = w; }
;                     else { *(f32x4*)((float*)out + ro + bj * HALF) = v0; *(f32x4*)((float*)out + ro + bj * HALF + 4) = v1; }
;                 }
	s_cbranch_scc0 .LBB0_141
	s_setprio 0
	s_lshl_b32 s11, s2, 8
	s_lshl_b32 s13, s43, 8
	v_mov_b32_e32 v66, v172
	v_mov_b32_e32 v175, v159
	s_add_i32 s11, s11, s37
	s_or_b32 s13, s13, s38
	s_ashr_i32 s2, s2, 5
	s_mov_b32 s43, s10
	v_lshl_add_u32 v170, v66, 3, s13
	s_mul_hi_i32 s13, s2, 0xc000
	s_mul_i32 s2, s2, 0xc000
	v_add_u32_e32 v176, s11, v175
	s_add_u32 s18, s27, s2
	v_ashrrev_i32_e32 v177, 31, v176
	s_addc_u32 s19, s28, s13
	v_ashrrev_i32_e32 v171, 31, v170
	v_lshlrev_b64 v[176:177], 11, v[176:177]
	v_lshl_add_u64 v[70:71], v[170:171], 2, s[18:19]
	v_lshl_add_u64 v[170:171], v[176:177], 0, v[170:171]
	v_lshl_add_u64 v[184:185], v[170:171], 2, s[8:9]
	global_load_dwordx4 v[82:85], v[70:71], off offset:16
	global_load_dwordx4 v[86:89], v[70:71], off
	global_load_dwordx4 v[66:69], v[70:71], off offset:528
	s_nop 0
	global_load_dwordx4 v[70:73], v[70:71], off offset:512
	v_lshlrev_b32_e32 v175, 2, v170
	v_lshlrev_b32_e32 v200, 1, v170
	s_mov_b64 s[92:93], s[8:9]
	s_mov_b64 s[94:95], s[6:7]
	global_load_dwordx4 v[176:179], v175, s[92:93]
	global_load_dwordx4 v[180:183], v175, s[92:93] offset:16
	global_load_dwordx4 v[184:187], v175, s[92:93] offset:512
	global_load_dwordx4 v[188:191], v175, s[92:93] offset:528
	s_add_u32 s92, s92, 0x20000
	s_addc_u32 s93, s93, 0
	global_load_dwordx4 v[192:195], v175, s[92:93]
	global_load_dwordx4 v[196:199], v175, s[92:93] offset:16
	global_load_dwordx4 v[210:213], v175, s[92:93] offset:512
	global_load_dwordx4 v[214:217], v175, s[92:93] offset:528
	s_add_u32 s92, s92, 0x20000
	s_addc_u32 s93, s93, 0
	global_load_dwordx4 v[218:221], v175, s[92:93]
	global_load_dwordx4 v[222:225], v175, s[92:93] offset:16
	global_load_dwordx4 v[226:229], v175, s[92:93] offset:512
	global_load_dwordx4 v[230:233], v175, s[92:93] offset:528
	s_waitcnt vmcnt(10)
	v_pk_fma_f32 v[142:143], v[142:143], v[86:87], v[176:177]
	v_pk_fma_f32 v[144:145], v[144:145], v[88:89], v[178:179]
	v_pk_fma_f32 v[138:139], v[138:139], v[82:83], v[180:181]
	v_pk_fma_f32 v[140:141], v[140:141], v[84:85], v[182:183]
	s_add_u32 s92, s92, 0x20000
	s_addc_u32 s93, s93, 0
	global_load_dwordx4 v[176:179], v175, s[92:93]
	global_load_dwordx4 v[180:183], v175, s[92:93] offset:16
	v_cvt_pk_bf16_f32 v142, v142, v143
	v_cvt_pk_bf16_f32 v143, v144, v145
	v_cvt_pk_bf16_f32 v144, v138, v139
	v_cvt_pk_bf16_f32 v145, v140, v141
	global_store_dwordx4 v200, v[142:145], s[94:95]
	s_waitcnt vmcnt(11)
	v_pk_fma_f32 v[134:135], v[134:135], v[70:71], v[184:185]
	v_pk_fma_f32 v[136:137], v[136:137], v[72:73], v[186:187]
	v_pk_fma_f32 v[130:131], v[130:131], v[66:67], v[188:189]
	v_pk_fma_f32 v[132:133], v[132:133], v[68:69], v[190:191]
	global_load_dwordx4 v[184:187], v175, s[92:93] offset:512
	global_load_dwordx4 v[188:191], v175, s[92:93] offset:528
	v_cvt_pk_bf16_f32 v134, v134, v135
	v_cvt_pk_bf16_f32 v135, v136, v137
	v_cvt_pk_bf16_f32 v136, v130, v131
	v_cvt_pk_bf16_f32 v137, v132, v133
	global_store_dwordx4 v200, v[134:137], s[94:95] offset:256
	s_waitcnt vmcnt(12)
	v_pk_fma_f32 v[126:127], v[126:127], v[86:87], v[192:193]
	v_pk_fma_f32 v[128:129], v[128:129], v[88:89], v[194:195]
	v_pk_fma_f32 v[122:123], v[122:123], v[82:83], v[196:197]
	v_pk_fma_f32 v[124:125], v[124:125], v[84:85], v[198:199]
	s_add_u32 s92, s92, 0xa0000
	s_addc_u32 s93, s93, 0
	global_load_dwordx4 v[192:195], v175, s[92:93]
	global_load_dwordx4 v[196:199], v175, s[92:93] offset:16
	s_add_u32 s94, s94, 0x10000
	s_addc_u32 s95, s95, 0
	v_cvt_pk_bf16_f32 v126, v126, v127
	v_cvt_pk_bf16_f32 v127, v128, v129
	v_cvt_pk_bf16_f32 v128, v122, v123
	v_cvt_pk_bf16_f32 v129, v124, v125
	global_store_dwordx4 v200, v[126:129], s[94:95]
	s_waitcnt vmcnt(13)
	v_pk_fma_f32 v[118:119], v[118:119], v[70:71], v[210:211]
	v_pk_fma_f32 v[120:121], v[120:121], v[72:73], v[212:213]
	v_pk_fma_f32 v[114:115], v[114:115], v[66:67], v[214:215]
	v_pk_fma_f32 v[116:117], v[116:117], v[68:69], v[216:217]
	global_load_dwordx4 v[210:213], v175, s[92:93] offset:512
	global_load_dwordx4 v[214:217], v175, s[92:93] offset:528
	v_cvt_pk_bf16_f32 v118, v118, v119
	v_cvt_pk_bf16_f32 v119, v120, v121
	v_cvt_pk_bf16_f32 v120, v114, v115
	v_cvt_pk_bf16_f32 v121, v116, v117
	global_store_dwordx4 v200, v[118:121], s[94:95] offset:256
	s_waitcnt vmcnt(14)
	v_pk_fma_f32 v[110:111], v[110:111], v[86:87], v[218:219]
	v_pk_fma_f32 v[112:113], v[112:113], v[88:89], v[220:221]
	v_pk_fma_f32 v[106:107], v[106:107], v[82:83], v[222:223]
	v_pk_fma_f32 v[108:109], v[108:109], v[84:85], v[224:225]
	s_add_u32 s92, s92, 0x20000
	s_addc_u32 s93, s93, 0
	global_load_dwordx4 v[218:221], v175, s[92:93]
	global_load_dwordx4 v[222:225], v175, s[92:93] offset:16
	s_add_u32 s94, s94, 0x10000
	s_addc_u32 s95, s95, 0
	v_cvt_pk_bf16_f32 v110, v110, v111
	v_cvt_pk_bf16_f32 v111, v112, v113
	v_cvt_pk_bf16_f32 v112, v106, v107
	v_cvt_pk_bf16_f32 v113, v108, v109
	global_store_dwordx4 v200, v[110:113], s[94:95]
	s_waitcnt vmcnt(15)
	v_pk_fma_f32 v[102:103], v[102:103], v[70:71], v[226:227]
	v_pk_fma_f32 v[104:105], v[104:105], v[72:73], v[228:229]
	v_pk_fma_f32 v[98:99], v[98:99], v[66:67], v[230:231]
	v_pk_fma_f32 v[100:101], v[100:101], v[68:69], v[232:233]
	global_load_dwordx4 v[226:229], v175, s[92:93] offset:512
	global_load_dwordx4 v[230:233], v175, s[92:93] offset:528
	v_cvt_pk_bf16_f32 v102, v102, v103
	v_cvt_pk_bf16_f32 v103, v104, v105
	v_cvt_pk_bf16_f32 v104, v98, v99
	v_cvt_pk_bf16_f32 v105, v100, v101
	global_store_dwordx4 v200, v[102:105], s[94:95] offset:256
	s_waitcnt vmcnt(16)
; __device__ __forceinline__ unsigned pk2(float lo, float hi) { f32x2 v = {lo, hi}; return __builtin_bit_cast(unsigned, __builtin_convertvector(v, bf16x2_t)); }
; __device__ __forceinline__ float bf_lo(unsigned w) { return __uint_as_float(w << 16); }
; __device__ __forceinline__ float bf_hi(unsigned w) { return __uint_as_float(w & 0xffff0000u); }
; #define PG8_WAIT_V(n) asm volatile("s_waitcnt vmcnt(" #n ")" ::: "memory")
; #define PG8_BAR __builtin_amdgcn_s_barrier()
;     __device__ __forceinline__ void operator()(const f32x4 (&acc)[2][2][4][2], const Unit& u, int wr, int wc, int fr, int fq) const {
;     ...
;             for (int m = 0; m < 4; ++m) {
;                 const size_t ro = (size_t)(row0 + ai * HALF + m * 16) * DM + col0;
; #pragma unroll
;                 for (int bj = 0; bj < 2; ++bj) {
;                     f32x4 r0, r1;
;                     if (RB) { const u32x4 rw = *(const u32x4*)((const bf16_t*)resid + ro + bj * HALF);
;                         r0 = (f32x4){bf_lo(rw.x), bf_hi(rw.x), bf_lo(rw.y), bf_hi(rw.y)}; r1 = (f32x4){bf_lo(rw.z), bf_hi(rw.z), bf_lo(rw.w), bf_hi(rw.w)}; }
;                     else { r0 = *(const f32x4*)((const float*)resid + ro + bj * HALF); r1 = *(const f32x4*)((const float*)resid + ro + bj * HALF + 4); }
;                     const f32x4 v0 = r0 + gv[bj][0] * acc[ai][bj][m][0], v1 = r1 + gv[bj][1] * acc[ai][bj][m][1];
;                     if (OB) { u32x4 w; w.x = pk2(v0[0], v0[1]); w.y = pk2(v0[2], v0[3]); w.z = pk2(v1[0], v1[1]); w.w = pk2(v1[2], v1[3]); *(u32x4*)((bf16_t*)out + ro + bj * HALF) = w; }
;                     else { *(f32x4*)((float*)out + ro + bj * HALF) = v0; *(f32x4*)((float*)out + ro + bj * HALF + 4) = v1; }
;                 }
; template <class Epi>
; __device__ __forceinline__ void gemm_phase(LAS unsigned char* lds, const Gemm g, const StaticOrder& S, const Epi& E, const int tid) {
;     ...
;         E(acc, cur, wr, wc, fr, fq);
;         if (!has_next) break;
; #pragma unroll
;         for (int a = 0; a < 2; ++a)
; #pragma unroll
;             for (int b = 0; b < 2; ++b)
; #pragma unroll
;                 for (int m = 0; m < 4; ++m)
; #pragma unroll
;                     for (int n = 0; n < 2; ++n) acc[a][b][m][n] = (f32x4){0.f, 0.f, 0.f, 0.f};
;         cur = nxt; cA = nA; cB = nB; ++ui;
;     }
;     PG8_WAIT_V(0);
;     if (wr == 0) PG8_BAR;
	v_pk_fma_f32 v[94:95], v[94:95], v[86:87], v[176:177]
	v_pk_fma_f32 v[96:97], v[96:97], v[88:89], v[178:179]
	v_pk_fma_f32 v[90:91], v[90:91], v[82:83], v[180:181]
	v_pk_fma_f32 v[92:93], v[92:93], v[84:85], v[182:183]
	s_add_u32 s92, s92, 0x20000
	s_addc_u32 s93, s93, 0
	global_load_dwordx4 v[176:179], v175, s[92:93]
	global_load_dwordx4 v[180:183], v175, s[92:93] offset:16
	s_add_u32 s94, s94, 0x10000
	s_addc_u32 s95, s95, 0
	v_cvt_pk_bf16_f32 v94, v94, v95
	v_cvt_pk_bf16_f32 v95, v96, v97
	v_cvt_pk_bf16_f32 v96, v90, v91
	v_cvt_pk_bf16_f32 v97, v92, v93
	global_store_dwordx4 v200, v[94:97], s[94:95]
	s_waitcnt vmcnt(16)
	v_pk_fma_f32 v[78:79], v[78:79], v[70:71], v[184:185]
	v_pk_fma_f32 v[80:81], v[80:81], v[72:73], v[186:187]
	v_pk_fma_f32 v[74:75], v[74:75], v[66:67], v[188:189]
	v_pk_fma_f32 v[76:77], v[76:77], v[68:69], v[190:191]
	global_load_dwordx4 v[184:187], v175, s[92:93] offset:512
	global_load_dwordx4 v[188:191], v175, s[92:93] offset:528
	v_cvt_pk_bf16_f32 v78, v78, v79
	v_cvt_pk_bf16_f32 v79, v80, v81
	v_cvt_pk_bf16_f32 v80, v74, v75
	v_cvt_pk_bf16_f32 v81, v76, v77
	global_store_dwordx4 v200, v[78:81], s[94:95] offset:256
	s_waitcnt vmcnt(16)
	v_pk_fma_f32 v[62:63], v[62:63], v[86:87], v[192:193]
	v_pk_fma_f32 v[64:65], v[64:65], v[88:89], v[194:195]
	v_pk_fma_f32 v[58:59], v[58:59], v[82:83], v[196:197]
	v_pk_fma_f32 v[60:61], v[60:61], v[84:85], v[198:199]
	s_add_u32 s92, s92, 0x20000
	s_addc_u32 s93, s93, 0
	global_load_dwordx4 v[192:195], v175, s[92:93]
	global_load_dwordx4 v[196:199], v175, s[92:93] offset:16
	s_add_u32 s94, s94, 0x50000
	s_addc_u32 s95, s95, 0
	v_cvt_pk_bf16_f32 v62, v62, v63
	v_cvt_pk_bf16_f32 v63, v64, v65
	v_cvt_pk_bf16_f32 v64, v58, v59
	v_cvt_pk_bf16_f32 v65, v60, v61
	global_store_dwordx4 v200, v[62:65], s[94:95]
	s_waitcnt vmcnt(16)
	v_pk_fma_f32 v[54:55], v[54:55], v[70:71], v[210:211]
	v_pk_fma_f32 v[56:57], v[56:57], v[72:73], v[212:213]
	v_pk_fma_f32 v[50:51], v[50:51], v[66:67], v[214:215]
	v_pk_fma_f32 v[52:53], v[52:53], v[68:69], v[216:217]
	global_load_dwordx4 v[210:213], v175, s[92:93] offset:512
	global_load_dwordx4 v[214:217], v175, s[92:93] offset:528
	v_cvt_pk_bf16_f32 v54, v54, v55
	v_cvt_pk_bf16_f32 v55, v56, v57
	v_cvt_pk_bf16_f32 v56, v50, v51
	v_cvt_pk_bf16_f32 v57, v52, v53
	global_store_dwordx4 v200, v[54:57], s[94:95] offset:256
	s_waitcnt vmcnt(16)
	v_pk_fma_f32 v[46:47], v[46:47], v[86:87], v[218:219]
	v_pk_fma_f32 v[48:49], v[48:49], v[88:89], v[220:221]
	v_pk_fma_f32 v[42:43], v[42:43], v[82:83], v[222:223]
	v_pk_fma_f32 v[44:45], v[44:45], v[84:85], v[224:225]
	s_add_u32 s94, s94, 0x10000
	s_addc_u32 s95, s95, 0
	v_cvt_pk_bf16_f32 v46, v46, v47
	v_cvt_pk_bf16_f32 v47, v48, v49
	v_cvt_pk_bf16_f32 v48, v42, v43
	v_cvt_pk_bf16_f32 v49, v44, v45
	global_store_dwordx4 v200, v[46:49], s[94:95]
	s_waitcnt vmcnt(14)
	v_pk_fma_f32 v[38:39], v[38:39], v[70:71], v[226:227]
	v_pk_fma_f32 v[40:41], v[40:41], v[72:73], v[228:229]
	v_pk_fma_f32 v[34:35], v[34:35], v[66:67], v[230:231]
	v_pk_fma_f32 v[36:37], v[36:37], v[68:69], v[232:233]
	v_cvt_pk_bf16_f32 v38, v38, v39
	v_cvt_pk_bf16_f32 v39, v40, v41
	v_cvt_pk_bf16_f32 v40, v34, v35
	v_cvt_pk_bf16_f32 v41, v36, v37
	global_store_dwordx4 v200, v[38:41], s[94:95] offset:256
	s_waitcnt vmcnt(12)
	v_pk_fma_f32 v[30:31], v[30:31], v[86:87], v[176:177]
	v_pk_fma_f32 v[32:33], v[32:33], v[88:89], v[178:179]
	v_pk_fma_f32 v[26:27], v[26:27], v[82:83], v[180:181]
	v_pk_fma_f32 v[28:29], v[28:29], v[84:85], v[182:183]
	s_add_u32 s94, s94, 0x10000
	s_addc_u32 s95, s95, 0
	v_cvt_pk_bf16_f32 v30, v30, v31
	v_cvt_pk_bf16_f32 v31, v32, v33
	v_cvt_pk_bf16_f32 v32, v26, v27
	v_cvt_pk_bf16_f32 v33, v28, v29
	global_store_dwordx4 v200, v[30:33], s[94:95]
	s_waitcnt vmcnt(10)
	v_pk_fma_f32 v[22:23], v[22:23], v[70:71], v[184:185]
	v_pk_fma_f32 v[24:25], v[24:25], v[72:73], v[186:187]
	v_pk_fma_f32 v[18:19], v[18:19], v[66:67], v[188:189]
	v_pk_fma_f32 v[20:21], v[20:21], v[68:69], v[190:191]
	v_cvt_pk_bf16_f32 v22, v22, v23
	v_cvt_pk_bf16_f32 v23, v24, v25
	v_cvt_pk_bf16_f32 v24, v18, v19
	v_cvt_pk_bf16_f32 v25, v20, v21
	global_store_dwordx4 v200, v[22:25], s[94:95] offset:256
	s_waitcnt vmcnt(8)
	v_pk_fma_f32 v[14:15], v[14:15], v[86:87], v[192:193]
	v_pk_fma_f32 v[16:17], v[16:17], v[88:89], v[194:195]
	v_pk_fma_f32 v[10:11], v[10:11], v[82:83], v[196:197]
	v_pk_fma_f32 v[12:13], v[12:13], v[84:85], v[198:199]
	s_add_u32 s94, s94, 0x10000
	s_addc_u32 s95, s95, 0
	v_cvt_pk_bf16_f32 v14, v14, v15
	v_cvt_pk_bf16_f32 v15, v16, v17
	v_cvt_pk_bf16_f32 v16, v10, v11
	v_cvt_pk_bf16_f32 v17, v12, v13
	global_store_dwordx4 v200, v[14:17], s[94:95]
	s_waitcnt vmcnt(6)
	v_pk_fma_f32 v[6:7], v[6:7], v[70:71], v[210:211]
	v_pk_fma_f32 v[8:9], v[8:9], v[72:73], v[212:213]
	v_pk_fma_f32 v[2:3], v[2:3], v[66:67], v[214:215]
	v_pk_fma_f32 v[4:5], v[4:5], v[68:69], v[216:217]
	v_cvt_pk_bf16_f32 v6, v6, v7
	v_cvt_pk_bf16_f32 v7, v8, v9
	v_cvt_pk_bf16_f32 v8, v2, v3
	v_cvt_pk_bf16_f32 v9, v4, v5
	global_store_dwordx4 v200, v[6:9], s[94:95] offset:256
	s_mov_b32 s2, s12
	s_mov_b64 s[20:21], s[14:15]
	s_mov_b64 s[18:19], s[16:17]
	s_and_b64 vcc, exec, s[4:5]
	s_nop 1
	s_cbranch_vccz .LBB0_134
	s_waitcnt vmcnt(0)
	s_cmpk_gt_u32 s29, 0xff
	s_cbranch_scc1 .LBB0_145
	s_barrier

; #define PG8_STAGE(bufoff, gbase, voff) do { _Pragma("unroll") for (int _i = 0; _i < 2; ++_i) \
;         __builtin_amdgcn_global_load_lds((const unsigned*)((const char*)(gbase) + (voff)[_i]), (LAS unsigned*)(lds + (bufoff) + ldsw + _i * 8192), 16, 0, 0); } while (0)
; #define PG8_LDA(dst, b, h) do { _Pragma("unroll") for (int m = 0; m < 4; ++m) _Pragma("unroll") for (int k = 0; k < 2; ++k) dst[m][k] = *(const LAS bf16x8*)(lds + PG8_SA(b, h) + aoff + m * 2048 + k * 1024); } while (0)
; #define PG8_LDB(dst, b, h) do { _Pragma("unroll") for (int n = 0; n < 2; ++n) _Pragma("unroll") for (int k = 0; k < 2; ++k) dst[n][k] = *(const LAS bf16x8*)(lds + PG8_SB(b, h) + boff + n * 2048 + k * 1024); } while (0)
; #define PG8_MMA(ai, bj, At, Bt) do { __builtin_amdgcn_s_setprio(1); _Pragma("unroll") for (int m = 0; m < 4; ++m) _Pragma("unroll") for (int n = 0; n < 2; ++n) _Pragma("unroll") for (int k = 0; k < 2; ++k) \
;         acc[ai][bj][m][n] = __builtin_amdgcn_mfma_f32_16x16x32_bf16(Bt[n][k], At[m][k], acc[ai][bj][m][n], 0, 0, 0); __builtin_amdgcn_s_setprio(0); } while (0)
; #define PG8_BAR __builtin_amdgcn_s_barrier()
; template <class Epi>
; __device__ __forceinline__ void gemm_phase(LAS unsigned char* lds, const Gemm g, const StaticOrder& S, const Epi& E, const int tid) {
;     ...
;         const bool has_next = S.next(ui + 1, nxt);
;         const char* nA = has_next ? (const char*)g.A + (size_t)nxt.pm * tstep : cA; const char* nB = has_next ? (const char*)g.Bt + (size_t)nxt.pn * tstep : cB;
;         for (int t = 0; t < nt; t += 2) {
;             const bool last = (t == nt - 2);
;             const char* a1 = cA + (size_t)(t + 1) * kstep;
;             const char* a2 = last ? nA : cA + (size_t)(t + 2) * kstep; const char* b2 = last ? nB : cB + (size_t)(t + 2) * kstep;
;             const char* a3 = a2 + kstep; const char* b3 = b2 + kstep;
;             PG8_LDB(B0, 0, 0); PG8_SCHED; PG8_LDA(At, 0, 0); PG8_STAGE(PG8_SA(1, 1), a1 + hstep, voffA);
;             PG8_WAIT_L(8); PG8_BAR; PG8_WAIT_L(0); PG8_MMA(0, 0, At, B0); PG8_BAR; PG8_SCHED;
;     ...
; #pragma unroll
;         for (int a = 0; a < 2; ++a)
; #pragma unroll
;             for (int b = 0; b < 2; ++b)
; #pragma unroll
;                 for (int m = 0; m < 4; ++m)
; #pragma unroll
;                     for (int n = 0; n < 2; ++n) acc[a][b][m][n] = (f32x4){0.f, 0.f, 0.f, 0.f};
;         cur = nxt; cA = nA; cB = nB; ++ui;
.LBB0_285:
	s_ashr_i32 s27, s26, 31
	v_cmp_lt_i64_e32 vcc, s[6:7], v[156:157]
	s_lshl_b64 s[6:7], s[26:27], 20
	s_add_u32 s28, s1, s6
	s_addc_u32 s29, s38, s7
	s_and_b64 s[6:7], vcc, exec
	s_cselect_b32 s3, s29, s37
	s_cselect_b32 s27, s28, s36
	s_ashr_i32 s25, s24, 31
	s_lshl_b64 s[6:7], s[24:25], 20
	s_add_u32 s30, s78, s6
	s_addc_u32 s31, s79, s7
	s_and_b64 s[6:7], vcc, exec
	s_cselect_b32 s25, s31, s35
	s_cselect_b32 s50, s30, s34
	s_add_u32 s66, s34, 0x100
	s_addc_u32 s72, s35, 0
	s_add_u32 s6, s36, 0x80080
	v_mov_b32_e32 v2, 0
	s_addc_u32 s7, s37, 0
	s_mov_b32 s36, -2
	v_mov_b32_e32 v3, v2
	v_mov_b32_e32 v4, v2
	v_mov_b32_e32 v5, v2
	v_mov_b32_e32 v6, v2
	v_mov_b32_e32 v7, v2
	v_mov_b32_e32 v8, v2
	v_mov_b32_e32 v9, v2
	v_mov_b32_e32 v10, v2
	v_mov_b32_e32 v11, v2
	v_mov_b32_e32 v12, v2
	v_mov_b32_e32 v13, v2
	v_mov_b32_e32 v14, v2
	v_mov_b32_e32 v15, v2
	v_mov_b32_e32 v16, v2
	v_mov_b32_e32 v17, v2
	v_mov_b32_e32 v26, v2
	v_mov_b32_e32 v27, v2
	v_mov_b32_e32 v28, v2
	v_mov_b32_e32 v29, v2
	v_mov_b32_e32 v30, v2
	v_mov_b32_e32 v31, v2
	v_mov_b32_e32 v32, v2
	v_mov_b32_e32 v33, v2
	v_mov_b32_e32 v42, v2
	v_mov_b32_e32 v43, v2
	v_mov_b32_e32 v44, v2
	v_mov_b32_e32 v45, v2
	v_mov_b32_e32 v46, v2
	v_mov_b32_e32 v47, v2
	v_mov_b32_e32 v48, v2
	v_mov_b32_e32 v49, v2
	v_mov_b32_e32 v18, v2
	v_mov_b32_e32 v19, v2
	v_mov_b32_e32 v20, v2
	v_mov_b32_e32 v21, v2
	v_mov_b32_e32 v22, v2
	v_mov_b32_e32 v23, v2
	v_mov_b32_e32 v24, v2
	v_mov_b32_e32 v25, v2
	v_mov_b32_e32 v34, v2
	v_mov_b32_e32 v35, v2
	v_mov_b32_e32 v36, v2
	v_mov_b32_e32 v37, v2
	v_mov_b32_e32 v38, v2
	v_mov_b32_e32 v39, v2
	v_mov_b32_e32 v40, v2
	v_mov_b32_e32 v41, v2
	v_mov_b32_e32 v50, v2
	v_mov_b32_e32 v51, v2
	v_mov_b32_e32 v52, v2
	v_mov_b32_e32 v53, v2
	v_mov_b32_e32 v54, v2
	v_mov_b32_e32 v55, v2
	v_mov_b32_e32 v56, v2
	v_mov_b32_e32 v57, v2
	v_mov_b32_e32 v58, v2
	v_mov_b32_e32 v59, v2
	v_mov_b32_e32 v60, v2
	v_mov_b32_e32 v61, v2
	v_mov_b32_e32 v62, v2
	v_mov_b32_e32 v63, v2
	v_mov_b32_e32 v64, v2
	v_mov_b32_e32 v65, v2
	v_mov_b32_e32 v66, v2
	v_mov_b32_e32 v67, v2
	v_mov_b32_e32 v68, v2
	v_mov_b32_e32 v69, v2
	v_mov_b32_e32 v70, v2
	v_mov_b32_e32 v71, v2
	v_mov_b32_e32 v72, v2
	v_mov_b32_e32 v73, v2
	v_mov_b32_e32 v74, v2
	v_mov_b32_e32 v75, v2
	v_mov_b32_e32 v76, v2
	v_mov_b32_e32 v77, v2
	v_mov_b32_e32 v78, v2
	v_mov_b32_e32 v79, v2
	v_mov_b32_e32 v80, v2
	v_mov_b32_e32 v81, v2
	v_mov_b32_e32 v90, v2
	v_mov_b32_e32 v91, v2
	v_mov_b32_e32 v92, v2
	v_mov_b32_e32 v93, v2
	v_mov_b32_e32 v94, v2
	v_mov_b32_e32 v95, v2
	v_mov_b32_e32 v96, v2
	v_mov_b32_e32 v97, v2
	v_mov_b32_e32 v106, v2
	v_mov_b32_e32 v107, v2
	v_mov_b32_e32 v108, v2
	v_mov_b32_e32 v109, v2
	v_mov_b32_e32 v110, v2
	v_mov_b32_e32 v111, v2
	v_mov_b32_e32 v112, v2
	v_mov_b32_e32 v113, v2
	v_mov_b32_e32 v82, v2
	v_mov_b32_e32 v83, v2
	v_mov_b32_e32 v84, v2
	v_mov_b32_e32 v85, v2
	v_mov_b32_e32 v86, v2
	v_mov_b32_e32 v87, v2
	v_mov_b32_e32 v88, v2
	v_mov_b32_e32 v89, v2
	v_mov_b32_e32 v98, v2
	v_mov_b32_e32 v99, v2
	v_mov_b32_e32 v100, v2
	v_mov_b32_e32 v101, v2
	v_mov_b32_e32 v102, v2
	v_mov_b32_e32 v103, v2
	v_mov_b32_e32 v104, v2
	v_mov_b32_e32 v105, v2
	v_mov_b32_e32 v114, v2
	v_mov_b32_e32 v115, v2
	v_mov_b32_e32 v116, v2
	v_mov_b32_e32 v117, v2
	v_mov_b32_e32 v118, v2
	v_mov_b32_e32 v119, v2
	v_mov_b32_e32 v120, v2
	v_mov_b32_e32 v121, v2
	v_mov_b32_e32 v122, v2
	v_mov_b32_e32 v123, v2
	v_mov_b32_e32 v124, v2
	v_mov_b32_e32 v125, v2
	v_mov_b32_e32 v126, v2
	v_mov_b32_e32 v127, v2
	v_mov_b32_e32 v128, v2
	v_mov_b32_e32 v129, v2
	v_readfirstlane_b32 s32, v158
	s_cmpk_lt_u32 s32, 0x100
	s_cbranch_scc1 .Lgprio5
	s_setprio 1
.Lgprio5:
.LBB0_286:
	s_add_u32 s8, s6, 0xfff80080
	s_addc_u32 s9, s7, -1
	s_add_i32 s37, 0, 0x10000
	v_add_u32_e32 v0, s37, v210
	ds_read_b128 v[130:133], v0
	ds_read_b128 v[134:137], v0 offset:1024
	ds_read_b128 v[138:141], v0 offset:2048
	ds_read_b128 v[142:145], v0 offset:3072
	s_cmp_eq_u32 s36, 28
	s_cselect_b32 s35, s3, s9
	s_cselect_b32 s34, s27, s8
	s_cselect_b32 s9, s25, s72
	s_cselect_b32 s8, s50, s66
	v_lshl_add_u64 v[200:201], s[6:7], 0, v[170:171]
	s_add_i32 m0, s21, 0xc000
	ds_read_b128 v[172:175], v211
	ds_read_b128 v[176:179], v211 offset:1024
	ds_read_b128 v[180:183], v211 offset:2048
	ds_read_b128 v[184:187], v211 offset:3072
	ds_read_b128 v[188:191], v211 offset:4096
	ds_read_b128 v[192:195], v211 offset:5120
	ds_read_b128 v[196:199], v211 offset:6144
	ds_read_b128 v[212:215], v211 offset:7168
	global_load_lds_dwordx4 v[200:201], off
	v_lshl_add_u64 v[200:201], s[6:7], 0, v[168:169]
	s_add_i32 m0, s21, 0xe000
	s_nop 0
	global_load_lds_dwordx4 v[200:201], off
	s_waitcnt lgkmcnt(8)
	s_barrier
	s_waitcnt lgkmcnt(0)
	v_mfma_f32_16x16x32_bf16 v[126:129], v[130:133], v[172:175], v[126:129]
	v_mfma_f32_16x16x32_bf16 v[122:125], v[138:141], v[172:175], v[122:125]
	v_mfma_f32_16x16x32_bf16 v[118:121], v[130:133], v[180:183], v[118:121]
	v_mfma_f32_16x16x32_bf16 v[114:117], v[138:141], v[180:183], v[114:117]
	v_mfma_f32_16x16x32_bf16 v[102:105], v[130:133], v[188:191], v[102:105]
	v_mfma_f32_16x16x32_bf16 v[98:101], v[138:141], v[188:191], v[98:101]
	v_mfma_f32_16x16x32_bf16 v[86:89], v[130:133], v[196:199], v[86:89]
	v_mfma_f32_16x16x32_bf16 v[82:85], v[138:141], v[196:199], v[82:85]
	v_mfma_f32_16x16x32_bf16 v[126:129], v[134:137], v[176:179], v[126:129]
	v_mfma_f32_16x16x32_bf16 v[122:125], v[142:145], v[176:179], v[122:125]
	v_mfma_f32_16x16x32_bf16 v[118:121], v[134:137], v[184:187], v[118:121]
	v_mfma_f32_16x16x32_bf16 v[114:117], v[142:145], v[184:187], v[114:117]
	v_mfma_f32_16x16x32_bf16 v[102:105], v[134:137], v[192:195], v[102:105]
	v_mfma_f32_16x16x32_bf16 v[98:101], v[142:145], v[192:195], v[98:101]
	v_mfma_f32_16x16x32_bf16 v[86:89], v[134:137], v[212:215], v[86:89]
	v_mfma_f32_16x16x32_bf16 v[82:85], v[142:145], v[212:215], v[82:85]
	s_barrier
; #define PG8_STAGE(bufoff, gbase, voff) do { _Pragma("unroll") for (int _i = 0; _i < 2; ++_i) \
;         __builtin_amdgcn_global_load_lds((const unsigned*)((const char*)(gbase) + (voff)[_i]), (LAS unsigned*)(lds + (bufoff) + ldsw + _i * 8192), 16, 0, 0); } while (0)
; #define PG8_LDA(dst, b, h) do { _Pragma("unroll") for (int m = 0; m < 4; ++m) _Pragma("unroll") for (int k = 0; k < 2; ++k) dst[m][k] = *(const LAS bf16x8*)(lds + PG8_SA(b, h) + aoff + m * 2048 + k * 1024); } while (0)
; #define PG8_LDB(dst, b, h) do { _Pragma("unroll") for (int n = 0; n < 2; ++n) _Pragma("unroll") for (int k = 0; k < 2; ++k) dst[n][k] = *(const LAS bf16x8*)(lds + PG8_SB(b, h) + boff + n * 2048 + k * 1024); } while (0)
; #define PG8_MMA(ai, bj, At, Bt) do { __builtin_amdgcn_s_setprio(1); _Pragma("unroll") for (int m = 0; m < 4; ++m) _Pragma("unroll") for (int n = 0; n < 2; ++n) _Pragma("unroll") for (int k = 0; k < 2; ++k) \
;         acc[ai][bj][m][n] = __builtin_amdgcn_mfma_f32_16x16x32_bf16(Bt[n][k], At[m][k], acc[ai][bj][m][n], 0, 0, 0); __builtin_amdgcn_s_setprio(0); } while (0)
; #define PG8_WAIT_V(n) asm volatile("s_waitcnt vmcnt(" #n ")" ::: "memory")
; #define PG8_WAIT_L(n) asm volatile("s_waitcnt lgkmcnt(" #n ")" ::: "memory")
; #define PG8_BAR __builtin_amdgcn_s_barrier()
; #define PG8_SCHED __builtin_amdgcn_sched_barrier(0)
; template <class Epi>
; __device__ __forceinline__ void gemm_phase(LAS unsigned char* lds, const Gemm g, const StaticOrder& S, const Epi& E, const int tid) {
;     ...
;             PG8_LDB(B1, 0, 1); PG8_STAGE(PG8_SB(0, 0), b2, voffB);
;             PG8_BAR; PG8_WAIT_L(0); PG8_MMA(0, 1, At, B1); PG8_BAR;
;             PG8_LDA(At, 0, 1); PG8_STAGE(PG8_SA(0, 0), a2, voffA);
;             PG8_BAR; PG8_WAIT_L(0); PG8_MMA(1, 0, At, B0); PG8_BAR; PG8_SCHED;
;             PG8_STAGE(PG8_SB(0, 1), b2 + hstep, voffB);
;             PG8_WAIT_V(6); PG8_BAR; PG8_MMA(1, 1, At, B1); PG8_BAR;
;             PG8_LDB(B0, 1, 0); PG8_SCHED; PG8_LDA(At, 1, 0); PG8_STAGE(PG8_SA(0, 1), a2 + hstep, voffA);
;             PG8_WAIT_L(8); PG8_BAR; PG8_WAIT_L(0); PG8_MMA(0, 0, At, B0); PG8_BAR; PG8_SCHED;
	s_add_i32 s73, 0, 0x14000
	s_add_i32 s37, s37, s39
	v_add_u32_e32 v0, s73, v210
	v_lshl_add_u64 v[200:201], s[8:9], 0, v[162:163]
	s_mov_b32 m0, s37
	ds_read_b128 v[216:219], v0
	ds_read_b128 v[220:223], v0 offset:1024
	ds_read_b128 v[224:227], v0 offset:2048
	ds_read_b128 v[228:231], v0 offset:3072
	global_load_lds_dwordx4 v[200:201], off
	v_lshl_add_u64 v[232:233], s[8:9], 0, v[166:167]
	s_add_i32 m0, s37, 0x2000
	s_nop 0
	global_load_lds_dwordx4 v[232:233], off
	s_barrier
	s_waitcnt lgkmcnt(0)
	v_mfma_f32_16x16x32_bf16 v[110:113], v[216:219], v[172:175], v[110:113]
	v_mfma_f32_16x16x32_bf16 v[106:109], v[224:227], v[172:175], v[106:109]
	v_mfma_f32_16x16x32_bf16 v[94:97], v[216:219], v[180:183], v[94:97]
	v_mfma_f32_16x16x32_bf16 v[90:93], v[224:227], v[180:183], v[90:93]
	v_mfma_f32_16x16x32_bf16 v[78:81], v[216:219], v[188:191], v[78:81]
	v_mfma_f32_16x16x32_bf16 v[74:77], v[224:227], v[188:191], v[74:77]
	v_mfma_f32_16x16x32_bf16 v[70:73], v[216:219], v[196:199], v[70:73]
	v_mfma_f32_16x16x32_bf16 v[66:69], v[224:227], v[196:199], v[66:69]
	v_mfma_f32_16x16x32_bf16 v[110:113], v[220:223], v[176:179], v[110:113]
	v_mfma_f32_16x16x32_bf16 v[106:109], v[228:231], v[176:179], v[106:109]
	v_mfma_f32_16x16x32_bf16 v[94:97], v[220:223], v[184:187], v[94:97]
	v_mfma_f32_16x16x32_bf16 v[90:93], v[228:231], v[184:187], v[90:93]
	v_mfma_f32_16x16x32_bf16 v[78:81], v[220:223], v[192:195], v[78:81]
	v_mfma_f32_16x16x32_bf16 v[74:77], v[228:231], v[192:195], v[74:77]
	v_mfma_f32_16x16x32_bf16 v[70:73], v[220:223], v[212:215], v[70:73]
	v_mfma_f32_16x16x32_bf16 v[66:69], v[228:231], v[212:215], v[66:69]
	s_mov_b32 m0, s21
	v_lshl_add_u64 v[234:235], s[34:35], 0, v[160:161]
	s_barrier
	ds_read_b128 v[172:175], v211 offset:16384
	ds_read_b128 v[176:179], v211 offset:17408
	ds_read_b128 v[180:183], v211 offset:18432
	ds_read_b128 v[184:187], v211 offset:19456
	ds_read_b128 v[188:191], v211 offset:20480
	ds_read_b128 v[192:195], v211 offset:21504
	ds_read_b128 v[196:199], v211 offset:22528
	ds_read_b128 v[212:215], v211 offset:23552
	global_load_lds_dwordx4 v[234:235], off
	v_lshl_add_u64 v[236:237], s[34:35], 0, v[164:165]
	s_mov_b32 m0, s40
	s_nop 0
	global_load_lds_dwordx4 v[236:237], off
	s_barrier
	s_waitcnt lgkmcnt(0)
	v_mfma_f32_16x16x32_bf16 v[62:65], v[130:133], v[172:175], v[62:65]
	v_mfma_f32_16x16x32_bf16 v[58:61], v[138:141], v[172:175], v[58:61]
	v_mfma_f32_16x16x32_bf16 v[54:57], v[130:133], v[180:183], v[54:57]
	v_mfma_f32_16x16x32_bf16 v[50:53], v[138:141], v[180:183], v[50:53]
	v_mfma_f32_16x16x32_bf16 v[38:41], v[130:133], v[188:191], v[38:41]
	v_mfma_f32_16x16x32_bf16 v[34:37], v[138:141], v[188:191], v[34:37]
	v_mfma_f32_16x16x32_bf16 v[22:25], v[130:133], v[196:199], v[22:25]
	v_mfma_f32_16x16x32_bf16 v[18:21], v[138:141], v[196:199], v[18:21]
	v_mfma_f32_16x16x32_bf16 v[62:65], v[134:137], v[176:179], v[62:65]
	v_mfma_f32_16x16x32_bf16 v[58:61], v[142:145], v[176:179], v[58:61]
	v_mfma_f32_16x16x32_bf16 v[54:57], v[134:137], v[184:187], v[54:57]
	v_mfma_f32_16x16x32_bf16 v[50:53], v[142:145], v[184:187], v[50:53]
	v_mfma_f32_16x16x32_bf16 v[38:41], v[134:137], v[192:195], v[38:41]
	v_mfma_f32_16x16x32_bf16 v[34:37], v[142:145], v[192:195], v[34:37]
	v_mfma_f32_16x16x32_bf16 v[22:25], v[134:137], v[212:215], v[22:25]
	v_mfma_f32_16x16x32_bf16 v[18:21], v[142:145], v[212:215], v[18:21]
	s_barrier
	s_add_u32 s74, s8, 0x80000
	s_addc_u32 s75, s9, 0
	s_add_i32 s37, s73, s39
	v_lshl_add_u64 v[130:131], s[74:75], 0, v[162:163]
	s_mov_b32 m0, s37
	s_nop 0
	global_load_lds_dwordx4 v[130:131], off
	v_lshl_add_u64 v[130:131], s[74:75], 0, v[166:167]
	s_add_i32 m0, s37, 0x2000
	s_nop 0
	global_load_lds_dwordx4 v[130:131], off
	s_waitcnt vmcnt(6)
	s_barrier
	v_mfma_f32_16x16x32_bf16 v[46:49], v[216:219], v[172:175], v[46:49]
	v_mfma_f32_16x16x32_bf16 v[42:45], v[224:227], v[172:175], v[42:45]
	v_mfma_f32_16x16x32_bf16 v[30:33], v[216:219], v[180:183], v[30:33]
	v_mfma_f32_16x16x32_bf16 v[26:29], v[224:227], v[180:183], v[26:29]
	v_mfma_f32_16x16x32_bf16 v[14:17], v[216:219], v[188:191], v[14:17]
	v_mfma_f32_16x16x32_bf16 v[10:13], v[224:227], v[188:191], v[10:13]
	v_mfma_f32_16x16x32_bf16 v[6:9], v[216:219], v[196:199], v[6:9]
	v_mfma_f32_16x16x32_bf16 v[2:5], v[224:227], v[196:199], v[2:5]
	v_mfma_f32_16x16x32_bf16 v[46:49], v[220:223], v[176:179], v[46:49]
	v_mfma_f32_16x16x32_bf16 v[42:45], v[228:231], v[176:179], v[42:45]
	v_mfma_f32_16x16x32_bf16 v[30:33], v[220:223], v[184:187], v[30:33]
	v_mfma_f32_16x16x32_bf16 v[26:29], v[228:231], v[184:187], v[26:29]
	v_mfma_f32_16x16x32_bf16 v[14:17], v[220:223], v[192:195], v[14:17]
	v_mfma_f32_16x16x32_bf16 v[10:13], v[228:231], v[192:195], v[10:13]
	v_mfma_f32_16x16x32_bf16 v[6:9], v[220:223], v[212:215], v[6:9]
	v_mfma_f32_16x16x32_bf16 v[2:5], v[228:231], v[212:215], v[2:5]
	s_add_i32 s37, 0, 0x18000
	v_add_u32_e32 v0, s37, v210
	s_barrier
	ds_read_b128 v[130:133], v0
	ds_read_b128 v[134:137], v0 offset:1024
	ds_read_b128 v[138:141], v0 offset:2048
	ds_read_b128 v[142:145], v0 offset:3072
	s_add_u32 s34, s34, 0x80000
	s_addc_u32 s35, s35, 0
	s_mov_b32 m0, s41
	v_lshl_add_u64 v[216:217], s[34:35], 0, v[160:161]
	ds_read_b128 v[172:175], v211 offset:32768
	ds_read_b128 v[176:179], v211 offset:33792
	ds_read_b128 v[180:183], v211 offset:34816
	ds_read_b128 v[184:187], v211 offset:35840
	ds_read_b128 v[188:191], v211 offset:36864
	ds_read_b128 v[192:195], v211 offset:37888
	ds_read_b128 v[196:199], v211 offset:38912
	ds_read_b128 v[212:215], v211 offset:39936
	global_load_lds_dwordx4 v[216:217], off
	v_lshl_add_u64 v[216:217], s[34:35], 0, v[164:165]
	s_mov_b32 m0, s42
	s_nop 0
	global_load_lds_dwordx4 v[216:217], off
	s_waitcnt lgkmcnt(8)
	s_barrier
; #define PG8_STAGE(bufoff, gbase, voff) do { _Pragma("unroll") for (int _i = 0; _i < 2; ++_i) \
;         __builtin_amdgcn_global_load_lds((const unsigned*)((const char*)(gbase) + (voff)[_i]), (LAS unsigned*)(lds + (bufoff) + ldsw + _i * 8192), 16, 0, 0); } while (0)
; #define PG8_LDA(dst, b, h) do { _Pragma("unroll") for (int m = 0; m < 4; ++m) _Pragma("unroll") for (int k = 0; k < 2; ++k) dst[m][k] = *(const LAS bf16x8*)(lds + PG8_SA(b, h) + aoff + m * 2048 + k * 1024); } while (0)
; #define PG8_LDB(dst, b, h) do { _Pragma("unroll") for (int n = 0; n < 2; ++n) _Pragma("unroll") for (int k = 0; k < 2; ++k) dst[n][k] = *(const LAS bf16x8*)(lds + PG8_SB(b, h) + boff + n * 2048 + k * 1024); } while (0)
; #define PG8_MMA(ai, bj, At, Bt) do { __builtin_amdgcn_s_setprio(1); _Pragma("unroll") for (int m = 0; m < 4; ++m) _Pragma("unroll") for (int n = 0; n < 2; ++n) _Pragma("unroll") for (int k = 0; k < 2; ++k) \
;         acc[ai][bj][m][n] = __builtin_amdgcn_mfma_f32_16x16x32_bf16(Bt[n][k], At[m][k], acc[ai][bj][m][n], 0, 0, 0); __builtin_amdgcn_s_setprio(0); } while (0)
; #define PG8_WAIT_V(n) asm volatile("s_waitcnt vmcnt(" #n ")" ::: "memory")
; #define PG8_WAIT_L(n) asm volatile("s_waitcnt lgkmcnt(" #n ")" ::: "memory")
; #define PG8_BAR __builtin_amdgcn_s_barrier()
; #define PG8_SCHED __builtin_amdgcn_sched_barrier(0)
; template <class Epi>
; __device__ __forceinline__ void gemm_phase(LAS unsigned char* lds, const Gemm g, const StaticOrder& S, const Epi& E, const int tid) {
;     ...
;             PG8_BAR; PG8_WAIT_L(0); PG8_MMA(1, 0, At, B0); PG8_BAR; PG8_SCHED;
;             PG8_STAGE(PG8_SB(0, 1), b2 + hstep, voffB);
;             PG8_WAIT_V(6); PG8_BAR; PG8_MMA(1, 1, At, B1); PG8_BAR;
;             PG8_LDB(B0, 1, 0); PG8_SCHED; PG8_LDA(At, 1, 0); PG8_STAGE(PG8_SA(0, 1), a2 + hstep, voffA);
;             PG8_WAIT_L(8); PG8_BAR; PG8_WAIT_L(0); PG8_MMA(0, 0, At, B0); PG8_BAR; PG8_SCHED;
;             PG8_LDB(B1, 1, 1); PG8_STAGE(PG8_SB(1, 0), b3, voffB);
;             PG8_BAR; PG8_WAIT_L(0); PG8_MMA(0, 1, At, B1); PG8_BAR;
;             PG8_LDA(At, 1, 1); PG8_STAGE(PG8_SA(1, 0), a3, voffA);
;             PG8_BAR; PG8_WAIT_L(0); PG8_MMA(1, 0, At, B0); PG8_BAR; PG8_SCHED;
	s_waitcnt lgkmcnt(0)
	v_mfma_f32_16x16x32_bf16 v[126:129], v[130:133], v[172:175], v[126:129]
	v_mfma_f32_16x16x32_bf16 v[122:125], v[138:141], v[172:175], v[122:125]
	v_mfma_f32_16x16x32_bf16 v[118:121], v[130:133], v[180:183], v[118:121]
	v_mfma_f32_16x16x32_bf16 v[114:117], v[138:141], v[180:183], v[114:117]
	v_mfma_f32_16x16x32_bf16 v[102:105], v[130:133], v[188:191], v[102:105]
	v_mfma_f32_16x16x32_bf16 v[98:101], v[138:141], v[188:191], v[98:101]
	v_mfma_f32_16x16x32_bf16 v[86:89], v[130:133], v[196:199], v[86:89]
	v_mfma_f32_16x16x32_bf16 v[82:85], v[138:141], v[196:199], v[82:85]
	v_mfma_f32_16x16x32_bf16 v[126:129], v[134:137], v[176:179], v[126:129]
	v_mfma_f32_16x16x32_bf16 v[122:125], v[142:145], v[176:179], v[122:125]
	v_mfma_f32_16x16x32_bf16 v[118:121], v[134:137], v[184:187], v[118:121]
	v_mfma_f32_16x16x32_bf16 v[114:117], v[142:145], v[184:187], v[114:117]
	v_mfma_f32_16x16x32_bf16 v[102:105], v[134:137], v[192:195], v[102:105]
	v_mfma_f32_16x16x32_bf16 v[98:101], v[142:145], v[192:195], v[98:101]
	v_mfma_f32_16x16x32_bf16 v[86:89], v[134:137], v[212:215], v[86:89]
	v_mfma_f32_16x16x32_bf16 v[82:85], v[142:145], v[212:215], v[82:85]
	s_barrier
	s_add_i32 s34, 0, 0x1c000
	s_add_i32 s35, s37, s39
	v_add_u32_e32 v0, s34, v210
	v_lshl_add_u64 v[200:201], v[200:201], 0, s[56:57]
	s_mov_b32 m0, s35
	ds_read_b128 v[216:219], v0
	ds_read_b128 v[220:223], v0 offset:1024
	ds_read_b128 v[224:227], v0 offset:2048
	ds_read_b128 v[228:231], v0 offset:3072
	global_load_lds_dwordx4 v[200:201], off
	v_lshl_add_u64 v[200:201], v[232:233], 0, s[56:57]
	s_add_i32 m0, s35, 0x2000
	s_nop 0
	global_load_lds_dwordx4 v[200:201], off
	s_barrier
	s_waitcnt lgkmcnt(0)
	v_mfma_f32_16x16x32_bf16 v[110:113], v[216:219], v[172:175], v[110:113]
	v_mfma_f32_16x16x32_bf16 v[106:109], v[224:227], v[172:175], v[106:109]
	v_mfma_f32_16x16x32_bf16 v[94:97], v[216:219], v[180:183], v[94:97]
	v_mfma_f32_16x16x32_bf16 v[90:93], v[224:227], v[180:183], v[90:93]
	v_mfma_f32_16x16x32_bf16 v[78:81], v[216:219], v[188:191], v[78:81]
	v_mfma_f32_16x16x32_bf16 v[74:77], v[224:227], v[188:191], v[74:77]
	v_mfma_f32_16x16x32_bf16 v[70:73], v[216:219], v[196:199], v[70:73]
	v_mfma_f32_16x16x32_bf16 v[66:69], v[224:227], v[196:199], v[66:69]
	v_mfma_f32_16x16x32_bf16 v[110:113], v[220:223], v[176:179], v[110:113]
	v_mfma_f32_16x16x32_bf16 v[106:109], v[228:231], v[176:179], v[106:109]
	v_mfma_f32_16x16x32_bf16 v[94:97], v[220:223], v[184:187], v[94:97]
	v_mfma_f32_16x16x32_bf16 v[90:93], v[228:231], v[184:187], v[90:93]
	v_mfma_f32_16x16x32_bf16 v[78:81], v[220:223], v[192:195], v[78:81]
	v_mfma_f32_16x16x32_bf16 v[74:77], v[228:231], v[192:195], v[74:77]
	v_mfma_f32_16x16x32_bf16 v[70:73], v[220:223], v[212:215], v[70:73]
	v_mfma_f32_16x16x32_bf16 v[66:69], v[228:231], v[212:215], v[66:69]
	s_mov_b32 m0, s49
	v_lshl_add_u64 v[200:201], v[234:235], 0, s[56:57]
	s_barrier
	ds_read_b128 v[172:175], v211 offset:49152
	ds_read_b128 v[176:179], v211 offset:50176
	ds_read_b128 v[180:183], v211 offset:51200
	ds_read_b128 v[184:187], v211 offset:52224
	ds_read_b128 v[188:191], v211 offset:53248
	ds_read_b128 v[192:195], v211 offset:54272
	ds_read_b128 v[196:199], v211 offset:55296
	ds_read_b128 v[212:215], v211 offset:56320
	global_load_lds_dwordx4 v[200:201], off
	v_lshl_add_u64 v[200:201], v[236:237], 0, s[56:57]
	s_mov_b32 m0, s52
	s_nop 0
	global_load_lds_dwordx4 v[200:201], off
	s_barrier
; __device__ __forceinline__ unsigned pk2(float lo, float hi) { f32x2 v = {lo, hi}; return __builtin_bit_cast(unsigned, __builtin_convertvector(v, bf16x2_t)); }
; #define PG8_WAIT_V(n) asm volatile("s_waitcnt vmcnt(" #n ")" ::: "memory")
; #define PG8_WAIT_L(n) asm volatile("s_waitcnt lgkmcnt(" #n ")" ::: "memory")
;     __device__ __forceinline__ void operator()(const f32x4 (&acc)[2][2][4][2], const Unit& u, int wr, int wc, int fr, int fq) const {
;     ...
;         const int type = (u.pn >> 2) % 3, grp = u.pn / 12;
;         const int row0 = u.pm * BM + wr * 64 + fr, col0 = u.pn * BM + wc * 32 + 8 * fq;
;         if (type == 2) {
; #pragma unroll
;             for (int ai = 0; ai < 2; ++ai)
; #pragma unroll
;                 for (int m = 0; m < 4; ++m) {
;                     bf16_t* rowp = O + ((size_t)(2 * u.pn) * MTOK + (row0 + ai * HALF + m * 16)) * 128 + wc * 32 + 8 * fq;
; #pragma unroll
;                     for (int bj = 0; bj < 2; ++bj) { const f32x4 v0 = acc[ai][bj][m][0], v1 = acc[ai][bj][m][1];
;                         u32x4 w; w.x = pk2(v0[0], v0[1]); w.y = pk2(v0[2], v0[3]); w.z = pk2(v1[0], v1[1]); w.w = pk2(v1[2], v1[3]); *(u32x4*)(rowp + (size_t)bj * MTOK * 128) = w; }
;                 }
;             return;
;         }
; #pragma unroll
;         for (int ai = 0; ai < 2; ++ai)
; #pragma unroll
;             for (int m = 0; m < 4; ++m)
; #pragma unroll
;                 for (int bj = 0; bj < 2; ++bj) {
;                     const f32x4 a = acc[ai][bj][m][0], b = acc[ai][bj][m][1];
;                     float s = (a[0] * a[0] + a[1] * a[1]) + (a[2] * a[2] + a[3] * a[3]) + (b[0] * b[0] + b[1] * b[1]) + (b[2] * b[2] + b[3] * b[3]);
;                     s += __shfl_xor(s, 16); s += __shfl_xor(s, 32);
;                     if (fq == 0) T[((wr * 128 + ai * 64 + m * 16 + fr) * 2 + bj) * 4 + wc] = s;
; template <class Epi>
; __device__ __forceinline__ void gemm_phase(LAS unsigned char* lds, const Gemm g, const StaticOrder& S, const Epi& E, const int tid) {
;     ...
;             PG8_BAR; PG8_WAIT_L(0); PG8_MMA(0, 1, At, B1); PG8_BAR;
;             PG8_LDA(At, 1, 1); PG8_STAGE(PG8_SA(1, 0), a3, voffA);
;             PG8_BAR; PG8_WAIT_L(0); PG8_MMA(1, 0, At, B0); PG8_BAR; PG8_SCHED;
;             PG8_STAGE(PG8_SB(1, 1), b3 + hstep, voffB);
;             PG8_WAIT_V(6); PG8_BAR; PG8_MMA(1, 1, At, B1); PG8_BAR;
;         }
	s_waitcnt lgkmcnt(0)
	v_mfma_f32_16x16x32_bf16 v[62:65], v[130:133], v[172:175], v[62:65]
	v_mfma_f32_16x16x32_bf16 v[58:61], v[138:141], v[172:175], v[58:61]
	v_mfma_f32_16x16x32_bf16 v[54:57], v[130:133], v[180:183], v[54:57]
	v_mfma_f32_16x16x32_bf16 v[50:53], v[138:141], v[180:183], v[50:53]
	v_mfma_f32_16x16x32_bf16 v[38:41], v[130:133], v[188:191], v[38:41]
	v_mfma_f32_16x16x32_bf16 v[34:37], v[138:141], v[188:191], v[34:37]
	v_mfma_f32_16x16x32_bf16 v[22:25], v[130:133], v[196:199], v[22:25]
	v_mfma_f32_16x16x32_bf16 v[18:21], v[138:141], v[196:199], v[18:21]
	v_mfma_f32_16x16x32_bf16 v[62:65], v[134:137], v[176:179], v[62:65]
	v_mfma_f32_16x16x32_bf16 v[58:61], v[142:145], v[176:179], v[58:61]
	v_mfma_f32_16x16x32_bf16 v[54:57], v[134:137], v[184:187], v[54:57]
	v_mfma_f32_16x16x32_bf16 v[50:53], v[142:145], v[184:187], v[50:53]
	v_mfma_f32_16x16x32_bf16 v[38:41], v[134:137], v[192:195], v[38:41]
	v_mfma_f32_16x16x32_bf16 v[34:37], v[142:145], v[192:195], v[34:37]
	v_mfma_f32_16x16x32_bf16 v[22:25], v[134:137], v[212:215], v[22:25]
	v_mfma_f32_16x16x32_bf16 v[18:21], v[142:145], v[212:215], v[18:21]
	s_barrier
	s_add_u32 s8, s8, 0x80080
	s_addc_u32 s9, s9, 0
	s_add_i32 s34, s34, s39
	v_lshl_add_u64 v[130:131], s[8:9], 0, v[162:163]
	s_mov_b32 m0, s34
	s_nop 0
	global_load_lds_dwordx4 v[130:131], off
	v_lshl_add_u64 v[130:131], s[8:9], 0, v[166:167]
	s_add_i32 m0, s34, 0x2000
	s_nop 0
	global_load_lds_dwordx4 v[130:131], off
	s_waitcnt vmcnt(6)
	s_barrier
	v_mfma_f32_16x16x32_bf16 v[46:49], v[216:219], v[172:175], v[46:49]
	v_mfma_f32_16x16x32_bf16 v[42:45], v[224:227], v[172:175], v[42:45]
	v_mfma_f32_16x16x32_bf16 v[30:33], v[216:219], v[180:183], v[30:33]
	v_mfma_f32_16x16x32_bf16 v[26:29], v[224:227], v[180:183], v[26:29]
	v_mfma_f32_16x16x32_bf16 v[14:17], v[216:219], v[188:191], v[14:17]
	v_mfma_f32_16x16x32_bf16 v[10:13], v[224:227], v[188:191], v[10:13]
	v_mfma_f32_16x16x32_bf16 v[6:9], v[216:219], v[196:199], v[6:9]
	v_mfma_f32_16x16x32_bf16 v[2:5], v[224:227], v[196:199], v[2:5]
	v_mfma_f32_16x16x32_bf16 v[46:49], v[220:223], v[176:179], v[46:49]
	v_mfma_f32_16x16x32_bf16 v[42:45], v[228:231], v[176:179], v[42:45]
	v_mfma_f32_16x16x32_bf16 v[30:33], v[220:223], v[184:187], v[30:33]
	v_mfma_f32_16x16x32_bf16 v[26:29], v[228:231], v[184:187], v[26:29]
	v_mfma_f32_16x16x32_bf16 v[14:17], v[220:223], v[192:195], v[14:17]
	v_mfma_f32_16x16x32_bf16 v[10:13], v[228:231], v[192:195], v[10:13]
	v_mfma_f32_16x16x32_bf16 v[6:9], v[220:223], v[212:215], v[6:9]
	v_mfma_f32_16x16x32_bf16 v[2:5], v[228:231], v[212:215], v[2:5]
	s_add_i32 s36, s36, 2
	s_add_u32 s66, s66, 0x100
	s_addc_u32 s72, s72, 0
	s_add_u32 s6, s6, 0x100
	s_addc_u32 s7, s7, 0
	s_cmp_gt_u32 s36, 29
	s_barrier
	s_cbranch_scc0 .LBB0_286
	s_setprio 0
	s_ashr_i32 s3, s20, 2
	s_mul_hi_i32 s6, s3, 0x55555556
	s_lshr_b32 s7, s6, 31
	s_add_i32 s6, s6, s7
	s_mul_i32 s6, s6, 3
	s_lshl_b32 s2, s2, 8
	v_mov_b32_e32 v138, v159
	v_mov_b32_e32 v0, v209
	s_sub_i32 s6, s3, s6
	s_add_i32 s2, s2, s47
	s_cmp_eq_u32 s6, 2
	v_add_u32_e32 v174, s2, v138
	v_lshlrev_b32_e32 v172, 3, v0
	s_mov_b64 s[2:3], -1
	s_cbranch_scc1 .LBB0_376
	v_mul_f32_e32 v132, v127, v127
	v_mul_f32_e32 v133, v129, v129
	v_fmac_f32_e32 v132, v126, v126
	v_fmac_f32_e32 v133, v128, v128
	v_and_b32_e32 v131, 64, v204
	v_add_f32_e32 v132, v132, v133
	v_mul_f32_e32 v133, v123, v123
	v_xor_b32_e32 v130, 16, v204
	v_add_u32_e32 v131, 64, v131
	v_fmac_f32_e32 v133, v122, v122
	v_cmp_lt_i32_e32 vcc, v130, v131
	v_add_f32_e32 v132, v132, v133
	v_mul_f32_e32 v133, v125, v125
	v_cndmask_b32_e32 v130, v204, v130, vcc
	v_fmac_f32_e32 v133, v124, v124
	v_lshlrev_b32_e32 v130, 2, v130
	v_add_f32_e32 v132, v133, v132
	ds_bpermute_b32 v133, v130, v132
	v_xor_b32_e32 v134, 32, v204
	v_cmp_lt_i32_e32 vcc, v134, v131
	v_lshlrev_b32_e32 v175, 5, v138
	s_waitcnt lgkmcnt(0)
	v_add_f32_e32 v132, v132, v133
	v_cndmask_b32_e32 v131, v204, v134, vcc
	v_lshlrev_b32_e32 v212, 2, v131
	ds_bpermute_b32 v133, v212, v132
	v_cmp_eq_u32_e32 vcc, 0, v0
	v_add_u32_e32 v131, s63, v175
	s_and_saveexec_b64 s[2:3], vcc
	s_cbranch_execz .LBB0_290
	s_waitcnt lgkmcnt(0)
	v_add_f32_e32 v132, v132, v133
	ds_write_b32 v131, v132
